# UM2 + 56 stale s_waitcnt lgkmcnt(0) removed at converted pointer-reload sites where no LDS read was pending (they only drained unrelated LDS writes)
# speedup vs baseline: 1.0043x; 1.0043x over previous
; #define LAS __attribute__((address_space(3)))
; __global__ void __launch_bounds__(512, 2) hymba_fwd(Params p) {
;     ...
;     if (threadIdx.x < 26) *(LAS unsigned long long*)(L + 131072 + 256 + 8 * threadIdx.x) = threadIdx.x < 24 ? (unsigned long long)p.in[threadIdx.x] : threadIdx.x == 24 ? (unsigned long long)p.ws : (unsigned long long)p.out;
;     ...
;     const int G = gridDim.x, c = blockIdx.x;
;     ...
;     volatile LAS unsigned* bst = (volatile LAS unsigned*)(L + 131072 + 64);
;     if (threadIdx.x == 0) { bst[0] = 0u; bst[1] = 0u; }
;     __syncthreads();
;     (void)xcd_barrier_post((unsigned*)(PWS + WS_BAR), bst);
.LBB0_8:
	s_or_b64 exec, exec, s[0:1]
	v_mov_b32_e32 v2, 0
	s_waitcnt lgkmcnt(0)
	s_barrier
	v_mbcnt_lo_u32_b32 v251, -1, 0
	v_mbcnt_hi_u32_b32 v251, -1, v251
	v_lshlrev_b32_e32 v251, 2, v251
	v_add_u32_e32 v251, 0x20100, v251
	ds_read_b32 v251, v251
	s_waitcnt lgkmcnt(0)
	s_nop 0
	v_add_u32_e32 v2, 0, v2
	v_add_u32_e32 v2, 0x201c0, v2
	s_nop 0
	s_getreg_b32 s11, hwreg(HW_REG_XCC_ID, 0, 4)
	v_readlane_b32 s8, v251, 49
	v_readlane_b32 s9, v251, 48
	s_and_saveexec_b64 s[0:1], vcc
	s_cbranch_execz .LBB0_11
	s_mov_b64 s[6:7], exec
	v_mbcnt_lo_u32_b32 v2, s6, 0
	v_mbcnt_hi_u32_b32 v2, s7, v2
	v_cmp_eq_u32_e32 vcc, 0, v2
	s_and_b64 s[12:13], exec, vcc
	s_mov_b64 exec, s[12:13]
	s_cbranch_execz .LBB0_11
	s_lshl_b32 s11, s11, 8
	s_and_b32 s11, s11, 0xf00
	s_add_u32 s12, s9, s11
	s_addc_u32 s13, s8, 0
	s_bcnt1_i32_b64 s6, s[6:7]
	v_mov_b32_e32 v2, 0x28680000
	v_mov_b32_e32 v3, s6
	global_atomic_add v2, v3, s[12:13] offset:1024

; #define LAS __attribute__((address_space(3)))
; #define PIN(i) ((const float*)ldq_(L, (i)))
; #define PREP_CONV(bit, SRC, Kd, Nd, DST, GK, MODE) if (mask & (bit)) { for (int it = gw; it < ((Kd) / 64) * ((Nd) / 64); it += NGW) transpose_item((SRC), (Kd), (Nd), (bf16_t*)(wl + (DST)), (GK), (MODE), scr, it, lane); }
; __device__ __forceinline__ void transpose_item(const float* W, int K, int N, bf16_t* WT, const float* gk, int mode, LAS float* scr_, int item, int lane) {
;     LAS unsigned* scr = (LAS unsigned*)scr_;
;     const int nblk = N / 64, kb = item / nblk, nb = item % nblk, k0 = 64 * kb, n0 = 64 * nb;
;     const int sc = (mode == 1) ? (((n0 >> 7) & 1) * DFF + (n0 >> 8) * 128 + (n0 & 127)) : n0;
;     const float* src = W + (size_t)k0 * N + sc + lane;
;     float va[32], vb[32];
; #pragma unroll
;     for (int kp = 0; kp < 32; ++kp) { va[kp] = src[(size_t)(2 * kp) * N]; vb[kp] = src[(size_t)(2 * kp + 1) * N]; }
; #pragma unroll
;     for (int kp = 0; kp < 32; ++kp) {
;         float a = va[kp], b = vb[kp];
;         if (gk) { a *= gk[k0 + 2 * kp]; b *= gk[k0 + 2 * kp + 1]; }
; __device__ __forceinline__ void prep(const Params& p, LAS unsigned char* L, int wv, int vb, int nvb, int l, int mask) {
;     ...
;     PREP_CONV(PM_FFA_IN, PIN(I_WFFA_IN) + (size_t)l * DM * NFF2, DM, NFF2, WL_FFA_IN, PIN(I_NFFA) + l * DM, 1)
.LBB0_15:
	v_mov_b32_e32 v6, 0
	s_mul_hi_i32 s0, s88, 0x2e8ba2e9
	v_add_u32_e32 v6, 0, v6
	v_add_u32_e32 v6, 0x20140, v6
	s_lshr_b32 s6, s0, 31
	s_ashr_i32 s0, s0, 4
	s_nop 0
	s_add_i32 s13, s0, s6
	s_mul_i32 s0, s13, 0xffffea00
	s_mul_i32 s7, s13, 0xfffff500
	s_add_i32 s89, s16, s0
	s_bfe_i32 s0, s88, 0x10001
	s_add_i32 s7, s18, s7
	s_and_b32 s0, s0, 0xb00
	s_and_b32 s7, s7, 0xffffff80
	s_lshl_b32 s6, s13, 6
	s_add_i32 s0, s0, s7
	s_and_b32 s7, s89, 64
	s_waitcnt lgkmcnt(0)
	v_readlane_b32 s12, v251, 16
	s_or_b32 s0, s0, s7
	s_ashr_i32 s7, s6, 31
	s_mul_i32 s13, s13, 0x160000
	v_readlane_b32 s1, v251, 17
	s_mul_hi_i32 s14, s6, 0x5800
	s_add_u32 s12, s12, s13
	v_mov_b32_e32 v8, 0
	s_addc_u32 s13, s1, s14
	s_ashr_i32 s1, s0, 31
	s_lshl_b64 s[0:1], s[0:1], 2
	v_add_u32_e32 v8, 0, v8
	s_add_u32 s0, s12, s0
	v_add_u32_e32 v6, 0x20138, v8
	s_addc_u32 s1, s13, s1
	s_nop 0
	v_lshl_add_u64 v[6:7], s[0:1], 0, v[2:3]
	v_add_co_u32_e32 v8, vcc, s23, v6
	v_readlane_b32 s13, v251, 15
	v_addc_co_u32_e32 v9, vcc, 0, v7, vcc
	v_add_co_u32_e32 v10, vcc, s24, v6
	v_readlane_b32 s12, v251, 14
	s_nop 0
	v_addc_co_u32_e32 v11, vcc, 0, v7, vcc
	v_add_co_u32_e32 v12, vcc, s25, v6
	s_cmp_lg_u64 s[12:13], 0
	s_nop 0
	v_addc_co_u32_e32 v13, vcc, 0, v7, vcc
	v_add_co_u32_e32 v14, vcc, s26, v6
	s_cselect_b64 s[14:15], -1, 0
	s_nop 0
	v_addc_co_u32_e32 v15, vcc, 0, v7, vcc
	v_add_co_u32_e32 v16, vcc, s27, v6
	s_cmp_eq_u64 s[12:13], 0
	s_nop 0
	v_addc_co_u32_e32 v17, vcc, 0, v7, vcc
	v_add_co_u32_e32 v18, vcc, s28, v6
	s_nop 1
	v_addc_co_u32_e32 v19, vcc, 0, v7, vcc
	v_add_co_u32_e32 v20, vcc, s29, v6
	s_nop 1
	v_addc_co_u32_e32 v21, vcc, 0, v7, vcc
	v_add_co_u32_e32 v22, vcc, s30, v6
	s_nop 1
	v_addc_co_u32_e32 v23, vcc, 0, v7, vcc
	global_load_dword v73, v[8:9], off offset:2048
	global_load_dword v70, v[10:11], off
	global_load_dword v71, v[12:13], off offset:2048
	global_load_dword v64, v[14:15], off
	global_load_dword v65, v[16:17], off offset:2048
	global_load_dword v66, v[18:19], off
	global_load_dword v67, v[20:21], off offset:2048
	global_load_dword v60, v[22:23], off
	v_add_co_u32_e32 v8, vcc, s31, v6
	s_nop 1
	v_addc_co_u32_e32 v9, vcc, 0, v7, vcc
	v_add_co_u32_e32 v10, vcc, s34, v6
	s_nop 1
	v_addc_co_u32_e32 v11, vcc, 0, v7, vcc
	v_add_co_u32_e32 v12, vcc, s35, v6
	s_nop 1
	v_addc_co_u32_e32 v13, vcc, 0, v7, vcc
	v_add_co_u32_e32 v14, vcc, s36, v6
	s_nop 1
	v_addc_co_u32_e32 v15, vcc, 0, v7, vcc
	v_add_co_u32_e32 v16, vcc, s37, v6
	s_nop 1
	v_addc_co_u32_e32 v17, vcc, 0, v7, vcc
	v_add_co_u32_e32 v18, vcc, s38, v6
	s_nop 1
	v_addc_co_u32_e32 v19, vcc, 0, v7, vcc
	v_add_co_u32_e32 v20, vcc, s39, v6
	s_nop 1
	v_addc_co_u32_e32 v21, vcc, 0, v7, vcc
	v_add_co_u32_e32 v22, vcc, s40, v6
	s_nop 1
	v_addc_co_u32_e32 v23, vcc, 0, v7, vcc
	global_load_dword v61, v[8:9], off offset:2048
	global_load_dword v62, v[10:11], off
	global_load_dword v63, v[12:13], off offset:2048
	global_load_dword v56, v[14:15], off
	global_load_dword v57, v[16:17], off offset:2048
	global_load_dword v58, v[18:19], off
	global_load_dword v59, v[20:21], off offset:2048
	global_load_dword v52, v[22:23], off
	v_add_co_u32_e32 v8, vcc, s41, v6
	s_nop 1
	v_addc_co_u32_e32 v9, vcc, 0, v7, vcc
	v_add_co_u32_e32 v10, vcc, s42, v6
	s_nop 1
	v_addc_co_u32_e32 v11, vcc, 0, v7, vcc
	v_add_co_u32_e32 v12, vcc, s43, v6
	s_nop 1
	v_addc_co_u32_e32 v13, vcc, 0, v7, vcc
	v_add_co_u32_e32 v14, vcc, s44, v6
	s_nop 1
	v_addc_co_u32_e32 v15, vcc, 0, v7, vcc
	v_add_co_u32_e32 v16, vcc, s45, v6
	s_nop 1
	v_addc_co_u32_e32 v17, vcc, 0, v7, vcc
	v_add_co_u32_e32 v18, vcc, s46, v6
	s_nop 1
	v_addc_co_u32_e32 v19, vcc, 0, v7, vcc
	v_add_co_u32_e32 v20, vcc, s47, v6
	s_nop 1
	v_addc_co_u32_e32 v21, vcc, 0, v7, vcc
	v_add_co_u32_e32 v22, vcc, s48, v6
	s_nop 1
	v_addc_co_u32_e32 v23, vcc, 0, v7, vcc
	global_load_dword v53, v[8:9], off offset:2048
	global_load_dword v54, v[10:11], off
	global_load_dword v55, v[12:13], off offset:2048
	global_load_dword v48, v[14:15], off
	global_load_dword v49, v[16:17], off offset:2048
	global_load_dword v50, v[18:19], off
	global_load_dword v51, v[20:21], off offset:2048
	global_load_dword v44, v[22:23], off
	v_add_co_u32_e32 v8, vcc, s49, v6
	s_nop 1
	v_addc_co_u32_e32 v9, vcc, 0, v7, vcc
	v_add_co_u32_e32 v10, vcc, s50, v6
	s_nop 1
	v_addc_co_u32_e32 v11, vcc, 0, v7, vcc
	v_add_co_u32_e32 v12, vcc, s51, v6
	s_nop 1
	v_addc_co_u32_e32 v13, vcc, 0, v7, vcc
	v_add_co_u32_e32 v14, vcc, s52, v6
	s_nop 1
	v_addc_co_u32_e32 v15, vcc, 0, v7, vcc
	v_add_co_u32_e32 v16, vcc, s53, v6
	s_nop 1
	v_addc_co_u32_e32 v17, vcc, 0, v7, vcc
	v_add_co_u32_e32 v18, vcc, s54, v6
	s_nop 1
	v_addc_co_u32_e32 v19, vcc, 0, v7, vcc
	v_add_co_u32_e32 v20, vcc, s55, v6
	s_nop 1
	v_addc_co_u32_e32 v21, vcc, 0, v7, vcc
	v_add_co_u32_e32 v22, vcc, s56, v6
; __device__ __forceinline__ void transpose_item(const float* W, int K, int N, bf16_t* WT, const float* gk, int mode, LAS float* scr_, int item, int lane) {
;     ...
;     for (int kp = 0; kp < 32; ++kp) { va[kp] = src[(size_t)(2 * kp) * N]; vb[kp] = src[(size_t)(2 * kp + 1) * N]; }
; #pragma unroll
;     for (int kp = 0; kp < 32; ++kp) {
;         float a = va[kp], b = vb[kp];
;         if (gk) { a *= gk[k0 + 2 * kp]; b *= gk[k0 + 2 * kp + 1]; }
	s_nop 1
	v_addc_co_u32_e32 v23, vcc, 0, v7, vcc
	global_load_dword v45, v[8:9], off offset:2048
	global_load_dword v46, v[10:11], off
	global_load_dword v47, v[12:13], off offset:2048
	global_load_dword v40, v[14:15], off
	global_load_dword v41, v[16:17], off offset:2048
	global_load_dword v42, v[18:19], off
	global_load_dword v43, v[20:21], off offset:2048
	global_load_dword v36, v[22:23], off
	v_add_co_u32_e32 v8, vcc, s57, v6
	s_nop 1
	v_addc_co_u32_e32 v9, vcc, 0, v7, vcc
	v_add_co_u32_e32 v10, vcc, s58, v6
	s_nop 1
	v_addc_co_u32_e32 v11, vcc, 0, v7, vcc
	v_add_co_u32_e32 v12, vcc, s59, v6
	s_nop 1
	v_addc_co_u32_e32 v13, vcc, 0, v7, vcc
	v_add_co_u32_e32 v14, vcc, s61, v6
	s_nop 1
	v_addc_co_u32_e32 v15, vcc, 0, v7, vcc
	v_add_co_u32_e32 v16, vcc, s62, v6
	s_nop 1
	v_addc_co_u32_e32 v17, vcc, 0, v7, vcc
	v_add_co_u32_e32 v18, vcc, s63, v6
	s_nop 1
	v_addc_co_u32_e32 v19, vcc, 0, v7, vcc
	v_add_co_u32_e32 v20, vcc, s65, v6
	s_nop 1
	v_addc_co_u32_e32 v21, vcc, 0, v7, vcc
	v_add_co_u32_e32 v22, vcc, s66, v6
	s_nop 1
	v_addc_co_u32_e32 v23, vcc, 0, v7, vcc
	global_load_dword v37, v[8:9], off offset:2048
	global_load_dword v38, v[10:11], off
	global_load_dword v39, v[12:13], off offset:2048
	global_load_dword v32, v[14:15], off
	global_load_dword v33, v[16:17], off offset:2048
	global_load_dword v34, v[18:19], off
	global_load_dword v35, v[20:21], off offset:2048
	global_load_dword v28, v[22:23], off
	v_add_co_u32_e32 v8, vcc, s67, v6
	s_nop 1
	v_addc_co_u32_e32 v9, vcc, 0, v7, vcc
	v_add_co_u32_e32 v10, vcc, s68, v6
	s_nop 1
	v_addc_co_u32_e32 v11, vcc, 0, v7, vcc
	v_add_co_u32_e32 v12, vcc, s69, v6
	s_nop 1
	v_addc_co_u32_e32 v13, vcc, 0, v7, vcc
	v_add_co_u32_e32 v14, vcc, s70, v6
	s_nop 1
	v_addc_co_u32_e32 v15, vcc, 0, v7, vcc
	v_add_co_u32_e32 v16, vcc, s71, v6
	s_nop 1
	v_addc_co_u32_e32 v17, vcc, 0, v7, vcc
	v_add_co_u32_e32 v18, vcc, s72, v6
	s_nop 1
	v_addc_co_u32_e32 v19, vcc, 0, v7, vcc
	v_add_co_u32_e32 v20, vcc, s73, v6
	s_nop 1
	v_addc_co_u32_e32 v21, vcc, 0, v7, vcc
	v_add_co_u32_e32 v74, vcc, s74, v6
	s_nop 1
	v_addc_co_u32_e32 v75, vcc, 0, v7, vcc
	global_load_dword v29, v[8:9], off offset:2048
	global_load_dword v30, v[10:11], off
	global_load_dword v31, v[12:13], off offset:2048
	global_load_dword v22, v[14:15], off
	global_load_dword v23, v[16:17], off offset:2048
	global_load_dword v24, v[18:19], off
	global_load_dword v25, v[20:21], off offset:2048
	s_nop 0
	global_load_dword v18, v[74:75], off
	v_add_co_u32_e32 v8, vcc, s75, v6
	s_nop 1
	v_addc_co_u32_e32 v9, vcc, 0, v7, vcc
	v_add_co_u32_e32 v10, vcc, s76, v6
	s_nop 1
	v_addc_co_u32_e32 v11, vcc, 0, v7, vcc
	v_add_co_u32_e32 v12, vcc, s77, v6
	s_nop 1
	v_addc_co_u32_e32 v13, vcc, 0, v7, vcc
	v_add_co_u32_e32 v14, vcc, s78, v6
	s_nop 1
	v_addc_co_u32_e32 v15, vcc, 0, v7, vcc
	v_add_co_u32_e32 v16, vcc, s79, v6
	s_nop 1
	v_addc_co_u32_e32 v17, vcc, 0, v7, vcc
	v_add_co_u32_e32 v74, vcc, s80, v6
	s_nop 1
	v_addc_co_u32_e32 v75, vcc, 0, v7, vcc
	v_add_co_u32_e32 v80, vcc, s81, v6
	s_nop 1
	v_addc_co_u32_e32 v81, vcc, 0, v7, vcc
	v_add_co_u32_e32 v82, vcc, s82, v6
	s_nop 1
	v_addc_co_u32_e32 v83, vcc, 0, v7, vcc
	global_load_dword v19, v[8:9], off offset:2048
	global_load_dword v20, v[10:11], off
	global_load_dword v21, v[12:13], off offset:2048
	s_nop 0
	global_load_dword v14, v[14:15], off
	s_nop 0
	global_load_dword v15, v[16:17], off offset:2048
	s_nop 0
	global_load_dword v16, v[74:75], off
	global_load_dword v17, v[80:81], off offset:2048
	global_load_dword v10, v[82:83], off
	v_add_co_u32_e32 v8, vcc, s83, v6
	s_nop 1
	v_addc_co_u32_e32 v9, vcc, 0, v7, vcc
	v_add_co_u32_e32 v12, vcc, s84, v6
	s_nop 1
	v_addc_co_u32_e32 v13, vcc, 0, v7, vcc
	v_add_co_u32_e32 v74, vcc, s85, v6
	s_nop 1
	v_addc_co_u32_e32 v75, vcc, 0, v7, vcc
	v_add_co_u32_e32 v80, vcc, s86, v6
	s_nop 1
	v_addc_co_u32_e32 v81, vcc, 0, v7, vcc
	v_add_co_u32_e32 v82, vcc, s87, v6
	s_nop 1
	v_addc_co_u32_e32 v83, vcc, 0, v7, vcc
	v_add_co_u32_e32 v84, vcc, 0x155000, v6
	s_nop 1
	v_addc_co_u32_e32 v85, vcc, 0, v7, vcc
	v_add_co_u32_e32 v86, vcc, 0x15a000, v6
	s_nop 1
	v_addc_co_u32_e32 v87, vcc, 0, v7, vcc
	global_load_dword v72, v2, s[0:1]
	global_load_dword v11, v[8:9], off offset:2048
	s_nop 0
	global_load_dword v12, v[12:13], off
	s_nop 0
	global_load_dword v13, v[74:75], off offset:2048
	global_load_dword v6, v[80:81], off
	global_load_dword v7, v[82:83], off offset:2048
	global_load_dword v8, v[84:85], off
	global_load_dword v9, v[86:87], off offset:2048
	s_mov_b64 s[0:1], -1
	s_cbranch_scc1 .LBB0_17
	s_lshl_b64 s[0:1], s[6:7], 2
	s_add_u32 s0, s12, s0
	s_addc_u32 s1, s13, s1
	global_load_dwordx4 v[80:83], v3, s[0:1]
	s_mov_b64 s[0:1], 0
	s_waitcnt vmcnt(0)
	v_pk_mul_f32 v[68:69], v[72:73], v[80:81]
	v_pk_mul_f32 v[74:75], v[70:71], v[82:83]

; #define LAS __attribute__((address_space(3)))
; #define PIN(i) ((const float*)ldq_(L, (i)))
; #define PREP_CONV(bit, SRC, Kd, Nd, DST, GK, MODE) if (mask & (bit)) { for (int it = gw; it < ((Kd) / 64) * ((Nd) / 64); it += NGW) transpose_item((SRC), (Kd), (Nd), (bf16_t*)(wl + (DST)), (GK), (MODE), scr, it, lane); }
; __device__ __forceinline__ void transpose_item(const float* W, int K, int N, bf16_t* WT, const float* gk, int mode, LAS float* scr_, int item, int lane) {
;     LAS unsigned* scr = (LAS unsigned*)scr_;
;     const int nblk = N / 64, kb = item / nblk, nb = item % nblk, k0 = 64 * kb, n0 = 64 * nb;
;     const int sc = (mode == 1) ? (((n0 >> 7) & 1) * DFF + (n0 >> 8) * 128 + (n0 & 127)) : n0;
;     const float* src = W + (size_t)k0 * N + sc + lane;
;     float va[32], vb[32];
; #pragma unroll
;     for (int kp = 0; kp < 32; ++kp) { va[kp] = src[(size_t)(2 * kp) * N]; vb[kp] = src[(size_t)(2 * kp + 1) * N]; }
; #pragma unroll
;     for (int kp = 0; kp < 32; ++kp) {
;         float a = va[kp], b = vb[kp];
;         if (gk) { a *= gk[k0 + 2 * kp]; b *= gk[k0 + 2 * kp + 1]; }
; __device__ __forceinline__ void prep(const Params& p, LAS unsigned char* L, int wv, int vb, int nvb, int l, int mask) {
;     ...
;     PREP_CONV(PM_WIN, PIN(I_WIN) + (size_t)l * DM * NIN, DM, NIN, WL_IN, PIN(I_NMIX) + l * DM, 0)
.LBB0_85:
	v_mov_b32_e32 v6, 0
	s_mul_hi_i32 s12, s92, 0x66666667
	v_add_u32_e32 v6, 0, v6
	v_add_u32_e32 v6, 0x20158, v6
	s_nop 0
	s_lshr_b32 s13, s12, 31
	s_ashr_i32 s12, s12, 3
	s_add_i32 s13, s12, s13
	s_lshl_b32 s14, s13, 6
	s_mul_i32 s12, s13, 0xfffffb00
	s_waitcnt lgkmcnt(0)
	v_readlane_b32 s1, v251, 22
	s_add_i32 s12, s24, s12
	s_ashr_i32 s15, s14, 31
	s_mul_i32 s13, s13, 0x50000
	v_readlane_b32 s0, v251, 23
	s_mul_hi_i32 s16, s14, 0x1400
	s_add_u32 s17, s1, s13
	v_mov_b32_e32 v8, 0
	s_addc_u32 s16, s0, s16
	s_ashr_i32 s13, s12, 31
	s_lshl_b64 s[0:1], s[12:13], 2
	v_add_u32_e32 v8, 0, v8
	s_add_u32 s0, s17, s0
	v_add_u32_e32 v6, 0x20150, v8
	s_addc_u32 s1, s16, s1
	s_nop 0
	v_lshl_add_u64 v[6:7], s[0:1], 0, v[2:3]
	v_add_co_u32_e32 v8, vcc, s26, v6
	v_readlane_b32 s17, v251, 21
	v_addc_co_u32_e32 v9, vcc, 0, v7, vcc
	v_add_co_u32_e32 v10, vcc, s27, v6
	v_readlane_b32 s16, v251, 20
	s_nop 0
	v_addc_co_u32_e32 v11, vcc, 0, v7, vcc
	v_add_co_u32_e32 v12, vcc, s28, v6
	s_cmp_lg_u64 s[16:17], 0
	s_nop 0
	v_addc_co_u32_e32 v13, vcc, 0, v7, vcc
	v_add_co_u32_e32 v14, vcc, s29, v6
	s_cselect_b64 s[18:19], -1, 0
	s_nop 0
	v_addc_co_u32_e32 v15, vcc, 0, v7, vcc
	v_add_co_u32_e32 v16, vcc, s30, v6
	s_cmp_eq_u64 s[16:17], 0
	s_nop 0
	v_addc_co_u32_e32 v17, vcc, 0, v7, vcc
	v_add_co_u32_e32 v18, vcc, s31, v6
	s_nop 1
	v_addc_co_u32_e32 v19, vcc, 0, v7, vcc
	v_add_co_u32_e32 v20, vcc, s34, v6
	s_nop 1
	v_addc_co_u32_e32 v21, vcc, 0, v7, vcc
	v_add_co_u32_e32 v22, vcc, s35, v6
	s_nop 1
	v_addc_co_u32_e32 v23, vcc, 0, v7, vcc
	global_load_dword v73, v[8:9], off offset:1024
	global_load_dword v70, v[10:11], off offset:2048
	global_load_dword v71, v[12:13], off offset:3072
	global_load_dword v64, v[14:15], off
	global_load_dword v65, v[16:17], off offset:1024
	global_load_dword v66, v[18:19], off offset:2048
	global_load_dword v67, v[20:21], off offset:3072
	global_load_dword v60, v[22:23], off
	v_add_co_u32_e32 v8, vcc, s36, v6
	s_nop 1
	v_addc_co_u32_e32 v9, vcc, 0, v7, vcc
	v_add_co_u32_e32 v10, vcc, s37, v6
	s_nop 1
	v_addc_co_u32_e32 v11, vcc, 0, v7, vcc
	v_add_co_u32_e32 v12, vcc, s38, v6
	s_nop 1
	v_addc_co_u32_e32 v13, vcc, 0, v7, vcc
	v_add_co_u32_e32 v14, vcc, s39, v6
	s_nop 1
	v_addc_co_u32_e32 v15, vcc, 0, v7, vcc
	v_add_co_u32_e32 v16, vcc, s40, v6
	s_nop 1
	v_addc_co_u32_e32 v17, vcc, 0, v7, vcc
	v_add_co_u32_e32 v18, vcc, s41, v6
	s_nop 1
	v_addc_co_u32_e32 v19, vcc, 0, v7, vcc
	v_add_co_u32_e32 v20, vcc, s42, v6
	s_nop 1
	v_addc_co_u32_e32 v21, vcc, 0, v7, vcc
	v_add_co_u32_e32 v22, vcc, s43, v6
	s_nop 1
	v_addc_co_u32_e32 v23, vcc, 0, v7, vcc
	global_load_dword v61, v[8:9], off offset:1024
	global_load_dword v62, v[10:11], off offset:2048
	global_load_dword v63, v[12:13], off offset:3072
	global_load_dword v56, v[14:15], off
	global_load_dword v57, v[16:17], off offset:1024
	global_load_dword v58, v[18:19], off offset:2048
	global_load_dword v59, v[20:21], off offset:3072
	global_load_dword v52, v[22:23], off
	v_add_co_u32_e32 v8, vcc, s44, v6
	s_nop 1
	v_addc_co_u32_e32 v9, vcc, 0, v7, vcc
	v_add_co_u32_e32 v10, vcc, s45, v6
	s_nop 1
	v_addc_co_u32_e32 v11, vcc, 0, v7, vcc
	v_add_co_u32_e32 v12, vcc, s46, v6
	s_nop 1
	v_addc_co_u32_e32 v13, vcc, 0, v7, vcc
	v_add_co_u32_e32 v14, vcc, s47, v6
	s_nop 1
	v_addc_co_u32_e32 v15, vcc, 0, v7, vcc
	v_add_co_u32_e32 v16, vcc, s48, v6
	s_nop 1
	v_addc_co_u32_e32 v17, vcc, 0, v7, vcc
	v_add_co_u32_e32 v18, vcc, s49, v6
	s_nop 1
	v_addc_co_u32_e32 v19, vcc, 0, v7, vcc
	v_add_co_u32_e32 v20, vcc, s50, v6
	s_nop 1
	v_addc_co_u32_e32 v21, vcc, 0, v7, vcc
	v_add_co_u32_e32 v22, vcc, s51, v6
	s_nop 1
	v_addc_co_u32_e32 v23, vcc, 0, v7, vcc
	global_load_dword v53, v[8:9], off offset:1024
	global_load_dword v54, v[10:11], off offset:2048
	global_load_dword v55, v[12:13], off offset:3072
	global_load_dword v48, v[14:15], off
	global_load_dword v49, v[16:17], off offset:1024
	global_load_dword v50, v[18:19], off offset:2048
	global_load_dword v51, v[20:21], off offset:3072
	global_load_dword v44, v[22:23], off
	v_add_co_u32_e32 v8, vcc, s52, v6
	s_nop 1
	v_addc_co_u32_e32 v9, vcc, 0, v7, vcc
	v_add_co_u32_e32 v10, vcc, s53, v6
	s_nop 1
	v_addc_co_u32_e32 v11, vcc, 0, v7, vcc
	v_add_co_u32_e32 v12, vcc, s54, v6
	s_nop 1
	v_addc_co_u32_e32 v13, vcc, 0, v7, vcc
	v_add_co_u32_e32 v14, vcc, s55, v6
	s_nop 1
	v_addc_co_u32_e32 v15, vcc, 0, v7, vcc
	v_add_co_u32_e32 v16, vcc, s56, v6
	s_nop 1
	v_addc_co_u32_e32 v17, vcc, 0, v7, vcc
	v_add_co_u32_e32 v18, vcc, s57, v6
	s_nop 1
	v_addc_co_u32_e32 v19, vcc, 0, v7, vcc
	v_add_co_u32_e32 v20, vcc, s58, v6
	s_nop 1
	v_addc_co_u32_e32 v21, vcc, 0, v7, vcc
	v_add_co_u32_e32 v22, vcc, s59, v6
	s_nop 1
	v_addc_co_u32_e32 v23, vcc, 0, v7, vcc
	global_load_dword v45, v[8:9], off offset:1024
; __device__ __forceinline__ void transpose_item(const float* W, int K, int N, bf16_t* WT, const float* gk, int mode, LAS float* scr_, int item, int lane) {
;     ...
;     for (int kp = 0; kp < 32; ++kp) { va[kp] = src[(size_t)(2 * kp) * N]; vb[kp] = src[(size_t)(2 * kp + 1) * N]; }
; #pragma unroll
;     for (int kp = 0; kp < 32; ++kp) {
;         float a = va[kp], b = vb[kp];
;         if (gk) { a *= gk[k0 + 2 * kp]; b *= gk[k0 + 2 * kp + 1]; }
	global_load_dword v46, v[10:11], off offset:2048
	global_load_dword v47, v[12:13], off offset:3072
	global_load_dword v40, v[14:15], off
	global_load_dword v41, v[16:17], off offset:1024
	global_load_dword v42, v[18:19], off offset:2048
	global_load_dword v43, v[20:21], off offset:3072
	global_load_dword v36, v[22:23], off
	v_add_co_u32_e32 v8, vcc, s62, v6
	s_nop 1
	v_addc_co_u32_e32 v9, vcc, 0, v7, vcc
	v_add_co_u32_e32 v10, vcc, s63, v6
	s_nop 1
	v_addc_co_u32_e32 v11, vcc, 0, v7, vcc
	v_add_co_u32_e32 v12, vcc, s65, v6
	s_nop 1
	v_addc_co_u32_e32 v13, vcc, 0, v7, vcc
	v_add_co_u32_e32 v14, vcc, s66, v6
	s_nop 1
	v_addc_co_u32_e32 v15, vcc, 0, v7, vcc
	v_add_co_u32_e32 v16, vcc, s67, v6
	s_nop 1
	v_addc_co_u32_e32 v17, vcc, 0, v7, vcc
	v_add_co_u32_e32 v18, vcc, s68, v6
	s_nop 1
	v_addc_co_u32_e32 v19, vcc, 0, v7, vcc
	v_add_co_u32_e32 v20, vcc, s69, v6
	s_nop 1
	v_addc_co_u32_e32 v21, vcc, 0, v7, vcc
	v_add_co_u32_e32 v22, vcc, s70, v6
	s_nop 1
	v_addc_co_u32_e32 v23, vcc, 0, v7, vcc
	global_load_dword v37, v[8:9], off offset:1024
	global_load_dword v38, v[10:11], off offset:2048
	global_load_dword v39, v[12:13], off offset:3072
	global_load_dword v32, v[14:15], off
	global_load_dword v33, v[16:17], off offset:1024
	global_load_dword v34, v[18:19], off offset:2048
	global_load_dword v35, v[20:21], off offset:3072
	global_load_dword v28, v[22:23], off
	v_add_co_u32_e32 v8, vcc, s71, v6
	s_nop 1
	v_addc_co_u32_e32 v9, vcc, 0, v7, vcc
	v_add_co_u32_e32 v10, vcc, s72, v6
	s_nop 1
	v_addc_co_u32_e32 v11, vcc, 0, v7, vcc
	v_add_co_u32_e32 v12, vcc, s73, v6
	s_nop 1
	v_addc_co_u32_e32 v13, vcc, 0, v7, vcc
	v_add_co_u32_e32 v14, vcc, s74, v6
	s_nop 1
	v_addc_co_u32_e32 v15, vcc, 0, v7, vcc
	v_add_co_u32_e32 v16, vcc, s75, v6
	s_nop 1
	v_addc_co_u32_e32 v17, vcc, 0, v7, vcc
	v_add_co_u32_e32 v18, vcc, s76, v6
	s_nop 1
	v_addc_co_u32_e32 v19, vcc, 0, v7, vcc
	v_add_co_u32_e32 v20, vcc, s77, v6
	s_nop 1
	v_addc_co_u32_e32 v21, vcc, 0, v7, vcc
	v_add_co_u32_e32 v74, vcc, s78, v6
	s_nop 1
	v_addc_co_u32_e32 v75, vcc, 0, v7, vcc
	global_load_dword v29, v[8:9], off offset:1024
	global_load_dword v30, v[10:11], off offset:2048
	global_load_dword v31, v[12:13], off offset:3072
	global_load_dword v22, v[14:15], off
	global_load_dword v23, v[16:17], off offset:1024
	global_load_dword v24, v[18:19], off offset:2048
	global_load_dword v25, v[20:21], off offset:3072
	s_nop 0
	global_load_dword v18, v[74:75], off
	v_add_co_u32_e32 v8, vcc, s79, v6
	s_nop 1
	v_addc_co_u32_e32 v9, vcc, 0, v7, vcc
	v_add_co_u32_e32 v10, vcc, s80, v6
	s_nop 1
	v_addc_co_u32_e32 v11, vcc, 0, v7, vcc
	v_add_co_u32_e32 v12, vcc, s81, v6
	s_nop 1
	v_addc_co_u32_e32 v13, vcc, 0, v7, vcc
	v_add_co_u32_e32 v14, vcc, s82, v6
	s_nop 1
	v_addc_co_u32_e32 v15, vcc, 0, v7, vcc
	v_add_co_u32_e32 v16, vcc, s83, v6
	s_nop 1
	v_addc_co_u32_e32 v17, vcc, 0, v7, vcc
	v_add_co_u32_e32 v74, vcc, s84, v6
	s_nop 1
	v_addc_co_u32_e32 v75, vcc, 0, v7, vcc
	v_add_co_u32_e32 v80, vcc, s85, v6
	s_nop 1
	v_addc_co_u32_e32 v81, vcc, 0, v7, vcc
	v_add_co_u32_e32 v82, vcc, s86, v6
	s_nop 1
	v_addc_co_u32_e32 v83, vcc, 0, v7, vcc
	global_load_dword v19, v[8:9], off offset:1024
	global_load_dword v20, v[10:11], off offset:2048
	global_load_dword v21, v[12:13], off offset:3072
	s_nop 0
	global_load_dword v14, v[14:15], off
	s_nop 0
	global_load_dword v15, v[16:17], off offset:1024
	s_nop 0
	global_load_dword v16, v[74:75], off offset:2048
	global_load_dword v17, v[80:81], off offset:3072
	global_load_dword v10, v[82:83], off
	v_add_co_u32_e32 v8, vcc, s87, v6
	s_nop 1
	v_addc_co_u32_e32 v9, vcc, 0, v7, vcc
	v_add_co_u32_e32 v12, vcc, s88, v6
	s_nop 1
	v_addc_co_u32_e32 v13, vcc, 0, v7, vcc
	v_add_co_u32_e32 v74, vcc, s89, v6
	s_nop 1
	v_addc_co_u32_e32 v75, vcc, 0, v7, vcc
	v_add_co_u32_e32 v80, vcc, s90, v6
	s_nop 1
	v_addc_co_u32_e32 v81, vcc, 0, v7, vcc
	v_add_co_u32_e32 v82, vcc, s91, v6
	s_nop 1
	v_addc_co_u32_e32 v83, vcc, 0, v7, vcc
	v_add_co_u32_e32 v84, vcc, 0x4d000, v6
	s_nop 1
	v_addc_co_u32_e32 v85, vcc, 0, v7, vcc
	v_add_co_u32_e32 v86, vcc, 0x4e000, v6
	s_nop 1
	v_addc_co_u32_e32 v87, vcc, 0, v7, vcc
	global_load_dword v72, v2, s[0:1]
	global_load_dword v11, v[8:9], off offset:1024
	s_nop 0
	global_load_dword v12, v[12:13], off offset:2048
	s_nop 0
	global_load_dword v13, v[74:75], off offset:3072
	global_load_dword v6, v[80:81], off
	global_load_dword v7, v[82:83], off offset:1024
	global_load_dword v8, v[84:85], off offset:2048
	global_load_dword v9, v[86:87], off offset:3072
	s_mov_b64 s[0:1], -1
	s_cbranch_scc1 .LBB0_87
	s_lshl_b64 s[0:1], s[14:15], 2
	s_add_u32 s0, s16, s0
	s_addc_u32 s1, s17, s1
	global_load_dwordx4 v[80:83], v3, s[0:1]
	s_mov_b64 s[0:1], 0
	s_waitcnt vmcnt(0)
	v_pk_mul_f32 v[68:69], v[72:73], v[80:81]
	v_pk_mul_f32 v[74:75], v[70:71], v[82:83]

; #define LAS __attribute__((address_space(3)))
; #define PIN(i) ((const float*)ldq_(L, (i)))
; #define PREP_CONV(bit, SRC, Kd, Nd, DST, GK, MODE) if (mask & (bit)) { for (int it = gw; it < ((Kd) / 64) * ((Nd) / 64); it += NGW) transpose_item((SRC), (Kd), (Nd), (bf16_t*)(wl + (DST)), (GK), (MODE), scr, it, lane); }
; __device__ __forceinline__ void transpose_item(const float* W, int K, int N, bf16_t* WT, const float* gk, int mode, LAS float* scr_, int item, int lane) {
;     LAS unsigned* scr = (LAS unsigned*)scr_;
;     const int nblk = N / 64, kb = item / nblk, nb = item % nblk, k0 = 64 * kb, n0 = 64 * nb;
;     const int sc = (mode == 1) ? (((n0 >> 7) & 1) * DFF + (n0 >> 8) * 128 + (n0 & 127)) : n0;
;     const float* src = W + (size_t)k0 * N + sc + lane;
;     float va[32], vb[32];
; #pragma unroll
;     for (int kp = 0; kp < 32; ++kp) { va[kp] = src[(size_t)(2 * kp) * N]; vb[kp] = src[(size_t)(2 * kp + 1) * N]; }
; #pragma unroll
;     for (int kp = 0; kp < 32; ++kp) {
;         float a = va[kp], b = vb[kp];
;         if (gk) { a *= gk[k0 + 2 * kp]; b *= gk[k0 + 2 * kp + 1]; }
; __device__ __forceinline__ void prep(const Params& p, LAS unsigned char* L, int wv, int vb, int nvb, int l, int mask) {
;     ...
;     PREP_CONV(PM_FFB_IN, PIN(I_WFFB_IN) + (size_t)l * DM * NFF2, DM, NFF2, WL_FFB_IN, PIN(I_NFFB) + l * DM, 1)
.LBB0_155:
	v_mov_b32_e32 v6, 0
	s_mul_hi_i32 s0, s92, 0x2e8ba2e9
	v_add_u32_e32 v6, 0, v6
	v_add_u32_e32 v6, 0x20198, v6
	s_lshr_b32 s10, s0, 31
	s_ashr_i32 s0, s0, 4
	s_nop 0
	s_add_i32 s15, s0, s10
	s_mul_i32 s0, s15, 0xffffea00
	s_mul_i32 s11, s15, 0xfffff500
	s_add_i32 s93, s18, s0
	s_bfe_i32 s0, s92, 0x10001
	s_add_i32 s11, s24, s11
	s_and_b32 s0, s0, 0xb00
	s_and_b32 s11, s11, 0xffffff80
	s_lshl_b32 s10, s15, 6
	s_add_i32 s0, s0, s11
	s_and_b32 s11, s93, 64
	s_waitcnt lgkmcnt(0)
	v_readlane_b32 s14, v251, 38
	s_or_b32 s0, s0, s11
	s_ashr_i32 s11, s10, 31
	s_mul_i32 s15, s15, 0x160000
	v_readlane_b32 s1, v251, 39
	s_mul_hi_i32 s16, s10, 0x5800
	s_add_u32 s14, s14, s15
	v_mov_b32_e32 v8, 0
	s_addc_u32 s15, s1, s16
	s_ashr_i32 s1, s0, 31
	s_lshl_b64 s[0:1], s[0:1], 2
	v_add_u32_e32 v8, 0, v8
	s_add_u32 s0, s14, s0
	v_add_u32_e32 v6, 0x20190, v8
	s_addc_u32 s1, s15, s1
	s_nop 0
	v_lshl_add_u64 v[6:7], s[0:1], 0, v[2:3]
	v_add_co_u32_e32 v8, vcc, s26, v6
	v_readlane_b32 s15, v251, 37
	v_addc_co_u32_e32 v9, vcc, 0, v7, vcc
	v_add_co_u32_e32 v10, vcc, s27, v6
	v_readlane_b32 s14, v251, 36
	s_nop 0
	v_addc_co_u32_e32 v11, vcc, 0, v7, vcc
	v_add_co_u32_e32 v12, vcc, s28, v6
	s_cmp_lg_u64 s[14:15], 0
	s_nop 0
	v_addc_co_u32_e32 v13, vcc, 0, v7, vcc
	v_add_co_u32_e32 v14, vcc, s29, v6
	s_cselect_b64 s[16:17], -1, 0
	s_nop 0
	v_addc_co_u32_e32 v15, vcc, 0, v7, vcc
	v_add_co_u32_e32 v16, vcc, s30, v6
	s_cmp_eq_u64 s[14:15], 0
	s_nop 0
	v_addc_co_u32_e32 v17, vcc, 0, v7, vcc
	v_add_co_u32_e32 v18, vcc, s31, v6
	s_nop 1
	v_addc_co_u32_e32 v19, vcc, 0, v7, vcc
	v_add_co_u32_e32 v20, vcc, s34, v6
	s_nop 1
	v_addc_co_u32_e32 v21, vcc, 0, v7, vcc
	v_add_co_u32_e32 v22, vcc, s35, v6
	s_nop 1
	v_addc_co_u32_e32 v23, vcc, 0, v7, vcc
	global_load_dword v73, v[8:9], off offset:2048
	global_load_dword v70, v[10:11], off
	global_load_dword v71, v[12:13], off offset:2048
	global_load_dword v64, v[14:15], off
	global_load_dword v65, v[16:17], off offset:2048
	global_load_dword v66, v[18:19], off
	global_load_dword v67, v[20:21], off offset:2048
	global_load_dword v60, v[22:23], off
	v_add_co_u32_e32 v8, vcc, s36, v6
	s_nop 1
	v_addc_co_u32_e32 v9, vcc, 0, v7, vcc
	v_add_co_u32_e32 v10, vcc, s37, v6
	s_nop 1
	v_addc_co_u32_e32 v11, vcc, 0, v7, vcc
	v_add_co_u32_e32 v12, vcc, s38, v6
	s_nop 1
	v_addc_co_u32_e32 v13, vcc, 0, v7, vcc
	v_add_co_u32_e32 v14, vcc, s39, v6
	s_nop 1
	v_addc_co_u32_e32 v15, vcc, 0, v7, vcc
	v_add_co_u32_e32 v16, vcc, s40, v6
	s_nop 1
	v_addc_co_u32_e32 v17, vcc, 0, v7, vcc
	v_add_co_u32_e32 v18, vcc, s41, v6
	s_nop 1
	v_addc_co_u32_e32 v19, vcc, 0, v7, vcc
	v_add_co_u32_e32 v20, vcc, s42, v6
	s_nop 1
	v_addc_co_u32_e32 v21, vcc, 0, v7, vcc
	v_add_co_u32_e32 v22, vcc, s43, v6
	s_nop 1
	v_addc_co_u32_e32 v23, vcc, 0, v7, vcc
	global_load_dword v61, v[8:9], off offset:2048
	global_load_dword v62, v[10:11], off
	global_load_dword v63, v[12:13], off offset:2048
	global_load_dword v56, v[14:15], off
	global_load_dword v57, v[16:17], off offset:2048
	global_load_dword v58, v[18:19], off
	global_load_dword v59, v[20:21], off offset:2048
	global_load_dword v52, v[22:23], off
	v_add_co_u32_e32 v8, vcc, s44, v6
	s_nop 1
	v_addc_co_u32_e32 v9, vcc, 0, v7, vcc
	v_add_co_u32_e32 v10, vcc, s45, v6
	s_nop 1
	v_addc_co_u32_e32 v11, vcc, 0, v7, vcc
	v_add_co_u32_e32 v12, vcc, s46, v6
	s_nop 1
	v_addc_co_u32_e32 v13, vcc, 0, v7, vcc
	v_add_co_u32_e32 v14, vcc, s47, v6
	s_nop 1
	v_addc_co_u32_e32 v15, vcc, 0, v7, vcc
	v_add_co_u32_e32 v16, vcc, s48, v6
	s_nop 1
	v_addc_co_u32_e32 v17, vcc, 0, v7, vcc
	v_add_co_u32_e32 v18, vcc, s49, v6
	s_nop 1
	v_addc_co_u32_e32 v19, vcc, 0, v7, vcc
	v_add_co_u32_e32 v20, vcc, s50, v6
	s_nop 1
	v_addc_co_u32_e32 v21, vcc, 0, v7, vcc
	v_add_co_u32_e32 v22, vcc, s51, v6
	s_nop 1
	v_addc_co_u32_e32 v23, vcc, 0, v7, vcc
	global_load_dword v53, v[8:9], off offset:2048
	global_load_dword v54, v[10:11], off
	global_load_dword v55, v[12:13], off offset:2048
	global_load_dword v48, v[14:15], off
	global_load_dword v49, v[16:17], off offset:2048
	global_load_dword v50, v[18:19], off
	global_load_dword v51, v[20:21], off offset:2048
	global_load_dword v44, v[22:23], off
	v_add_co_u32_e32 v8, vcc, s52, v6
	s_nop 1
	v_addc_co_u32_e32 v9, vcc, 0, v7, vcc
	v_add_co_u32_e32 v10, vcc, s53, v6
	s_nop 1
	v_addc_co_u32_e32 v11, vcc, 0, v7, vcc
	v_add_co_u32_e32 v12, vcc, s54, v6
	s_nop 1
	v_addc_co_u32_e32 v13, vcc, 0, v7, vcc
	v_add_co_u32_e32 v14, vcc, s55, v6
	s_nop 1
	v_addc_co_u32_e32 v15, vcc, 0, v7, vcc
	v_add_co_u32_e32 v16, vcc, s56, v6
	s_nop 1
	v_addc_co_u32_e32 v17, vcc, 0, v7, vcc
	v_add_co_u32_e32 v18, vcc, s57, v6
	s_nop 1
	v_addc_co_u32_e32 v19, vcc, 0, v7, vcc
	v_add_co_u32_e32 v20, vcc, s58, v6
	s_nop 1
	v_addc_co_u32_e32 v21, vcc, 0, v7, vcc
	v_add_co_u32_e32 v22, vcc, s59, v6
; __device__ __forceinline__ void transpose_item(const float* W, int K, int N, bf16_t* WT, const float* gk, int mode, LAS float* scr_, int item, int lane) {
;     ...
;     for (int kp = 0; kp < 32; ++kp) { va[kp] = src[(size_t)(2 * kp) * N]; vb[kp] = src[(size_t)(2 * kp + 1) * N]; }
; #pragma unroll
;     for (int kp = 0; kp < 32; ++kp) {
;         float a = va[kp], b = vb[kp];
;         if (gk) { a *= gk[k0 + 2 * kp]; b *= gk[k0 + 2 * kp + 1]; }
	s_nop 1
	v_addc_co_u32_e32 v23, vcc, 0, v7, vcc
	global_load_dword v45, v[8:9], off offset:2048
	global_load_dword v46, v[10:11], off
	global_load_dword v47, v[12:13], off offset:2048
	global_load_dword v40, v[14:15], off
	global_load_dword v41, v[16:17], off offset:2048
	global_load_dword v42, v[18:19], off
	global_load_dword v43, v[20:21], off offset:2048
	global_load_dword v36, v[22:23], off
	v_add_co_u32_e32 v8, vcc, s62, v6
	s_nop 1
	v_addc_co_u32_e32 v9, vcc, 0, v7, vcc
	v_add_co_u32_e32 v10, vcc, s63, v6
	s_nop 1
	v_addc_co_u32_e32 v11, vcc, 0, v7, vcc
	v_add_co_u32_e32 v12, vcc, s65, v6
	s_nop 1
	v_addc_co_u32_e32 v13, vcc, 0, v7, vcc
	v_add_co_u32_e32 v14, vcc, s66, v6
	s_nop 1
	v_addc_co_u32_e32 v15, vcc, 0, v7, vcc
	v_add_co_u32_e32 v16, vcc, s67, v6
	s_nop 1
	v_addc_co_u32_e32 v17, vcc, 0, v7, vcc
	v_add_co_u32_e32 v18, vcc, s68, v6
	s_nop 1
	v_addc_co_u32_e32 v19, vcc, 0, v7, vcc
	v_add_co_u32_e32 v20, vcc, s69, v6
	s_nop 1
	v_addc_co_u32_e32 v21, vcc, 0, v7, vcc
	v_add_co_u32_e32 v22, vcc, s70, v6
	s_nop 1
	v_addc_co_u32_e32 v23, vcc, 0, v7, vcc
	global_load_dword v37, v[8:9], off offset:2048
	global_load_dword v38, v[10:11], off
	global_load_dword v39, v[12:13], off offset:2048
	global_load_dword v32, v[14:15], off
	global_load_dword v33, v[16:17], off offset:2048
	global_load_dword v34, v[18:19], off
	global_load_dword v35, v[20:21], off offset:2048
	global_load_dword v28, v[22:23], off
	v_add_co_u32_e32 v8, vcc, s71, v6
	s_nop 1
	v_addc_co_u32_e32 v9, vcc, 0, v7, vcc
	v_add_co_u32_e32 v10, vcc, s72, v6
	s_nop 1
	v_addc_co_u32_e32 v11, vcc, 0, v7, vcc
	v_add_co_u32_e32 v12, vcc, s73, v6
	s_nop 1
	v_addc_co_u32_e32 v13, vcc, 0, v7, vcc
	v_add_co_u32_e32 v14, vcc, s74, v6
	s_nop 1
	v_addc_co_u32_e32 v15, vcc, 0, v7, vcc
	v_add_co_u32_e32 v16, vcc, s75, v6
	s_nop 1
	v_addc_co_u32_e32 v17, vcc, 0, v7, vcc
	v_add_co_u32_e32 v18, vcc, s76, v6
	s_nop 1
	v_addc_co_u32_e32 v19, vcc, 0, v7, vcc
	v_add_co_u32_e32 v20, vcc, s77, v6
	s_nop 1
	v_addc_co_u32_e32 v21, vcc, 0, v7, vcc
	v_add_co_u32_e32 v74, vcc, s78, v6
	s_nop 1
	v_addc_co_u32_e32 v75, vcc, 0, v7, vcc
	global_load_dword v29, v[8:9], off offset:2048
	global_load_dword v30, v[10:11], off
	global_load_dword v31, v[12:13], off offset:2048
	global_load_dword v22, v[14:15], off
	global_load_dword v23, v[16:17], off offset:2048
	global_load_dword v24, v[18:19], off
	global_load_dword v25, v[20:21], off offset:2048
	s_nop 0
	global_load_dword v18, v[74:75], off
	v_add_co_u32_e32 v8, vcc, s79, v6
	s_nop 1
	v_addc_co_u32_e32 v9, vcc, 0, v7, vcc
	v_add_co_u32_e32 v10, vcc, s80, v6
	s_nop 1
	v_addc_co_u32_e32 v11, vcc, 0, v7, vcc
	v_add_co_u32_e32 v12, vcc, s81, v6
	s_nop 1
	v_addc_co_u32_e32 v13, vcc, 0, v7, vcc
	v_add_co_u32_e32 v14, vcc, s82, v6
	s_nop 1
	v_addc_co_u32_e32 v15, vcc, 0, v7, vcc
	v_add_co_u32_e32 v16, vcc, s83, v6
	s_nop 1
	v_addc_co_u32_e32 v17, vcc, 0, v7, vcc
	v_add_co_u32_e32 v74, vcc, s84, v6
	s_nop 1
	v_addc_co_u32_e32 v75, vcc, 0, v7, vcc
	v_add_co_u32_e32 v80, vcc, s85, v6
	s_nop 1
	v_addc_co_u32_e32 v81, vcc, 0, v7, vcc
	v_add_co_u32_e32 v82, vcc, s86, v6
	s_nop 1
	v_addc_co_u32_e32 v83, vcc, 0, v7, vcc
	global_load_dword v19, v[8:9], off offset:2048
	global_load_dword v20, v[10:11], off
	global_load_dword v21, v[12:13], off offset:2048
	s_nop 0
	global_load_dword v14, v[14:15], off
	s_nop 0
	global_load_dword v15, v[16:17], off offset:2048
	s_nop 0
	global_load_dword v16, v[74:75], off
	global_load_dword v17, v[80:81], off offset:2048
	global_load_dword v10, v[82:83], off
	v_add_co_u32_e32 v8, vcc, s87, v6
	s_nop 1
	v_addc_co_u32_e32 v9, vcc, 0, v7, vcc
	v_add_co_u32_e32 v12, vcc, s88, v6
	s_nop 1
	v_addc_co_u32_e32 v13, vcc, 0, v7, vcc
	v_add_co_u32_e32 v74, vcc, s89, v6
	s_nop 1
	v_addc_co_u32_e32 v75, vcc, 0, v7, vcc
	v_add_co_u32_e32 v80, vcc, s90, v6
	s_nop 1
	v_addc_co_u32_e32 v81, vcc, 0, v7, vcc
	v_add_co_u32_e32 v82, vcc, s91, v6
	s_nop 1
	v_addc_co_u32_e32 v83, vcc, 0, v7, vcc
	v_add_co_u32_e32 v84, vcc, 0x155000, v6
	s_nop 1
	v_addc_co_u32_e32 v85, vcc, 0, v7, vcc
	v_add_co_u32_e32 v86, vcc, 0x15a000, v6
	s_nop 1
	v_addc_co_u32_e32 v87, vcc, 0, v7, vcc
	global_load_dword v72, v2, s[0:1]
	global_load_dword v11, v[8:9], off offset:2048
	s_nop 0
	global_load_dword v12, v[12:13], off
	s_nop 0
	global_load_dword v13, v[74:75], off offset:2048
	global_load_dword v6, v[80:81], off
	global_load_dword v7, v[82:83], off offset:2048
	global_load_dword v8, v[84:85], off
	global_load_dword v9, v[86:87], off offset:2048
	s_mov_b64 s[0:1], -1
	s_cbranch_scc1 .LBB0_157
	s_lshl_b64 s[0:1], s[10:11], 2
	s_add_u32 s0, s14, s0
	s_addc_u32 s1, s15, s1
	global_load_dwordx4 v[80:83], v3, s[0:1]
	s_mov_b64 s[0:1], 0
	s_waitcnt vmcnt(0)
	v_pk_mul_f32 v[68:69], v[72:73], v[80:81]
	v_pk_mul_f32 v[74:75], v[70:71], v[82:83]

; #define LAS __attribute__((address_space(3)))
; #define PIN(i) ((const float*)ldq_(L, (i)))
; #define PREP_CONV(bit, SRC, Kd, Nd, DST, GK, MODE) if (mask & (bit)) { for (int it = gw; it < ((Kd) / 64) * ((Nd) / 64); it += NGW) transpose_item((SRC), (Kd), (Nd), (bf16_t*)(wl + (DST)), (GK), (MODE), scr, it, lane); }
; __device__ __forceinline__ void transpose_item(const float* W, int K, int N, bf16_t* WT, const float* gk, int mode, LAS float* scr_, int item, int lane) {
;     LAS unsigned* scr = (LAS unsigned*)scr_;
;     const int nblk = N / 64, kb = item / nblk, nb = item % nblk, k0 = 64 * kb, n0 = 64 * nb;
;     const int sc = (mode == 1) ? (((n0 >> 7) & 1) * DFF + (n0 >> 8) * 128 + (n0 & 127)) : n0;
;     const float* src = W + (size_t)k0 * N + sc + lane;
;     float va[32], vb[32];
; #pragma unroll
;     for (int kp = 0; kp < 32; ++kp) { va[kp] = src[(size_t)(2 * kp) * N]; vb[kp] = src[(size_t)(2 * kp + 1) * N]; }
; #pragma unroll
;     for (int kp = 0; kp < 32; ++kp) {
;         float a = va[kp], b = vb[kp];
;         if (gk) { a *= gk[k0 + 2 * kp]; b *= gk[k0 + 2 * kp + 1]; }
; __device__ __forceinline__ void prep(const Params& p, LAS unsigned char* L, int wv, int vb, int nvb, int l, int mask) {
;     ...
;     PREP_CONV(PM_PEG, PIN(I_WPEG) + (size_t)l * DM * DM, DM, DM, WL_PEG, PIN(I_NPE) + l * DM, 0)
.LBB0_225:
	v_mov_b32_e32 v6, 0
	s_ashr_i32 s0, s52, 31
	v_add_u32_e32 v6, 0, v6
	v_add_u32_e32 v6, 0x201b0, v6
	s_nop 0
	s_lshr_b32 s0, s0, 28
	s_add_i32 s0, s52, s0
	s_ashr_i32 s0, s0, 4
	s_lshl_b32 s6, s0, 6
	s_lshl_b32 s53, s0, 10
	s_ashr_i32 s7, s6, 31
	s_waitcnt lgkmcnt(0)
	v_readlane_b32 s12, v251, 44
	s_sub_i32 s0, s14, s53
	s_lshl_b64 s[10:11], s[6:7], 12
	v_readlane_b32 s1, v251, 45
	s_add_u32 s10, s12, s10
	s_addc_u32 s11, s1, s11
	s_ashr_i32 s1, s0, 31
	v_mov_b32_e32 v8, 0
	s_lshl_b64 s[0:1], s[0:1], 2
	s_add_u32 s0, s10, s0
	v_add_u32_e32 v8, 0, v8
	s_addc_u32 s1, s11, s1
	v_add_u32_e32 v6, 0x201a8, v8
	v_lshl_add_u64 v[8:9], s[0:1], 0, v[2:3]
	v_add_co_u32_e32 v72, vcc, s16, v8
	s_nop 0
	s_nop 0
	v_addc_co_u32_e32 v73, vcc, 0, v9, vcc
	v_add_co_u32_e32 v74, vcc, s17, v8
	v_readlane_b32 s11, v251, 43
	v_addc_co_u32_e32 v75, vcc, 0, v9, vcc
	v_add_co_u32_e32 v6, vcc, s18, v8
	v_readlane_b32 s10, v251, 42
	s_nop 0
	v_addc_co_u32_e32 v7, vcc, 0, v9, vcc
	v_add_co_u32_e32 v10, vcc, s19, v8
	s_cmp_lg_u64 s[10:11], 0
	s_nop 0
	v_addc_co_u32_e32 v11, vcc, 0, v9, vcc
	v_add_co_u32_e32 v12, vcc, s23, v8
	s_cselect_b64 s[12:13], -1, 0
	s_nop 0
	v_addc_co_u32_e32 v13, vcc, 0, v9, vcc
	v_add_co_u32_e32 v14, vcc, s24, v8
	s_cmp_eq_u64 s[10:11], 0
	s_nop 0
	v_addc_co_u32_e32 v15, vcc, 0, v9, vcc
	global_load_dword v67, v[6:7], off offset:-4096
	global_load_dword v64, v[6:7], off
	global_load_dword v65, v[10:11], off offset:-4096
	global_load_dword v60, v[10:11], off
	global_load_dword v61, v[12:13], off offset:-4096
	global_load_dword v62, v[12:13], off
	global_load_dword v63, v[14:15], off offset:-4096
	global_load_dword v56, v[14:15], off
	v_add_co_u32_e32 v6, vcc, s25, v8
	s_nop 1
	v_addc_co_u32_e32 v7, vcc, 0, v9, vcc
	v_add_co_u32_e32 v10, vcc, s26, v8
	s_nop 1
	v_addc_co_u32_e32 v11, vcc, 0, v9, vcc
	v_add_co_u32_e32 v12, vcc, s27, v8
	s_nop 1
	v_addc_co_u32_e32 v13, vcc, 0, v9, vcc
	v_add_co_u32_e32 v14, vcc, s28, v8
	s_nop 1
	v_addc_co_u32_e32 v15, vcc, 0, v9, vcc
	global_load_dword v57, v[6:7], off offset:-4096
	global_load_dword v58, v[6:7], off
	global_load_dword v59, v[10:11], off offset:-4096
	global_load_dword v52, v[10:11], off
	global_load_dword v53, v[12:13], off offset:-4096
	global_load_dword v54, v[12:13], off
	global_load_dword v55, v[14:15], off offset:-4096
	global_load_dword v48, v[14:15], off
	v_add_co_u32_e32 v6, vcc, s29, v8
	s_nop 1
	v_addc_co_u32_e32 v7, vcc, 0, v9, vcc
	v_add_co_u32_e32 v10, vcc, s30, v8
	s_nop 1
	v_addc_co_u32_e32 v11, vcc, 0, v9, vcc
	v_add_co_u32_e32 v12, vcc, s31, v8
	s_nop 1
	v_addc_co_u32_e32 v13, vcc, 0, v9, vcc
	v_add_co_u32_e32 v14, vcc, s34, v8
	s_nop 1
	v_addc_co_u32_e32 v15, vcc, 0, v9, vcc
	global_load_dword v49, v[6:7], off offset:-4096
	global_load_dword v50, v[6:7], off
	global_load_dword v51, v[10:11], off offset:-4096
	global_load_dword v44, v[10:11], off
	global_load_dword v45, v[12:13], off offset:-4096
	global_load_dword v46, v[12:13], off
	global_load_dword v47, v[14:15], off offset:-4096
	global_load_dword v40, v[14:15], off
	v_add_co_u32_e32 v6, vcc, s35, v8
	s_nop 1
	v_addc_co_u32_e32 v7, vcc, 0, v9, vcc
	v_add_co_u32_e32 v10, vcc, s36, v8
	s_nop 1
	v_addc_co_u32_e32 v11, vcc, 0, v9, vcc
	v_add_co_u32_e32 v12, vcc, s37, v8
	s_nop 1
	v_addc_co_u32_e32 v13, vcc, 0, v9, vcc
	v_add_co_u32_e32 v14, vcc, s38, v8
	s_nop 1
	v_addc_co_u32_e32 v15, vcc, 0, v9, vcc
	global_load_dword v41, v[6:7], off offset:-4096
	global_load_dword v42, v[6:7], off
	global_load_dword v43, v[10:11], off offset:-4096
	global_load_dword v36, v[10:11], off
	global_load_dword v37, v[12:13], off offset:-4096
	global_load_dword v38, v[12:13], off
	global_load_dword v39, v[14:15], off offset:-4096
	global_load_dword v32, v[14:15], off
	v_add_co_u32_e32 v6, vcc, s39, v8
	s_nop 1
	v_addc_co_u32_e32 v7, vcc, 0, v9, vcc
	v_add_co_u32_e32 v10, vcc, s40, v8
	s_nop 1
	v_addc_co_u32_e32 v11, vcc, 0, v9, vcc
	v_add_co_u32_e32 v12, vcc, s41, v8
	s_nop 1
	v_addc_co_u32_e32 v13, vcc, 0, v9, vcc
	v_add_co_u32_e32 v14, vcc, s42, v8
	s_nop 1
	v_addc_co_u32_e32 v15, vcc, 0, v9, vcc
	global_load_dword v33, v[6:7], off offset:-4096
	global_load_dword v34, v[6:7], off
	global_load_dword v35, v[10:11], off offset:-4096
	global_load_dword v28, v[10:11], off
	global_load_dword v29, v[12:13], off offset:-4096
	global_load_dword v30, v[12:13], off
	global_load_dword v31, v[14:15], off offset:-4096
	global_load_dword v22, v[14:15], off
	v_add_co_u32_e32 v6, vcc, s43, v8
	s_nop 1
	v_addc_co_u32_e32 v7, vcc, 0, v9, vcc
	v_add_co_u32_e32 v10, vcc, s44, v8
	s_nop 1
	v_addc_co_u32_e32 v11, vcc, 0, v9, vcc
	v_add_co_u32_e32 v12, vcc, s45, v8
	s_nop 1
	v_addc_co_u32_e32 v13, vcc, 0, v9, vcc
	v_add_co_u32_e32 v14, vcc, s46, v8
	s_nop 1
	v_addc_co_u32_e32 v15, vcc, 0, v9, vcc
	global_load_dword v23, v[6:7], off offset:-4096
	global_load_dword v24, v[6:7], off
	global_load_dword v25, v[10:11], off offset:-4096
	global_load_dword v18, v[10:11], off
	global_load_dword v19, v[12:13], off offset:-4096
	global_load_dword v20, v[12:13], off
	global_load_dword v21, v[14:15], off offset:-4096
	s_nop 0
	global_load_dword v14, v[14:15], off
	v_add_co_u32_e32 v6, vcc, s47, v8
	s_nop 1
	v_addc_co_u32_e32 v7, vcc, 0, v9, vcc
	v_add_co_u32_e32 v10, vcc, s48, v8
	s_nop 1
	v_addc_co_u32_e32 v11, vcc, 0, v9, vcc
	v_add_co_u32_e32 v12, vcc, s49, v8
	s_nop 1
	v_addc_co_u32_e32 v13, vcc, 0, v9, vcc
	v_add_co_u32_e32 v70, vcc, s50, v8
	s_nop 1
	v_addc_co_u32_e32 v71, vcc, 0, v9, vcc
	v_add_co_u32_e32 v80, vcc, s51, v8
	global_load_dword v15, v[6:7], off offset:-4096
	global_load_dword v16, v[6:7], off
	global_load_dword v17, v[10:11], off offset:-4096
	s_nop 0
	global_load_dword v10, v[10:11], off
	s_nop 0
	global_load_dword v11, v[12:13], off offset:-4096
	s_nop 0
	global_load_dword v12, v[12:13], off
	s_nop 0
	global_load_dword v13, v[70:71], off offset:-4096
	global_load_dword v6, v[70:71], off
	v_addc_co_u32_e32 v81, vcc, 0, v9, vcc
	v_add_co_u32_e32 v82, vcc, 0x3e000, v8
	s_nop 1
	v_addc_co_u32_e32 v83, vcc, 0, v9, vcc
	v_add_co_u32_e32 v84, vcc, 0x3f000, v8
	s_nop 1
	v_addc_co_u32_e32 v85, vcc, 0, v9, vcc
	global_load_dword v70, v2, s[0:1]
	global_load_dword v71, v[72:73], off offset:-4096
	s_nop 0
	global_load_dword v72, v[72:73], off
	s_nop 0
	global_load_dword v73, v[74:75], off offset:-4096
	global_load_dword v66, v[74:75], off
	global_load_dword v7, v[80:81], off
	global_load_dword v8, v[82:83], off
	global_load_dword v9, v[84:85], off
	s_mov_b64 s[0:1], -1
	s_cbranch_scc1 .LBB0_227
	s_lshl_b64 s[0:1], s[6:7], 2
	s_add_u32 s0, s10, s0
	s_addc_u32 s1, s11, s1
	global_load_dwordx4 v[80:83], v3, s[0:1]
	s_mov_b64 s[0:1], 0
	s_waitcnt vmcnt(0)
	v_pk_mul_f32 v[68:69], v[70:71], v[80:81]
	v_pk_mul_f32 v[74:75], v[72:73], v[82:83]

; #define LAS __attribute__((address_space(3)))
; #define PIN(i) ((const float*)ldq_(L, (i)))
; #define PREP_CONV(bit, SRC, Kd, Nd, DST, GK, MODE) if (mask & (bit)) { for (int it = gw; it < ((Kd) / 64) * ((Nd) / 64); it += NGW) transpose_item((SRC), (Kd), (Nd), (bf16_t*)(wl + (DST)), (GK), (MODE), scr, it, lane); }
; __device__ __forceinline__ void transpose_item(const float* W, int K, int N, bf16_t* WT, const float* gk, int mode, LAS float* scr_, int item, int lane) {
;     LAS unsigned* scr = (LAS unsigned*)scr_;
;     const int nblk = N / 64, kb = item / nblk, nb = item % nblk, k0 = 64 * kb, n0 = 64 * nb;
;     const int sc = (mode == 1) ? (((n0 >> 7) & 1) * DFF + (n0 >> 8) * 128 + (n0 & 127)) : n0;
;     const float* src = W + (size_t)k0 * N + sc + lane;
;     float va[32], vb[32];
; #pragma unroll
;     for (int kp = 0; kp < 32; ++kp) { va[kp] = src[(size_t)(2 * kp) * N]; vb[kp] = src[(size_t)(2 * kp + 1) * N]; }
; #pragma unroll
;     for (int kp = 0; kp < 32; ++kp) {
;         float a = va[kp], b = vb[kp];
;         if (gk) { a *= gk[k0 + 2 * kp]; b *= gk[k0 + 2 * kp + 1]; }
; __device__ __forceinline__ void prep(const Params& p, LAS unsigned char* L, int wv, int vb, int nvb, int l, int mask) {
;     ...
;     PREP_CONV(PM_PEG, PIN(I_WPEG) + (size_t)l * DM * DM, DM, DM, WL_PEG, PIN(I_NPE) + l * DM, 0)
.LBB0_570:
	v_mov_b32_e32 v8, 0
	v_mov_b32_e32 v10, 0
	v_add_u32_e32 v8, 0, v8
	v_add_u32_e32 v8, 0x201b0, v8
	s_nop 0
	s_waitcnt lgkmcnt(0)
	v_readlane_b32 s13, v251, 44
	v_add_u32_e32 v10, 0, v10
	v_add_u32_e32 v10, 0x201a8, v10
	s_nop 0
	v_readlane_b32 s3, v251, 45
	v_readlane_b32 s0, v251, 42
	v_readlane_b32 s1, v251, 43
	s_add_u32 s54, s0, 0x1000
	s_addc_u32 s55, s1, 0
	s_ashr_i32 s10, s52, 31
	s_lshr_b32 s10, s10, 28
	s_add_i32 s10, s52, s10
	s_ashr_i32 s11, s10, 4
	s_lshl_b32 s10, s11, 6
	s_lshl_b32 s53, s11, 10
	s_ashr_i32 s11, s10, 31
	s_sub_i32 s12, s14, s53
	s_lshl_b64 s[56:57], s[10:11], 12
	s_add_u32 s56, s13, s56
	s_addc_u32 s3, s3, s57
	s_ashr_i32 s13, s12, 31
	s_lshl_b64 s[12:13], s[12:13], 2
	s_add_u32 s12, s56, s12
	s_addc_u32 s13, s3, s13
	v_lshl_add_u64 v[10:11], s[12:13], 0, v[4:5]
	v_add_co_u32_e32 v66, vcc, s16, v10
	s_cmp_lg_u64 s[0:1], 0
	s_nop 0
	v_addc_co_u32_e32 v67, vcc, 0, v11, vcc
	v_add_co_u32_e32 v72, vcc, s17, v10
	s_cselect_b64 s[12:13], -1, 0
	s_nop 0
	v_addc_co_u32_e32 v73, vcc, 0, v11, vcc
	v_add_co_u32_e32 v74, vcc, s18, v10
	s_cmp_eq_u64 s[0:1], 0
	s_nop 0
	v_addc_co_u32_e32 v75, vcc, 0, v11, vcc
	v_add_co_u32_e32 v8, vcc, s19, v10
	s_mov_b64 s[0:1], -1
	s_nop 0
	v_addc_co_u32_e32 v9, vcc, 0, v11, vcc
	v_add_co_u32_e32 v12, vcc, s23, v10
	s_nop 1
	v_addc_co_u32_e32 v13, vcc, 0, v11, vcc
	v_add_co_u32_e32 v14, vcc, s24, v10
	s_nop 1
	v_addc_co_u32_e32 v15, vcc, 0, v11, vcc
	v_add_co_u32_e32 v16, vcc, s25, v10
	s_nop 1
	v_addc_co_u32_e32 v17, vcc, 0, v11, vcc
	global_load_dword v64, v[8:9], off offset:-4096
	global_load_dword v65, v[8:9], off
	global_load_dword v60, v[12:13], off offset:-4096
	global_load_dword v61, v[12:13], off
	global_load_dword v62, v[14:15], off offset:-4096
	global_load_dword v63, v[14:15], off
	global_load_dword v56, v[16:17], off offset:-4096
	global_load_dword v57, v[16:17], off
	v_add_co_u32_e32 v8, vcc, s26, v10
	s_nop 1
	v_addc_co_u32_e32 v9, vcc, 0, v11, vcc
	v_add_co_u32_e32 v12, vcc, s27, v10
	s_nop 1
	v_addc_co_u32_e32 v13, vcc, 0, v11, vcc
	v_add_co_u32_e32 v14, vcc, s28, v10
	s_nop 1
	v_addc_co_u32_e32 v15, vcc, 0, v11, vcc
	v_add_co_u32_e32 v16, vcc, s29, v10
	s_nop 1
	v_addc_co_u32_e32 v17, vcc, 0, v11, vcc
	global_load_dword v58, v[8:9], off offset:-4096
	global_load_dword v59, v[8:9], off
	global_load_dword v52, v[12:13], off offset:-4096
	global_load_dword v53, v[12:13], off
	global_load_dword v54, v[14:15], off offset:-4096
	global_load_dword v55, v[14:15], off
	global_load_dword v48, v[16:17], off offset:-4096
	global_load_dword v49, v[16:17], off
	v_add_co_u32_e32 v8, vcc, s30, v10
	s_nop 1
	v_addc_co_u32_e32 v9, vcc, 0, v11, vcc
	v_add_co_u32_e32 v12, vcc, s31, v10
	s_nop 1
	v_addc_co_u32_e32 v13, vcc, 0, v11, vcc
	v_add_co_u32_e32 v14, vcc, s34, v10
	s_nop 1
	v_addc_co_u32_e32 v15, vcc, 0, v11, vcc
	v_add_co_u32_e32 v16, vcc, s35, v10
	s_nop 1
	v_addc_co_u32_e32 v17, vcc, 0, v11, vcc
	global_load_dword v50, v[8:9], off offset:-4096
	global_load_dword v51, v[8:9], off
	global_load_dword v44, v[12:13], off offset:-4096
	global_load_dword v45, v[12:13], off
	global_load_dword v46, v[14:15], off offset:-4096
	global_load_dword v47, v[14:15], off
	global_load_dword v40, v[16:17], off offset:-4096
	global_load_dword v41, v[16:17], off
	v_add_co_u32_e32 v8, vcc, s36, v10
	s_nop 1
	v_addc_co_u32_e32 v9, vcc, 0, v11, vcc
	v_add_co_u32_e32 v12, vcc, s37, v10
	s_nop 1
	v_addc_co_u32_e32 v13, vcc, 0, v11, vcc
	v_add_co_u32_e32 v14, vcc, s38, v10
	s_nop 1
	v_addc_co_u32_e32 v15, vcc, 0, v11, vcc
	v_add_co_u32_e32 v16, vcc, s39, v10
	s_nop 1
	v_addc_co_u32_e32 v17, vcc, 0, v11, vcc
	global_load_dword v42, v[8:9], off offset:-4096
	global_load_dword v43, v[8:9], off
	global_load_dword v36, v[12:13], off offset:-4096
	global_load_dword v37, v[12:13], off
	global_load_dword v38, v[14:15], off offset:-4096
	global_load_dword v39, v[14:15], off
	global_load_dword v32, v[16:17], off offset:-4096
	global_load_dword v33, v[16:17], off
	v_add_co_u32_e32 v8, vcc, s40, v10
	s_nop 1
	v_addc_co_u32_e32 v9, vcc, 0, v11, vcc
	v_add_co_u32_e32 v12, vcc, s41, v10
	s_nop 1
	v_addc_co_u32_e32 v13, vcc, 0, v11, vcc
	v_add_co_u32_e32 v14, vcc, s42, v10
	s_nop 1
	v_addc_co_u32_e32 v15, vcc, 0, v11, vcc
	v_add_co_u32_e32 v16, vcc, s43, v10
	s_nop 1
	v_addc_co_u32_e32 v17, vcc, 0, v11, vcc
	global_load_dword v34, v[8:9], off offset:-4096
	global_load_dword v35, v[8:9], off
	global_load_dword v28, v[12:13], off offset:-4096
	global_load_dword v29, v[12:13], off
	global_load_dword v30, v[14:15], off offset:-4096
	global_load_dword v31, v[14:15], off
	global_load_dword v24, v[16:17], off offset:-4096
	global_load_dword v25, v[16:17], off
	v_add_co_u32_e32 v8, vcc, s44, v10
	s_nop 1
	v_addc_co_u32_e32 v9, vcc, 0, v11, vcc
	v_add_co_u32_e32 v12, vcc, s45, v10
	s_nop 1
	v_addc_co_u32_e32 v13, vcc, 0, v11, vcc
	v_add_co_u32_e32 v14, vcc, s46, v10
	s_nop 1
	v_addc_co_u32_e32 v15, vcc, 0, v11, vcc
	v_add_co_u32_e32 v18, vcc, s47, v10
	s_nop 1
	v_addc_co_u32_e32 v19, vcc, 0, v11, vcc
	global_load_dword v26, v[8:9], off offset:-4096
	global_load_dword v27, v[8:9], off
	global_load_dword v20, v[12:13], off offset:-4096
	global_load_dword v21, v[12:13], off
	global_load_dword v22, v[14:15], off offset:-4096
	global_load_dword v23, v[14:15], off
	global_load_dword v16, v[18:19], off offset:-4096
	global_load_dword v17, v[18:19], off
	v_add_co_u32_e32 v8, vcc, s48, v10
	s_nop 1
	v_addc_co_u32_e32 v9, vcc, 0, v11, vcc
	v_add_co_u32_e32 v14, vcc, s49, v10
	s_nop 1
	v_addc_co_u32_e32 v15, vcc, 0, v11, vcc
	v_add_co_u32_e32 v68, vcc, s50, v10
	s_nop 1
	v_addc_co_u32_e32 v69, vcc, 0, v11, vcc
	v_add_co_u32_e32 v70, vcc, s51, v10
	s_nop 1
	v_addc_co_u32_e32 v71, vcc, 0, v11, vcc
	v_add_co_u32_e32 v80, vcc, 0x43e000, v10
	global_load_dword v18, v[8:9], off offset:-4096
	global_load_dword v19, v[8:9], off
	global_load_dword v12, v[14:15], off offset:-4096
	global_load_dword v13, v[14:15], off
	s_nop 0
	global_load_dword v14, v[68:69], off offset:-4096
	global_load_dword v15, v[68:69], off
	global_load_dword v8, v[70:71], off offset:-4096
	global_load_dword v9, v[70:71], off
	v_addc_co_u32_e32 v81, vcc, 0, v11, vcc
	v_add_co_u32_e32 v82, vcc, 0x43f000, v10
	s_nop 1
	v_addc_co_u32_e32 v83, vcc, 0, v11, vcc
	global_load_dword v68, v[66:67], off offset:-4096
	global_load_dword v69, v[66:67], off
	global_load_dword v70, v[72:73], off offset:-4096
	global_load_dword v71, v[72:73], off
	s_nop 0
	global_load_dword v66, v[74:75], off offset:-4096
	global_load_dword v67, v[74:75], off
	global_load_dword v10, v[80:81], off
	global_load_dword v11, v[82:83], off
	s_cbranch_scc1 .LBB0_572
	s_lshl_b64 s[0:1], s[10:11], 2
	s_add_u32 s0, s54, s0
	s_addc_u32 s1, s55, s1
	global_load_dwordx4 v[72:75], v5, s[0:1]
	s_mov_b64 s[0:1], 0
	s_waitcnt vmcnt(0)
	v_pk_mul_f32 v[72:73], v[68:69], v[72:73]
	v_pk_mul_f32 v[74:75], v[70:71], v[74:75]

; #define LAS __attribute__((address_space(3)))
; #define PIN(i) ((const float*)ldq_(L, (i)))
; #define PREP_CONV(bit, SRC, Kd, Nd, DST, GK, MODE) if (mask & (bit)) { for (int it = gw; it < ((Kd) / 64) * ((Nd) / 64); it += NGW) transpose_item((SRC), (Kd), (Nd), (bf16_t*)(wl + (DST)), (GK), (MODE), scr, it, lane); }
; __device__ __forceinline__ void transpose_item(const float* W, int K, int N, bf16_t* WT, const float* gk, int mode, LAS float* scr_, int item, int lane) {
;     LAS unsigned* scr = (LAS unsigned*)scr_;
;     const int nblk = N / 64, kb = item / nblk, nb = item % nblk, k0 = 64 * kb, n0 = 64 * nb;
;     const int sc = (mode == 1) ? (((n0 >> 7) & 1) * DFF + (n0 >> 8) * 128 + (n0 & 127)) : n0;
;     const float* src = W + (size_t)k0 * N + sc + lane;
;     float va[32], vb[32];
; #pragma unroll
;     for (int kp = 0; kp < 32; ++kp) { va[kp] = src[(size_t)(2 * kp) * N]; vb[kp] = src[(size_t)(2 * kp + 1) * N]; }
; #pragma unroll
;     for (int kp = 0; kp < 32; ++kp) {
;         float a = va[kp], b = vb[kp];
;         if (gk) { a *= gk[k0 + 2 * kp]; b *= gk[k0 + 2 * kp + 1]; }
; __device__ __forceinline__ void prep(const Params& p, LAS unsigned char* L, int wv, int vb, int nvb, int l, int mask) {
;     ...
;     PREP_CONV(PM_FFA_IN, PIN(I_WFFA_IN) + (size_t)l * DM * NFF2, DM, NFF2, WL_FFA_IN, PIN(I_NFFA) + l * DM, 1)
.LBB0_664:
	v_mov_b32_e32 v8, 0
	s_mul_hi_i32 s0, s82, 0x2e8ba2e9
	v_add_u32_e32 v8, 0, v8
	v_add_u32_e32 v8, 0x20140, v8
	s_lshr_b32 s8, s0, 31
	s_ashr_i32 s0, s0, 4
	s_nop 0
	s_add_i32 s11, s0, s8
	s_mul_i32 s0, s11, 0xffffea00
	s_mul_i32 s9, s11, 0xfffff500
	s_add_i32 s83, s16, s0
	s_bfe_i32 s0, s82, 0x10001
	s_add_i32 s9, s17, s9
	s_and_b32 s0, s0, 0xb00
	s_and_b32 s9, s9, 0xffffff80
	s_lshl_b32 s8, s11, 6
	s_add_i32 s0, s0, s9
	s_and_b32 s9, s83, 64
	s_waitcnt lgkmcnt(0)
	v_readlane_b32 s10, v251, 16
	s_or_b32 s0, s0, s9
	s_ashr_i32 s9, s8, 31
	s_mul_i32 s11, s11, 0x160000
	v_readlane_b32 s1, v251, 17
	s_mul_hi_i32 s12, s8, 0x5800
	s_add_u32 s10, s10, s11
	s_addc_u32 s11, s1, s12
	s_ashr_i32 s1, s0, 31
	s_lshl_b64 s[0:1], s[0:1], 2
	s_add_u32 s0, s10, s0
	s_addc_u32 s1, s11, s1
	v_lshl_add_u64 v[8:9], s[0:1], 0, v[4:5]
	v_add_co_u32_e32 v46, vcc, s18, v8
	v_mov_b32_e32 v10, 0
	s_nop 0
	v_addc_co_u32_e32 v47, vcc, 0, v9, vcc
	v_add_co_u32_e32 v48, vcc, s19, v8
	s_waitcnt vmcnt(12)
	s_nop 0
	v_addc_co_u32_e32 v49, vcc, 0, v9, vcc
	s_waitcnt vmcnt(11)
	v_add_co_u32_e32 v50, vcc, s22, v8
	v_add_u32_e32 v10, 0, v10
	s_waitcnt vmcnt(10)
	v_addc_co_u32_e32 v51, vcc, 0, v9, vcc
	v_add_co_u32_e32 v52, vcc, s23, v8
	v_add_u32_e32 v10, 0x20138, v10
	s_nop 0
	v_addc_co_u32_e32 v53, vcc, 0, v9, vcc
	v_add_co_u32_e32 v54, vcc, s24, v8
	s_nop 0
	s_nop 0
	v_addc_co_u32_e32 v55, vcc, 0, v9, vcc
	v_add_co_u32_e32 v56, vcc, s25, v8
	v_readlane_b32 s11, v251, 15
	v_addc_co_u32_e32 v57, vcc, 0, v9, vcc
	v_add_co_u32_e32 v58, vcc, s26, v8
	v_readlane_b32 s10, v251, 14
	s_nop 0
	v_addc_co_u32_e32 v59, vcc, 0, v9, vcc
	v_add_co_u32_e32 v60, vcc, s27, v8
	s_cmp_lg_u64 s[10:11], 0
	s_nop 0
	v_addc_co_u32_e32 v61, vcc, 0, v9, vcc
	s_waitcnt vmcnt(9)
	v_add_co_u32_e32 v66, vcc, s28, v8
	s_cselect_b64 s[12:13], -1, 0
	s_nop 0
	v_addc_co_u32_e32 v67, vcc, 0, v9, vcc
	v_add_co_u32_e32 v68, vcc, s29, v8
	s_cmp_eq_u64 s[10:11], 0
	s_nop 0
	v_addc_co_u32_e32 v69, vcc, 0, v9, vcc
	v_add_co_u32_e32 v70, vcc, s30, v8
	s_nop 1
	v_addc_co_u32_e32 v71, vcc, 0, v9, vcc
	v_add_co_u32_e32 v72, vcc, s31, v8
	s_nop 1
	v_addc_co_u32_e32 v73, vcc, 0, v9, vcc
	v_add_co_u32_e32 v74, vcc, s33, v8
	s_nop 1
	v_addc_co_u32_e32 v75, vcc, 0, v9, vcc
	v_add_co_u32_e32 v76, vcc, s34, v8
	s_nop 1
	v_addc_co_u32_e32 v77, vcc, 0, v9, vcc
	v_add_co_u32_e32 v78, vcc, s35, v8
	s_nop 1
	v_addc_co_u32_e32 v79, vcc, 0, v9, vcc
	v_add_co_u32_e32 v80, vcc, s36, v8
	s_nop 1
	v_addc_co_u32_e32 v81, vcc, 0, v9, vcc
	v_add_co_u32_e32 v84, vcc, s37, v8
	s_nop 1
	v_addc_co_u32_e32 v85, vcc, 0, v9, vcc
	v_add_co_u32_e32 v82, vcc, s38, v8
	s_nop 1
	v_addc_co_u32_e32 v83, vcc, 0, v9, vcc
	v_add_co_u32_e32 v86, vcc, s39, v8
	s_nop 1
	v_addc_co_u32_e32 v87, vcc, 0, v9, vcc
	v_add_co_u32_e32 v88, vcc, s40, v8
	s_nop 1
	v_addc_co_u32_e32 v89, vcc, 0, v9, vcc
	v_add_co_u32_e32 v90, vcc, s41, v8
	s_nop 1
	v_addc_co_u32_e32 v91, vcc, 0, v9, vcc
	v_add_co_u32_e32 v92, vcc, s42, v8
	s_nop 1
	v_addc_co_u32_e32 v93, vcc, 0, v9, vcc
	v_add_co_u32_e32 v94, vcc, s43, v8
	s_nop 1
	v_addc_co_u32_e32 v95, vcc, 0, v9, vcc
	v_add_co_u32_e32 v96, vcc, s44, v8
	s_nop 1
	v_addc_co_u32_e32 v97, vcc, 0, v9, vcc
	v_add_co_u32_e32 v42, vcc, s46, v8
	s_nop 1
	v_addc_co_u32_e32 v43, vcc, 0, v9, vcc
	v_add_co_u32_e32 v44, vcc, s47, v8
	s_nop 1
	v_addc_co_u32_e32 v45, vcc, 0, v9, vcc
	v_add_co_u32_e32 v64, vcc, s48, v8
	s_nop 1
	v_addc_co_u32_e32 v65, vcc, 0, v9, vcc
	v_add_co_u32_e32 v98, vcc, s49, v8
	s_nop 1
	v_addc_co_u32_e32 v99, vcc, 0, v9, vcc
	v_add_co_u32_e32 v100, vcc, s50, v8
	s_nop 1
	v_addc_co_u32_e32 v101, vcc, 0, v9, vcc
	v_add_co_u32_e32 v108, vcc, s51, v8
	s_nop 1
	v_addc_co_u32_e32 v109, vcc, 0, v9, vcc
	v_add_co_u32_e32 v32, vcc, s54, v8
	s_nop 1
	v_addc_co_u32_e32 v33, vcc, 0, v9, vcc
	v_add_co_u32_e32 v34, vcc, s55, v8
	s_nop 1
	v_addc_co_u32_e32 v35, vcc, 0, v9, vcc
	v_add_co_u32_e32 v38, vcc, s56, v8
	s_nop 1
	v_addc_co_u32_e32 v39, vcc, 0, v9, vcc
	v_add_co_u32_e32 v62, vcc, s57, v8
	s_nop 1
	v_addc_co_u32_e32 v63, vcc, 0, v9, vcc
	v_add_co_u32_e32 v110, vcc, s58, v8
	s_nop 1
	v_addc_co_u32_e32 v111, vcc, 0, v9, vcc
	v_add_co_u32_e32 v112, vcc, s59, v8
	s_nop 1
	v_addc_co_u32_e32 v113, vcc, 0, v9, vcc
	v_add_co_u32_e32 v24, vcc, s62, v8
	s_nop 1
	v_addc_co_u32_e32 v25, vcc, 0, v9, vcc
	v_add_co_u32_e32 v26, vcc, s63, v8
	s_nop 1
	v_addc_co_u32_e32 v27, vcc, 0, v9, vcc
	v_add_co_u32_e32 v30, vcc, s64, v8
	s_nop 1
	v_addc_co_u32_e32 v31, vcc, 0, v9, vcc
	v_add_co_u32_e32 v36, vcc, s65, v8
	s_nop 1
	v_addc_co_u32_e32 v37, vcc, 0, v9, vcc
	v_add_co_u32_e32 v114, vcc, s66, v8
	s_nop 1
	v_addc_co_u32_e32 v115, vcc, 0, v9, vcc
	v_add_co_u32_e32 v116, vcc, s67, v8
	s_nop 1
	v_addc_co_u32_e32 v117, vcc, 0, v9, vcc
	v_add_co_u32_e32 v16, vcc, s70, v8
	s_nop 1
	v_addc_co_u32_e32 v17, vcc, 0, v9, vcc
	v_add_co_u32_e32 v18, vcc, s71, v8
	s_nop 1
	v_addc_co_u32_e32 v19, vcc, 0, v9, vcc
	v_add_co_u32_e32 v22, vcc, s72, v8
	s_nop 1
	v_addc_co_u32_e32 v23, vcc, 0, v9, vcc
	v_add_co_u32_e32 v28, vcc, s73, v8
	s_nop 1
	v_addc_co_u32_e32 v29, vcc, 0, v9, vcc
	v_add_co_u32_e32 v118, vcc, s74, v8
	s_nop 1
	v_addc_co_u32_e32 v119, vcc, 0, v9, vcc
	v_add_co_u32_e32 v120, vcc, s75, v8
	s_nop 1
	v_addc_co_u32_e32 v121, vcc, 0, v9, vcc
	v_add_co_u32_e32 v122, vcc, s45, v8
	s_nop 1
	v_addc_co_u32_e32 v123, vcc, 0, v9, vcc
	v_add_co_u32_e32 v124, vcc, s52, v8
	s_nop 1
	v_addc_co_u32_e32 v125, vcc, 0, v9, vcc
	v_add_co_u32_e32 v126, vcc, s53, v8
	s_nop 1
	v_addc_co_u32_e32 v127, vcc, 0, v9, vcc
	v_add_co_u32_e32 v128, vcc, s60, v8
	s_nop 1
	v_addc_co_u32_e32 v129, vcc, 0, v9, vcc
	v_add_co_u32_e32 v130, vcc, s61, v8
	s_nop 1
	v_addc_co_u32_e32 v131, vcc, 0, v9, vcc
	v_add_co_u32_e32 v132, vcc, s68, v8
	s_nop 1
	v_addc_co_u32_e32 v133, vcc, 0, v9, vcc
	v_add_co_u32_e32 v134, vcc, s69, v8
	s_nop 1
	v_addc_co_u32_e32 v135, vcc, 0, v9, vcc
	v_add_co_u32_e32 v136, vcc, s76, v8
	s_nop 1
	v_addc_co_u32_e32 v137, vcc, 0, v9, vcc
	v_add_co_u32_e32 v14, vcc, s77, v8
	s_nop 1
	v_addc_co_u32_e32 v15, vcc, 0, v9, vcc
	v_add_co_u32_e32 v10, vcc, s78, v8
	s_nop 1
	v_addc_co_u32_e32 v11, vcc, 0, v9, vcc
	v_add_co_u32_e32 v20, vcc, s79, v8
	s_nop 1
	v_addc_co_u32_e32 v21, vcc, 0, v9, vcc
	v_add_co_u32_e32 v102, vcc, s80, v8
	s_waitcnt vmcnt(8)
; __device__ __forceinline__ void transpose_item(const float* W, int K, int N, bf16_t* WT, const float* gk, int mode, LAS float* scr_, int item, int lane) {
;     ...
;     for (int kp = 0; kp < 32; ++kp) { va[kp] = src[(size_t)(2 * kp) * N]; vb[kp] = src[(size_t)(2 * kp + 1) * N]; }
; #pragma unroll
;     for (int kp = 0; kp < 32; ++kp) {
;         float a = va[kp], b = vb[kp];
;         if (gk) { a *= gk[k0 + 2 * kp]; b *= gk[k0 + 2 * kp + 1]; }
	s_nop 0
	v_addc_co_u32_e32 v103, vcc, 0, v9, vcc
	v_add_co_u32_e32 v138, vcc, s81, v8
	s_nop 1
	v_addc_co_u32_e32 v139, vcc, 0, v9, vcc
	v_add_co_u32_e32 v140, vcc, 0x155000, v8
	s_nop 1
	v_addc_co_u32_e32 v141, vcc, 0, v9, vcc
	v_add_co_u32_e32 v142, vcc, 0x15a000, v8
	s_nop 1
	v_addc_co_u32_e32 v143, vcc, 0, v9, vcc
	global_load_dword v12, v[10:11], off
	global_load_dword v13, v[20:21], off offset:2048
	global_load_dword v8, v[102:103], off
	global_load_dword v9, v[138:139], off offset:2048
	s_nop 0
	global_load_dword v10, v[140:141], off
	global_load_dword v11, v[142:143], off offset:2048
	global_load_dword v102, v4, s[0:1]
	s_nop 0
	global_load_dword v15, v[14:15], off offset:2048
	s_nop 0
	global_load_dword v20, v[16:17], off
	global_load_dword v21, v[18:19], off offset:2048
	s_nop 0
	global_load_dword v16, v[22:23], off
	global_load_dword v17, v[28:29], off offset:2048
	global_load_dword v18, v[118:119], off
	global_load_dword v19, v[120:121], off offset:2048
	global_load_dword v14, v[136:137], off
	s_nop 0
	global_load_dword v23, v[134:135], off offset:2048
	global_load_dword v28, v[24:25], off
	global_load_dword v29, v[26:27], off offset:2048
	s_nop 0
	global_load_dword v24, v[30:31], off
	global_load_dword v25, v[36:37], off offset:2048
	global_load_dword v26, v[114:115], off
	global_load_dword v27, v[116:117], off offset:2048
	global_load_dword v22, v[132:133], off
	s_nop 0
	global_load_dword v31, v[130:131], off offset:2048
	global_load_dword v36, v[32:33], off
	global_load_dword v37, v[34:35], off offset:2048
	s_nop 0
	global_load_dword v32, v[38:39], off
	global_load_dword v33, v[62:63], off offset:2048
	global_load_dword v34, v[110:111], off
	global_load_dword v35, v[112:113], off offset:2048
	global_load_dword v30, v[128:129], off
	s_nop 0
	global_load_dword v39, v[126:127], off offset:2048
	global_load_dword v62, v[42:43], off
	global_load_dword v63, v[44:45], off offset:2048
	s_nop 0
	global_load_dword v42, v[64:65], off
	global_load_dword v43, v[98:99], off offset:2048
	global_load_dword v44, v[100:101], off
	global_load_dword v45, v[108:109], off offset:2048
	global_load_dword v38, v[124:125], off
	s_nop 0
	global_load_dword v65, v[122:123], off offset:2048
	global_load_dword v98, v[82:83], off
	global_load_dword v99, v[86:87], off offset:2048
	s_nop 0
	global_load_dword v82, v[88:89], off
	global_load_dword v83, v[90:91], off offset:2048
	global_load_dword v86, v[92:93], off
	global_load_dword v87, v[94:95], off offset:2048
	global_load_dword v64, v[96:97], off
	s_nop 0
	global_load_dword v85, v[84:85], off offset:2048
	s_nop 0
	global_load_dword v88, v[68:69], off
	global_load_dword v89, v[70:71], off offset:2048
	s_nop 0
	global_load_dword v68, v[72:73], off
	global_load_dword v69, v[74:75], off offset:2048
	global_load_dword v70, v[76:77], off
	global_load_dword v71, v[78:79], off offset:2048
	global_load_dword v84, v[80:81], off
	s_nop 0
	global_load_dword v67, v[66:67], off offset:2048
	s_nop 0
	global_load_dword v72, v[48:49], off
	global_load_dword v73, v[50:51], off offset:2048
	s_nop 0
	global_load_dword v48, v[52:53], off
	global_load_dword v49, v[54:55], off offset:2048
	global_load_dword v50, v[56:57], off
	global_load_dword v51, v[58:59], off offset:2048
	global_load_dword v66, v[60:61], off
	global_load_dword v103, v[46:47], off offset:2048
	s_mov_b64 s[0:1], -1
	s_cbranch_scc1 .LBB0_666
	s_lshl_b64 s[0:1], s[8:9], 2
	s_add_u32 s0, s10, s0
	s_addc_u32 s1, s11, s1
	global_load_dwordx4 v[52:55], v5, s[0:1]
	s_mov_b64 s[0:1], 0
	s_waitcnt vmcnt(0)
	v_pk_mul_f32 v[40:41], v[102:103], v[52:53]
	v_pk_mul_f32 v[46:47], v[72:73], v[54:55]

; #define PG8_STAGE(bufoff, gbase, voff) do { _Pragma("unroll") for (int _i = 0; _i < 2; ++_i) \
;         __builtin_amdgcn_global_load_lds((const unsigned*)((const char*)(gbase) + (voff)[_i]), (PG8_LAS unsigned*)(lds + (bufoff) + ldsw + _i * 8192), 16, 0, 0); } while (0)
; #define PG8_WAIT_V(n) asm volatile("s_waitcnt vmcnt(" #n ")" ::: "memory")
; template <class Epi, class Sched, bool ALIGN_EPI = false, bool SP2 = false>
; __device__ __forceinline__ void gemm_phase(PG8_LAS unsigned char* lds, const Gemm g, const Sched& S, const Epi& E, int wv) {
;     ...
;     for (int i = 0; i < 2; ++i) { int R, C; stage_rc(tid * 16 + i * 8192, R, C); const int Rb = Epi::PERM ? ((R & ~31) + perm32(R & 31)) : R;
;         voffA[i] = (unsigned)(R * K + C) * 2u; voffB[i] = (unsigned)(Rb * K + C) * 2u; }
;     const size_t kstep = (size_t)(BK * 2);
;     const size_t hstep = (size_t)HALF * K * 2;
;     const size_t tstep = 2 * hstep;
;     const unsigned ldsw = (unsigned)wid * 1024u;
;     const int aoff = lds_byte(wr * 64 + fr, fq * 8), boff = lds_byte(wc * 32 + fr, fq * 8);
;     ...
;     Unit cur, nxt; int ui = 0;
;     if (!S.next(0, cur)) return;
;     f32x4 acc[2][2][4][2];
; #pragma unroll
;     for (int a = 0; a < 2; ++a)
; #pragma unroll
;         for (int b = 0; b < 2; ++b)
; #pragma unroll
;             for (int m = 0; m < 4; ++m)
; #pragma unroll
;                 for (int n = 0; n < 2; ++n) acc[a][b][m][n] = (f32x4){0.f, 0.f, 0.f, 0.f};
;     bf16x8 At[4][2], B0[2][2], B1[2][2];
;     const char* cA = (const char*)g.A + (size_t)cur.pm * tstep; const char* cB = (const char*)g.Bt + (size_t)cur.pn * tstep;
;     S.a_ready(cur);
;     if constexpr (SP2) {
;         PG8_STAGE(PG8_SB(0, 0), cB, voffB); PG8_STAGE(PG8_SB(0, 1), cB + hstep, voffB); PG8_STAGE(PG8_SA(0, 0), cA, voffA); PG8_STAGE(PG8_SA(0, 1), cA + hstep, voffA);
;         if (wr == 1) PG8_BAR;
;         PG8_WAIT_V(2); PG8_BAR;
;         PG8_STAGE(PG8_SB(1, 0), cB + kstep, voffB); PG8_STAGE(PG8_SA(1, 0), cA + kstep, voffA); PG8_STAGE(PG8_SB(1, 1), cB + hstep + kstep, voffB);
; __global__ void __launch_bounds__(512, 2) hymba_fwd(Params p) {
;     ...
;         { PHASE_VARS pg8::Gemm g{ly == 0 ? xb : (const bf16_t*)(ws + WS_XB2), (const bf16_t*)(wl + WL_FFA_IN), MT, NFF2, DM}; pg8::StaticOrder S; S.init(MT, NFF2, G, c); EpiSwiglu E{act, sq};
;           pg8::gemm_phase<EpiSwiglu, pg8::StaticOrder, true, true>(L, g, S, E, wv); }
.LBB0_764:
	s_mov_b64 s[4:5], 0
	s_mov_b32 s8, s12
	v_mov_b32_e32 v0, v161
	v_writelane_b32 v250, s12, 0
	v_add_u32_e32 v0, 0, v0
	v_add_u32_e32 v0, 0x201c0, v0
	s_waitcnt lgkmcnt(0)
	s_nop 0
	v_readlane_b32 s10, v250, 33
	v_mov_b32_e32 v8, v183
	v_readlane_b32 s11, v250, 34
	s_and_b64 vcc, exec, s[10:11]
	v_readlane_b32 s7, v251, 48
	v_mov_b32_e32 v0, v161
	v_readlane_b32 s6, v251, 49
	v_add_u32_e32 v0, 0, v0
	v_add_u32_e32 v0, 0x201c8, v0
	ds_read_b64 v[0:1], v0
	s_nop 0
	v_readfirstlane_b32 s10, v8
	s_cbranch_vccnz .LBB0_780
	s_waitcnt lgkmcnt(0)
	v_lshlrev_b32_e32 v0, 4, v8
	v_add_u32_e32 v1, 0x2000, v0
	v_ashrrev_i32_e32 v2, 31, v1
	v_lshrrev_b32_e32 v2, 22, v2
	v_add_u32_e32 v2, v1, v2
	v_ashrrev_i32_e32 v9, 10, v2
	v_mul_i32_i24_e32 v2, 0x400, v9
	v_sub_u32_e32 v1, v1, v2
	v_lshrrev_b32_e32 v2, 4, v1
	s_add_u32 s9, s7, s4
	v_bitop3_b32 v1, v2, v1, 32 bitop3:0x6c
	s_addc_u32 s12, s6, s5
	s_mul_i32 s5, s8, 0x2900000
	v_ashrrev_i32_e32 v2, 31, v1
	s_mul_hi_i32 s4, s8, 0x2900000
	s_add_u32 s16, s9, s5
	v_lshrrev_b32_e32 v2, 26, v2
	s_addc_u32 s29, s12, s4
	v_add_u32_e32 v2, v1, v2
	v_lshlrev_b32_e32 v3, 3, v9
	s_cmp_eq_u32 s8, 0
	s_mov_b32 s4, 0x5200000
	v_ashrrev_i32_e32 v10, 6, v2
	v_and_b32_e32 v3, -16, v3
	s_cselect_b32 s4, s4, 0x28700000
	v_add_u32_e32 v3, v10, v3
	s_add_u32 s30, s9, s4
	v_and_b32_e32 v4, 3, v10
	s_mov_b32 s4, 0x1fffe0
	v_lshrrev_b32_e32 v5, 2, v3
	v_lshlrev_b32_e32 v6, 1, v3
	v_and_b32_e32 v2, 0xc0, v2
	v_and_or_b32 v4, v3, s4, v4
	v_and_b32_e32 v5, 4, v5
	v_and_b32_e32 v6, 24, v6
	v_sub_u32_e32 v1, v1, v2
	v_or3_b32 v4, v4, v5, v6
	v_lshlrev_b32_e32 v5, 5, v9
	v_ashrrev_i16_sdwa v1, v193, sext(v1) dst_sel:DWORD dst_unused:UNUSED_PAD src0_sel:DWORD src1_sel:BYTE_0
	v_and_b32_e32 v5, 32, v5
	v_bfe_i32 v11, v1, 0, 16
	v_add_lshl_u32 v1, v5, v11, 1
	v_lshl_add_u32 v128, v4, 11, v1
	v_lshl_add_u32 v130, v3, 11, v1
	v_bfe_i32 v1, v8, 27, 1
	v_lshrrev_b32_e32 v1, 22, v1
	v_add_u32_e32 v1, v0, v1
	v_and_b32_e32 v1, 0xfffffc00, v1
	v_sub_u32_e32 v0, v0, v1
	v_lshrrev_b32_e32 v1, 4, v0
	v_ashrrev_i32_e32 v2, 31, v8
	v_bitop3_b32 v0, v1, v0, 32 bitop3:0x6c
	v_lshrrev_b32_e32 v2, 26, v2
	v_ashrrev_i32_e32 v1, 31, v0
	v_add_u32_e32 v2, v8, v2
	v_lshrrev_b32_e32 v1, 26, v1
	v_ashrrev_i32_e32 v13, 6, v2
	v_add_u32_e32 v1, v0, v1
	v_lshlrev_b32_e32 v2, 3, v13
	v_ashrrev_i32_e32 v12, 6, v1
	v_and_b32_e32 v2, -16, v2
	v_add_u32_e32 v2, v12, v2
	v_and_b32_e32 v3, 3, v12
	v_lshrrev_b32_e32 v4, 2, v2
	v_lshlrev_b32_e32 v5, 1, v2
	v_and_b32_e32 v1, 0xc0, v1
	s_addc_u32 s31, s12, 0
	s_ashr_i32 s11, s10, 6
	v_and_or_b32 v3, v2, s4, v3
	v_and_b32_e32 v4, 4, v4
	v_and_b32_e32 v5, 24, v5
	v_sub_u32_e32 v0, v0, v1
	s_ashr_i32 s13, s10, 8
	s_lshl_b32 s50, s11, 10
	v_or3_b32 v3, v3, v4, v5
	v_lshlrev_b32_e32 v4, 5, v13
	v_ashrrev_i16_sdwa v0, v193, sext(v0) dst_sel:DWORD dst_unused:UNUSED_PAD src0_sel:DWORD src1_sel:BYTE_0
	v_readlane_b32 s4, v250, 5
	v_and_b32_e32 v4, 32, v4
	v_bfe_i32 v14, v0, 0, 16
	v_readlane_b32 s5, v250, 6
	s_add_u32 s44, s16, s4
	v_add_lshl_u32 v0, v4, v14, 1
	s_addc_u32 s45, s29, s5
	s_add_i32 s51, s50, 0
	v_lshl_add_u32 v160, v3, 11, v0
	s_add_i32 m0, s51, 0x10000
	v_lshl_add_u32 v132, v2, 11, v0
	global_load_lds_dwordx4 v160, s[44:45]
	s_add_i32 m0, s51, 0x12000
	s_add_u32 s4, s44, 0x40000
	global_load_lds_dwordx4 v128, s[44:45]
	s_addc_u32 s5, s45, 0
	s_add_i32 m0, s51, 0x14000
	v_mov_b32_e32 v129, v161
	global_load_lds_dwordx4 v160, s[4:5]
	s_add_i32 m0, s51, 0x16000
	v_mov_b32_e32 v133, v161
	global_load_lds_dwordx4 v128, s[4:5]
	v_readlane_b32 s4, v250, 21
	v_readlane_b32 s5, v250, 22
	s_add_u32 s42, s30, s4
	s_addc_u32 s43, s31, s5
	s_add_i32 s52, s51, 0x2000
	s_mov_b32 m0, s51
	s_add_u32 s4, s42, 0x40000
	global_load_lds_dwordx4 v132, s[42:43]
	s_mov_b32 m0, s52
	s_addc_u32 s5, s43, 0
	s_add_i32 s53, s51, 0x4000
	global_load_lds_dwordx4 v130, s[42:43]
	s_mov_b32 m0, s53
	s_add_i32 s54, s51, 0x6000
	global_load_lds_dwordx4 v132, s[4:5]
	s_mov_b32 m0, s54
	v_mov_b32_e32 v131, v161
	global_load_lds_dwordx4 v130, s[4:5]
	s_cmp_eq_u32 s13, 1
	v_lshl_add_u64 v[6:7], s[44:45], 0, v[160:161]
	v_lshl_add_u64 v[4:5], s[44:45], 0, v[128:129]
	v_lshl_add_u64 v[0:1], s[42:43], 0, v[132:133]
	s_cselect_b64 s[4:5], -1, 0
	s_cmp_lg_u32 s13, 1
	v_lshl_add_u64 v[2:3], s[42:43], 0, v[130:131]
	s_cbranch_scc1 .LBB0_767
	s_barrier

; __device__ __forceinline__ unsigned xb_ld(unsigned* p)              { return __hip_atomic_load(p, __ATOMIC_RELAXED, __HIP_MEMORY_SCOPE_AGENT); }
; __device__ __forceinline__ void xcd_barrier_complete(unsigned* bar, unsigned x, unsigned& nloc, unsigned& nx) {
;     const unsigned G = gridDim.x * gridDim.y * gridDim.z;
;     unsigned sum, cnt, mine, sp = 0u;
;     for (;;) {
;         sum = 0u; cnt = 0u; mine = 0u;
; #pragma unroll
;         for (unsigned j = 0; j < 16; ++j) { const unsigned c = xb_ld(&bar[XB_XCNT(j)]); sum += c; cnt += (c > 0u) ? 1u : 0u; mine = (j == x) ? c : mine; }
;         if (sum == G) break;
; __device__ __forceinline__ void xcd_barrier(const XcdBarrier& b, bool t0) {
;     asm volatile("s_waitcnt vmcnt(0)" ::: "memory");
;     __syncthreads();
;     if (t0) {
;         unsigned* bar = b.bar;
;         __builtin_amdgcn_s_waitcnt(0);
;         unsigned nloc = b.st[0], nx = b.st[1];
;         if (nloc == 0u) { xcd_barrier_complete(bar, b.x, nloc, nx); b.st[0] = nloc; b.st[1] = nx; }
.LBB0_780:
	s_waitcnt lgkmcnt(0)
	v_mov_b32_e32 v0, v161
	v_mov_b32_e32 v2, v183
	v_add_u32_e32 v0, 0, v0
	v_add_u32_e32 v0, 0x201c0, v0
	s_nop 0
	s_getreg_b32 s8, hwreg(HW_REG_XCC_ID, 0, 4)
	s_waitcnt vmcnt(0)
	v_readlane_b32 s7, v251, 49
	v_readlane_b32 s6, v251, 48
	v_cmp_eq_u32_e32 vcc, 0, v2
	s_barrier
	s_and_saveexec_b64 s[4:5], vcc
	s_cbranch_execz .LBB0_832
	v_readlane_b32 s9, v250, 17
	s_waitcnt vmcnt(0) expcnt(0) lgkmcnt(0)
	s_and_b32 s16, s8, 15
	v_mov_b32_e32 v0, s9
	ds_read_b32 v2, v0
	v_readlane_b32 s9, v250, 18
	s_waitcnt lgkmcnt(0)
	v_cmp_ne_u32_e32 vcc, 0, v2
	v_mov_b32_e32 v0, s9
	ds_read_b32 v0, v0
	s_cbranch_vccnz .LBB0_796
	s_add_u32 s8, s6, 0x28680200
	s_addc_u32 s9, s7, 0
	s_add_u32 s10, s6, 0x28680400
	s_addc_u32 s11, s7, 0
	s_add_u32 s12, s6, 0x28680500
	s_addc_u32 s13, s7, 0
	s_add_u32 s14, s6, 0x28680600
	s_addc_u32 s15, s7, 0
	s_add_u32 s18, s6, 0x28680700
	s_addc_u32 s19, s7, 0
	s_add_u32 s34, s6, 0x28680800
	s_addc_u32 s35, s7, 0
	s_add_u32 s40, s6, 0x28680900
	s_addc_u32 s41, s7, 0
	s_add_u32 s42, s6, 0x28680a00
	s_addc_u32 s43, s7, 0
	s_add_u32 s44, s6, 0x28680b00
	s_addc_u32 s45, s7, 0
	s_add_u32 s48, s6, 0x28680c00
	s_addc_u32 s49, s7, 0
	s_add_u32 s50, s6, 0x28680d00
	s_addc_u32 s51, s7, 0
	s_add_u32 s52, s6, 0x28680e00
	s_addc_u32 s53, s7, 0
	s_add_u32 s56, s6, 0x28680f00
	s_addc_u32 s57, s7, 0
	s_add_u32 s60, s6, 0x28681000
	s_addc_u32 s61, s7, 0
	s_add_u32 s62, s6, 0x28681100
	s_addc_u32 s63, s7, 0
	s_add_u32 s64, s6, 0x28681200
	s_addc_u32 s65, s7, 0
	s_add_u32 s66, s6, 0x28681300
	s_addc_u32 s67, s7, 0
	s_mov_b32 s21, 1
	s_branch .LBB0_784

; #define PG8_BAR __builtin_amdgcn_s_barrier()
; template <class Epi, class Sched, bool ALIGN_EPI = false, bool SP2 = false>
; __device__ __forceinline__ void gemm_phase(PG8_LAS unsigned char* lds, const Gemm g, const Sched& S, const Epi& E, int wv) {
;     ...
;     const int tid = tid_, wid = __builtin_amdgcn_readfirstlane(tid >> 6), lane = tid & 63, wr = wid >> 2, wc = wid & 3, fr = lane & 15, fq = lane >> 4;
;     const int K = g.K, nt = K / BK;
;     unsigned voffA[2], voffB[2];
; #pragma unroll
;     for (int i = 0; i < 2; ++i) { int R, C; stage_rc(tid * 16 + i * 8192, R, C); const int Rb = Epi::PERM ? ((R & ~31) + perm32(R & 31)) : R;
;         voffA[i] = (unsigned)(R * K + C) * 2u; voffB[i] = (unsigned)(Rb * K + C) * 2u; }
;     const size_t kstep = (size_t)(BK * 2);
;     const size_t hstep = (size_t)HALF * K * 2;
;     const size_t tstep = 2 * hstep;
;     const unsigned ldsw = (unsigned)wid * 1024u;
;     const int aoff = lds_byte(wr * 64 + fr, fq * 8), boff = lds_byte(wc * 32 + fr, fq * 8);
;     ...
;     Unit cur, nxt; int ui = 0;
;     if (!S.next(0, cur)) return;
;     f32x4 acc[2][2][4][2];
; #pragma unroll
;     for (int a = 0; a < 2; ++a)
; #pragma unroll
;         for (int b = 0; b < 2; ++b)
; #pragma unroll
;             for (int m = 0; m < 4; ++m)
; #pragma unroll
;                 for (int n = 0; n < 2; ++n) acc[a][b][m][n] = (f32x4){0.f, 0.f, 0.f, 0.f};
;     bf16x8 At[4][2], B0[2][2], B1[2][2];
;     const char* cA = (const char*)g.A + (size_t)cur.pm * tstep; const char* cB = (const char*)g.Bt + (size_t)cur.pn * tstep;
;     S.a_ready(cur);
;     if constexpr (SP2) {
;         PG8_STAGE(PG8_SB(0, 0), cB, voffB); PG8_STAGE(PG8_SB(0, 1), cB + hstep, voffB); PG8_STAGE(PG8_SA(0, 0), cA, voffA); PG8_STAGE(PG8_SA(0, 1), cA + hstep, voffA);
;         if (wr == 1) PG8_BAR;
;         PG8_WAIT_V(2); PG8_BAR;
;         PG8_STAGE(PG8_SB(1, 0), cB + kstep, voffB); PG8_STAGE(PG8_SA(1, 0), cA + kstep, voffA); PG8_STAGE(PG8_SB(1, 1), cB + hstep + kstep, voffB);
; __global__ void __launch_bounds__(512, 2) hymba_fwd(Params p) {
;     ...
;         { PHASE_VARS pg8::Gemm g{act, (const bf16_t*)(wl + WL_FFA_OUT), MT, DM, DFF}; pg8::StaticOrder S; S.init(MT, DM, G, c);
;           EpiResid<0> E{ly == 0 ? xb : (const bf16_t*)(ws + WS_XB2), xb, nullptr, sq + MT, 0.5f, nullptr, nullptr};
;           pg8::gemm_phase<EpiResid<0>, pg8::StaticOrder, true, true>(L, g, S, E, wv); }
.LBB0_832:
	s_or_b64 exec, exec, s[4:5]
	s_mov_b64 s[4:5], 0
	v_readlane_b32 s12, v250, 0
	s_waitcnt lgkmcnt(0)
	v_mov_b32_e32 v0, v161
	s_barrier
	v_readlane_b32 s8, v250, 1
	v_add_u32_e32 v0, 0, v0
	v_add_u32_e32 v0, 0x201c0, v0
	s_nop 0
	v_readlane_b32 s9, v250, 2
	v_mov_b32_e32 v16, v183
	s_andn2_b64 vcc, exec, s[8:9]
	v_readlane_b32 s7, v251, 48
	v_mov_b32_e32 v0, v161
	v_readlane_b32 s6, v251, 49
	v_add_u32_e32 v0, 0, v0
	v_add_u32_e32 v0, 0x201c8, v0
	ds_read_b64 v[0:1], v0
	s_waitcnt lgkmcnt(0)
	v_cndmask_b32_e64 v0, 0, 1, s[8:9]
	v_cmp_ne_u32_e64 s[10:11], 1, v0
	s_nop 0
	v_readfirstlane_b32 s24, v16
	v_writelane_b32 v250, s10, 42
	s_nop 1
	v_writelane_b32 v250, s11, 43
	s_cbranch_vccnz .LBB0_868
	v_lshlrev_b32_e32 v0, 4, v16
	v_add_u32_e32 v1, 0x2000, v0
	v_ashrrev_i32_e32 v2, 31, v1
	v_lshrrev_b32_e32 v2, 22, v2
	v_add_u32_e32 v2, v1, v2
	v_ashrrev_i32_e32 v8, 10, v2
	v_mul_i32_i24_e32 v2, 0x400, v8
	v_sub_u32_e32 v1, v1, v2
	v_lshrrev_b32_e32 v2, 4, v1
	v_bitop3_b32 v1, v2, v1, 32 bitop3:0x6c
	v_ashrrev_i32_e32 v2, 31, v1
	v_lshrrev_b32_e32 v2, 26, v2
	v_add_u32_e32 v2, v1, v2
	v_lshlrev_b32_e32 v3, 3, v8
	v_ashrrev_i32_e32 v9, 6, v2
	v_and_b32_e32 v3, -16, v3
	s_add_u32 s13, s7, s4
	v_add_u32_e32 v3, v9, v3
	s_addc_u32 s18, s6, s5
	v_and_b32_e32 v4, 3, v9
	s_mov_b32 s6, 0xffffe0
	v_lshrrev_b32_e32 v5, 2, v3
	v_lshlrev_b32_e32 v6, 1, v3
	v_and_b32_e32 v2, 0xc0, v2
	v_and_or_b32 v4, v3, s6, v4
	v_and_b32_e32 v5, 4, v5
	v_and_b32_e32 v6, 24, v6
	v_sub_u32_e32 v1, v1, v2
	v_or3_b32 v4, v4, v5, v6
	v_lshlrev_b32_e32 v5, 5, v8
	v_ashrrev_i16_sdwa v1, v193, sext(v1) dst_sel:DWORD dst_unused:UNUSED_PAD src0_sel:DWORD src1_sel:BYTE_0
	v_and_b32_e32 v10, 32, v5
	v_bfe_i32 v11, v1, 0, 16
	s_movk_i32 s7, 0xb00
	v_mul_u32_u24_e32 v4, 0xb00, v4
	v_add_u32_e32 v1, v10, v11
	v_mul_lo_u32 v2, v3, s7
	v_add_lshl_u32 v152, v4, v1, 1
	v_add_lshl_u32 v154, v1, v2, 1
	v_bfe_i32 v1, v16, 27, 1
	v_lshrrev_b32_e32 v1, 22, v1
	v_add_u32_e32 v1, v0, v1
	v_and_b32_e32 v1, 0xfffffc00, v1
	v_sub_u32_e32 v0, v0, v1
	v_lshrrev_b32_e32 v1, 4, v0
	v_ashrrev_i32_e32 v2, 31, v16
	v_bitop3_b32 v0, v1, v0, 32 bitop3:0x6c
	v_lshrrev_b32_e32 v2, 26, v2
	v_ashrrev_i32_e32 v1, 31, v0
	v_add_u32_e32 v2, v16, v2
	s_add_u32 s14, s13, 0xd600000
	v_lshrrev_b32_e32 v1, 26, v1
	v_ashrrev_i32_e32 v13, 6, v2
	s_addc_u32 s15, s18, 0
	s_mul_i32 s5, s12, 0x2900000
	v_add_u32_e32 v1, v0, v1
	v_lshlrev_b32_e32 v2, 3, v13
	s_mul_hi_i32 s4, s12, 0x2900000
	s_add_u32 s19, s13, s5
	v_ashrrev_i32_e32 v12, 6, v1
	v_and_b32_e32 v2, -16, v2
	s_addc_u32 s21, s18, s4
	v_add_u32_e32 v2, v12, v2
	s_add_u32 s16, s19, 0xb00000
	v_and_b32_e32 v3, 3, v12
	v_lshrrev_b32_e32 v4, 2, v2
	v_lshlrev_b32_e32 v5, 1, v2
	v_and_b32_e32 v1, 0xc0, v1
	s_addc_u32 s29, s21, 0
	s_ashr_i32 s4, s24, 6
	v_and_or_b32 v3, v2, s6, v3
	v_and_b32_e32 v4, 4, v4
	v_and_b32_e32 v5, 24, v5
	v_sub_u32_e32 v0, v0, v1
	s_ashr_i32 s5, s24, 8
	s_lshl_b32 s30, s4, 10
	v_or3_b32 v3, v3, v4, v5
	v_lshlrev_b32_e32 v4, 5, v13
	v_ashrrev_i16_sdwa v0, v193, sext(v0) dst_sel:DWORD dst_unused:UNUSED_PAD src0_sel:DWORD src1_sel:BYTE_0
	v_readlane_b32 s6, v250, 14
	v_and_b32_e32 v14, 32, v4
	v_bfe_i32 v15, v0, 0, 16
	s_add_u32 s44, s16, s6
	v_readlane_b32 s6, v250, 12
	v_mul_u32_u24_e32 v3, 0xb00, v3
	v_add_u32_e32 v0, v14, v15
	s_addc_u32 s45, s29, s6
	s_add_i32 s31, s30, 0
	v_add_lshl_u32 v160, v3, v0, 1
	s_add_i32 m0, s31, 0x10000
	v_mul_lo_u32 v1, v2, s7
	global_load_lds_dwordx4 v160, s[44:45]
	s_add_i32 m0, s31, 0x12000
	s_add_u32 s6, s44, 0xb0000
	global_load_lds_dwordx4 v152, s[44:45]
	s_addc_u32 s7, s45, 0
	s_add_i32 m0, s31, 0x14000
	v_add_lshl_u32 v156, v0, v1, 1
	global_load_lds_dwordx4 v160, s[6:7]
	s_add_i32 m0, s31, 0x16000
	v_mov_b32_e32 v153, v161
	global_load_lds_dwordx4 v152, s[6:7]
	v_readlane_b32 s6, v250, 11
	s_add_u32 s6, s14, s6
	v_readlane_b32 s7, v250, 10
	s_addc_u32 s7, s15, s7
	s_add_i32 s52, s31, 0x2000
	s_mov_b32 m0, s31
	s_add_u32 s8, s6, 0xb0000
	s_addc_u32 s9, s7, 0
	global_load_lds_dwordx4 v156, s[6:7]
	s_mov_b32 m0, s52
	s_add_i32 s53, s31, 0x4000
	global_load_lds_dwordx4 v154, s[6:7]
	s_mov_b32 m0, s53
	s_add_i32 s54, s31, 0x6000
	global_load_lds_dwordx4 v156, s[8:9]
	s_mov_b32 m0, s54
	v_mov_b32_e32 v157, v161
	global_load_lds_dwordx4 v154, s[8:9]
	v_mov_b32_e32 v155, v161
	s_cmp_eq_u32 s5, 1
	v_lshl_add_u64 v[6:7], s[44:45], 0, v[160:161]
	v_lshl_add_u64 v[4:5], s[44:45], 0, v[152:153]
	v_lshl_add_u64 v[0:1], s[6:7], 0, v[156:157]
	s_cselect_b64 s[8:9], -1, 0
	s_cmp_lg_u32 s5, 1
	v_lshl_add_u64 v[2:3], s[6:7], 0, v[154:155]
	s_cbranch_scc1 .LBB0_835
	s_barrier

; __device__ __forceinline__ int tid_of(int wv) { return wv * 64 + (int)__builtin_amdgcn_mbcnt_hi(~0u, __builtin_amdgcn_mbcnt_lo(~0u, 0u)); }
; #define LAS __attribute__((address_space(3)))
; #define PIN(i) ((const float*)ldq_(L, (i)))
; #define PREP_CONV(bit, SRC, Kd, Nd, DST, GK, MODE) if (mask & (bit)) { for (int it = gw; it < ((Kd) / 64) * ((Nd) / 64); it += NGW) transpose_item((SRC), (Kd), (Nd), (bf16_t*)(wl + (DST)), (GK), (MODE), scr, it, lane); }
; __device__ __forceinline__ void prep(const Params& p, LAS unsigned char* L, int wv, int vb, int nvb, int l, int mask) {
;     int tid_ = tid_of(wv); asm volatile("" : "+v"(tid_));
;     const int tid = tid_, lane = tid & 63, wave = __builtin_amdgcn_readfirstlane(tid >> 6);
;     const int gw = vb * 8 + wave, NGW = nvb * 8; const int gt = vb * 512 + tid, NGT = nvb * 512;
;     LAS float* scr = (LAS float*)(L + wave * 16384);
;     unsigned char* ws = PWS; unsigned char* wl = ws + WS_W + (size_t)l * WL_STRIDE;
;     ...
;     PREP_CONV(PM_FFA_IN, PIN(I_WFFA_IN) + (size_t)l * DM * NFF2, DM, NFF2, WL_FFA_IN, PIN(I_NFFA) + l * DM, 1)
;     PREP_CONV(PM_FFA_OUT, PIN(I_WFFA_OUT) + (size_t)l * DFF * DM, DFF, DM, WL_FFA_OUT, nullptr, 0)
;     PREP_CONV(PM_WIN, PIN(I_WIN) + (size_t)l * DM * NIN, DM, NIN, WL_IN, PIN(I_NMIX) + l * DM, 0)
.LBB0_868:
	v_readlane_b32 s4, v250, 31
	v_readlane_b32 s5, v250, 32
	s_and_b64 s[4:5], s[4:5], exec
	s_cselect_b32 s6, 0, 2
	s_mov_b32 s35, s2
	s_mov_b32 s4, s20
	s_cmpk_eq_i32 s4, 0x100
	s_cselect_b64 s[4:5], -1, 0
	s_cmp_gt_i32 s35, 31
	s_cselect_b64 s[8:9], -1, 0
	s_and_b64 s[4:5], s[4:5], s[8:9]
	s_cmp_lt_i32 s6, 2
	s_cselect_b64 s[8:9], -1, 0
	s_and_b64 s[4:5], s[4:5], s[8:9]
	s_andn2_b64 vcc, exec, s[4:5]
	s_cbranch_vccnz .LBB0_1127
	v_mov_b32_e32 v75, v183
	s_waitcnt lgkmcnt(0)
	v_mov_b32_e32 v1, v161
	s_sub_i32 s40, s35, 32
	v_add_u32_e32 v1, 0, v1
	v_add_u32_e32 v1, 0x201c0, v1
	s_nop 0
	v_readfirstlane_b32 s4, v75
	s_ashr_i32 s4, s4, 6
	s_lshl_b32 s5, s40, 3
	s_add_i32 s41, s4, s5
	s_lshl_b32 s4, s4, 14
	s_add_i32 s14, s4, 0
	v_readlane_b32 s34, v251, 48
	s_ashr_i32 s7, s6, 31
	s_mul_i32 s5, s6, 0x2900000
	v_and_b32_e32 v0, 63, v75
	v_readlane_b32 s16, v251, 49
	s_mul_hi_i32 s4, s6, 0x2900000
	s_add_u32 s8, s34, s5
	s_addc_u32 s9, s16, s4
	v_and_b32_e32 v74, 7, v75
	v_lshrrev_b32_e32 v76, 3, v0
	s_cmpk_gt_i32 s41, 0x13f
	v_lshl_add_u32 v77, v0, 2, s14
	v_mul_u32_u24_e32 v1, 0x410, v74
	v_lshlrev_b32_e32 v2, 4, v74
	v_lshlrev_b32_e32 v78, 2, v76
	s_cbranch_scc1 .LBB0_936
	s_lshl_b32 s4, s6, 10
	v_mov_b32_e32 v3, v161
	s_ashr_i32 s5, s4, 31
	v_lshl_add_u64 v[4:5], s[8:9], 0, v[2:3]
	s_mov_b64 s[10:11], 0x1080000
	v_lshl_add_u64 v[4:5], v[4:5], 0, s[10:11]
	v_add3_u32 v3, s14, v1, v78
	s_lshl_b32 s15, s41, 6
	s_lshl_b64 s[10:11], s[4:5], 2
	v_lshlrev_b32_e32 v160, 2, v0
	s_mov_b32 s29, s41
	s_branch .LBB0_872

; #define LAS __attribute__((address_space(3)))
; __device__ __forceinline__ unsigned pk2(float lo, float hi) { f32x2 v = {lo, hi}; bf16x2_t b = __builtin_convertvector(v, bf16x2_t); return __builtin_bit_cast(unsigned, b); }
; __device__ __forceinline__ void transpose_item(const float* W, int K, int N, bf16_t* WT, const float* gk, int mode, LAS float* scr_, int item, int lane) {
;     LAS unsigned* scr = (LAS unsigned*)scr_;
;     const int nblk = N / 64, kb = item / nblk, nb = item % nblk, k0 = 64 * kb, n0 = 64 * nb;
;     const int sc = (mode == 1) ? (((n0 >> 7) & 1) * DFF + (n0 >> 8) * 128 + (n0 & 127)) : n0;
;     const float* src = W + (size_t)k0 * N + sc + lane;
;     float va[32], vb[32];
; #pragma unroll
;     for (int kp = 0; kp < 32; ++kp) { va[kp] = src[(size_t)(2 * kp) * N]; vb[kp] = src[(size_t)(2 * kp + 1) * N]; }
; #pragma unroll
;     for (int kp = 0; kp < 32; ++kp) {
;         float a = va[kp], b = vb[kp];
;         if (gk) { a *= gk[k0 + 2 * kp]; b *= gk[k0 + 2 * kp + 1]; }
;         scr[kp * 65 + lane] = pk2(a, b);
;     }
.LBB0_872:
	v_mov_b32_e32 v6, v161
	s_mul_i32 s12, s6, 0x500000
	v_add_u32_e32 v6, 0, v6
	v_add_u32_e32 v6, 0x20158, v6
	s_nop 0
	s_mov_b64 s[30:31], -1
	s_waitcnt lgkmcnt(0)
	v_readlane_b32 s5, v251, 22
	v_mov_b32_e32 v6, v161
	v_readlane_b32 s4, v251, 23
	v_add_u32_e32 v6, 0, v6
	v_add_u32_e32 v6, 0x20150, v6
	s_nop 0
	s_add_u32 s13, s5, s12
	s_mul_hi_i32 s5, s6, 0x500000
	s_addc_u32 s21, s4, s5
	s_mul_hi_i32 s12, s29, 0x66666667
	v_readlane_b32 s4, v251, 20
	v_readlane_b32 s5, v251, 21
	s_add_u32 s42, s4, s10
	s_addc_u32 s43, s5, s11
	s_lshr_b32 s18, s12, 31
	s_ashr_i32 s12, s12, 3
	s_add_i32 s24, s12, s18
	s_lshl_b32 s18, s24, 6
	s_mul_i32 s12, s24, 0xfffffb00
	s_add_i32 s12, s15, s12
	s_ashr_i32 s19, s18, 31
	s_mul_i32 s24, s24, 0x50000
	s_mul_hi_i32 s25, s18, 0x1400
	s_add_u32 s26, s13, s24
	s_addc_u32 s21, s21, s25
	s_ashr_i32 s13, s12, 31
	s_lshl_b64 s[24:25], s[12:13], 2
	s_add_u32 s24, s26, s24
	s_addc_u32 s25, s21, s25
	v_lshl_add_u64 v[70:71], s[24:25], 0, v[160:161]
	s_movk_i32 s13, 0x1000
	v_add_co_u32_e32 v6, vcc, s13, v70
	s_movk_i32 s13, 0x3000
	s_nop 0
	v_addc_co_u32_e32 v7, vcc, 0, v71, vcc
	global_load_dword v67, v[6:7], off offset:1024
	v_add_co_u32_e32 v6, vcc, s79, v70
	global_load_dword v66, v160, s[24:25]
	s_nop 0
	v_addc_co_u32_e32 v7, vcc, 0, v71, vcc
	global_load_dword v68, v[6:7], off offset:2048
	v_add_co_u32_e32 v6, vcc, s13, v70
	s_movk_i32 s13, 0x5000
	s_nop 0
	v_addc_co_u32_e32 v7, vcc, 0, v71, vcc
	global_load_dword v69, v[6:7], off offset:3072
	v_add_co_u32_e32 v6, vcc, s13, v70
	s_movk_i32 s13, 0x7000
	s_nop 0
	v_addc_co_u32_e32 v7, vcc, 0, v71, vcc
	global_load_dword v58, v[6:7], off
	v_add_co_u32_e32 v6, vcc, s80, v70
	s_cmp_lg_u64 s[4:5], 0
	s_nop 0
	v_addc_co_u32_e32 v7, vcc, 0, v71, vcc
	global_load_dword v59, v[6:7], off offset:1024
	v_add_co_u32_e32 v6, vcc, s13, v70
	s_mov_b32 s13, 0xb000
	s_nop 0
	v_addc_co_u32_e32 v7, vcc, 0, v71, vcc
	global_load_dword v64, v[6:7], off offset:2048
	v_add_co_u32_e32 v6, vcc, s70, v70
	s_cselect_b64 s[24:25], -1, 0
	s_nop 0
	v_addc_co_u32_e32 v7, vcc, 0, v71, vcc
	global_load_dword v65, v[6:7], off offset:3072
	v_add_co_u32_e32 v6, vcc, s71, v70
	s_cmp_eq_u64 s[4:5], 0
	s_nop 0
	v_addc_co_u32_e32 v7, vcc, 0, v71, vcc
	global_load_dword v60, v[6:7], off
	v_add_co_u32_e32 v6, vcc, s13, v70
	s_mov_b32 s13, 0xd000
	s_nop 0
	v_addc_co_u32_e32 v7, vcc, 0, v71, vcc
	global_load_dword v61, v[6:7], off offset:1024
	v_add_co_u32_e32 v6, vcc, s91, v70
	s_nop 1
	v_addc_co_u32_e32 v7, vcc, 0, v71, vcc
	global_load_dword v62, v[6:7], off offset:2048
	v_add_co_u32_e32 v6, vcc, s13, v70
	s_mov_b32 s13, 0xf000
	s_nop 0
	v_addc_co_u32_e32 v7, vcc, 0, v71, vcc
	global_load_dword v63, v[6:7], off offset:3072
	v_add_co_u32_e32 v6, vcc, s13, v70
	s_mov_b32 s13, 0x11000
	s_nop 0
	v_addc_co_u32_e32 v7, vcc, 0, v71, vcc
	global_load_dword v50, v[6:7], off
	v_add_co_u32_e32 v6, vcc, s37, v70
	s_nop 1
	v_addc_co_u32_e32 v7, vcc, 0, v71, vcc
	global_load_dword v51, v[6:7], off offset:1024
	v_add_co_u32_e32 v6, vcc, s13, v70
	s_mov_b32 s13, 0x15000
	s_nop 0
	v_addc_co_u32_e32 v7, vcc, 0, v71, vcc
	global_load_dword v56, v[6:7], off offset:2048
	v_add_co_u32_e32 v6, vcc, s94, v70
	s_nop 1
	v_addc_co_u32_e32 v7, vcc, 0, v71, vcc
	global_load_dword v57, v[6:7], off offset:3072
	v_add_co_u32_e32 v6, vcc, s46, v70
	s_nop 1
	v_addc_co_u32_e32 v7, vcc, 0, v71, vcc
	global_load_dword v52, v[6:7], off
	v_add_co_u32_e32 v6, vcc, s13, v70
	s_mov_b32 s13, 0x17000
	s_nop 0
	v_addc_co_u32_e32 v7, vcc, 0, v71, vcc
	global_load_dword v53, v[6:7], off offset:1024
	v_add_co_u32_e32 v6, vcc, s47, v70
	s_nop 1
	v_addc_co_u32_e32 v7, vcc, 0, v71, vcc
	global_load_dword v54, v[6:7], off offset:2048
	v_add_co_u32_e32 v6, vcc, s13, v70
	s_mov_b32 s13, 0x19000
	s_nop 0
	v_addc_co_u32_e32 v7, vcc, 0, v71, vcc
	global_load_dword v55, v[6:7], off offset:3072
	v_add_co_u32_e32 v6, vcc, s13, v70
	s_mov_b32 s13, 0x1b000
	s_nop 0
	v_addc_co_u32_e32 v7, vcc, 0, v71, vcc
	global_load_dword v42, v[6:7], off
	v_add_co_u32_e32 v6, vcc, s81, v70
	s_nop 1
	v_addc_co_u32_e32 v7, vcc, 0, v71, vcc
	global_load_dword v43, v[6:7], off offset:1024
	v_add_co_u32_e32 v6, vcc, s13, v70
	s_mov_b32 s13, 0x1f000
	s_nop 0
	v_addc_co_u32_e32 v7, vcc, 0, v71, vcc
	global_load_dword v48, v[6:7], off offset:2048
	v_add_co_u32_e32 v6, vcc, s83, v70
	s_nop 1
	v_addc_co_u32_e32 v7, vcc, 0, v71, vcc
	global_load_dword v49, v[6:7], off offset:3072
	v_add_co_u32_e32 v6, vcc, s27, v70
	s_nop 1
	v_addc_co_u32_e32 v7, vcc, 0, v71, vcc
	global_load_dword v44, v[6:7], off
	v_add_co_u32_e32 v6, vcc, s13, v70
	s_mov_b32 s13, 0x21000
	s_nop 0
	v_addc_co_u32_e32 v7, vcc, 0, v71, vcc
	global_load_dword v45, v[6:7], off offset:1024
	v_add_co_u32_e32 v6, vcc, s50, v70
	s_nop 1
	v_addc_co_u32_e32 v7, vcc, 0, v71, vcc
	global_load_dword v46, v[6:7], off offset:2048
	v_add_co_u32_e32 v6, vcc, s13, v70
	s_mov_b32 s13, 0x23000
	s_nop 0
	v_addc_co_u32_e32 v7, vcc, 0, v71, vcc
	global_load_dword v47, v[6:7], off offset:3072
	v_add_co_u32_e32 v6, vcc, s13, v70
	s_mov_b32 s13, 0x25000
	s_nop 0
	v_addc_co_u32_e32 v7, vcc, 0, v71, vcc
	global_load_dword v34, v[6:7], off
	v_add_co_u32_e32 v6, vcc, s0, v70
	s_nop 1
	v_addc_co_u32_e32 v7, vcc, 0, v71, vcc
; #define LAS __attribute__((address_space(3)))
; __device__ __forceinline__ unsigned pk2(float lo, float hi) { f32x2 v = {lo, hi}; bf16x2_t b = __builtin_convertvector(v, bf16x2_t); return __builtin_bit_cast(unsigned, b); }
; __device__ __forceinline__ void transpose_item(const float* W, int K, int N, bf16_t* WT, const float* gk, int mode, LAS float* scr_, int item, int lane) {
;     LAS unsigned* scr = (LAS unsigned*)scr_;
;     const int nblk = N / 64, kb = item / nblk, nb = item % nblk, k0 = 64 * kb, n0 = 64 * nb;
;     const int sc = (mode == 1) ? (((n0 >> 7) & 1) * DFF + (n0 >> 8) * 128 + (n0 & 127)) : n0;
;     const float* src = W + (size_t)k0 * N + sc + lane;
;     float va[32], vb[32];
; #pragma unroll
;     for (int kp = 0; kp < 32; ++kp) { va[kp] = src[(size_t)(2 * kp) * N]; vb[kp] = src[(size_t)(2 * kp + 1) * N]; }
; #pragma unroll
;     for (int kp = 0; kp < 32; ++kp) {
;         float a = va[kp], b = vb[kp];
;         if (gk) { a *= gk[k0 + 2 * kp]; b *= gk[k0 + 2 * kp + 1]; }
;         scr[kp * 65 + lane] = pk2(a, b);
;     }
	global_load_dword v35, v[6:7], off offset:1024
	v_add_co_u32_e32 v6, vcc, s13, v70
	s_mov_b32 s13, 0x29000
	s_nop 0
	v_addc_co_u32_e32 v7, vcc, 0, v71, vcc
	global_load_dword v40, v[6:7], off offset:2048
	v_add_co_u32_e32 v6, vcc, s73, v70
	s_nop 1
	v_addc_co_u32_e32 v7, vcc, 0, v71, vcc
	global_load_dword v41, v[6:7], off offset:3072
	v_add_co_u32_e32 v6, vcc, s1, v70
	s_nop 1
	v_addc_co_u32_e32 v7, vcc, 0, v71, vcc
	global_load_dword v36, v[6:7], off
	v_add_co_u32_e32 v6, vcc, s13, v70
	s_mov_b32 s13, 0x2b000
	s_nop 0
	v_addc_co_u32_e32 v7, vcc, 0, v71, vcc
	global_load_dword v37, v[6:7], off offset:1024
	v_add_co_u32_e32 v6, vcc, s72, v70
	s_nop 1
	v_addc_co_u32_e32 v7, vcc, 0, v71, vcc
	global_load_dword v38, v[6:7], off offset:2048
	v_add_co_u32_e32 v6, vcc, s13, v70
	s_mov_b32 s13, 0x2d000
	s_nop 0
	v_addc_co_u32_e32 v7, vcc, 0, v71, vcc
	global_load_dword v39, v[6:7], off offset:3072
	v_add_co_u32_e32 v6, vcc, s13, v70
	s_mov_b32 s13, 0x2f000
	s_nop 0
	v_addc_co_u32_e32 v7, vcc, 0, v71, vcc
	global_load_dword v26, v[6:7], off
	v_add_co_u32_e32 v6, vcc, s33, v70
	s_nop 1
	v_addc_co_u32_e32 v7, vcc, 0, v71, vcc
	global_load_dword v27, v[6:7], off offset:1024
	v_add_co_u32_e32 v6, vcc, s13, v70
	s_mov_b32 s13, 0x33000
	s_nop 0
	v_addc_co_u32_e32 v7, vcc, 0, v71, vcc
	global_load_dword v32, v[6:7], off offset:2048
	v_add_co_u32_e32 v6, vcc, s22, v70
	s_nop 1
	v_addc_co_u32_e32 v7, vcc, 0, v71, vcc
	global_load_dword v33, v[6:7], off offset:3072
	v_add_co_u32_e32 v6, vcc, s38, v70
	s_nop 1
	v_addc_co_u32_e32 v7, vcc, 0, v71, vcc
	global_load_dword v28, v[6:7], off
	v_add_co_u32_e32 v6, vcc, s13, v70
	s_mov_b32 s13, 0x35000
	s_nop 0
	v_addc_co_u32_e32 v7, vcc, 0, v71, vcc
	global_load_dword v29, v[6:7], off offset:1024
	v_add_co_u32_e32 v6, vcc, s39, v70
	s_nop 1
	v_addc_co_u32_e32 v7, vcc, 0, v71, vcc
	global_load_dword v30, v[6:7], off offset:2048
	v_add_co_u32_e32 v6, vcc, s13, v70
	s_mov_b32 s13, 0x37000
	s_nop 0
	v_addc_co_u32_e32 v7, vcc, 0, v71, vcc
	global_load_dword v31, v[6:7], off offset:3072
	v_add_co_u32_e32 v6, vcc, s13, v70
	s_mov_b32 s13, 0x39000
	s_nop 0
	v_addc_co_u32_e32 v7, vcc, 0, v71, vcc
	global_load_dword v18, v[6:7], off
	v_add_co_u32_e32 v6, vcc, s69, v70
	s_nop 1
	v_addc_co_u32_e32 v7, vcc, 0, v71, vcc
	global_load_dword v19, v[6:7], off offset:1024
	v_add_co_u32_e32 v6, vcc, s13, v70
	s_mov_b32 s13, 0x3d000
	s_nop 0
	v_addc_co_u32_e32 v7, vcc, 0, v71, vcc
	global_load_dword v24, v[6:7], off offset:2048
	v_add_co_u32_e32 v6, vcc, s87, v70
	s_nop 1
	v_addc_co_u32_e32 v7, vcc, 0, v71, vcc
	global_load_dword v25, v[6:7], off offset:3072
	v_add_co_u32_e32 v6, vcc, s90, v70
	s_nop 1
	v_addc_co_u32_e32 v7, vcc, 0, v71, vcc
	global_load_dword v20, v[6:7], off
	v_add_co_u32_e32 v6, vcc, s13, v70
	s_mov_b32 s13, 0x41000
	s_nop 0
	v_addc_co_u32_e32 v7, vcc, 0, v71, vcc
	global_load_dword v21, v[6:7], off offset:1024
	v_add_co_u32_e32 v6, vcc, s51, v70
	s_nop 1
	v_addc_co_u32_e32 v7, vcc, 0, v71, vcc
	global_load_dword v22, v[6:7], off offset:2048
	v_add_co_u32_e32 v6, vcc, s52, v70
	s_nop 1
	v_addc_co_u32_e32 v7, vcc, 0, v71, vcc
	global_load_dword v23, v[6:7], off offset:3072
	v_add_co_u32_e32 v6, vcc, s13, v70
	s_mov_b32 s13, 0x43000
	s_nop 0
	v_addc_co_u32_e32 v7, vcc, 0, v71, vcc
	global_load_dword v8, v[6:7], off
	v_add_co_u32_e32 v6, vcc, s93, v70
	s_nop 1
	v_addc_co_u32_e32 v7, vcc, 0, v71, vcc
	global_load_dword v9, v[6:7], off offset:1024
	v_add_co_u32_e32 v6, vcc, s13, v70
	s_mov_b32 s13, 0x44000
	s_nop 0
	v_addc_co_u32_e32 v7, vcc, 0, v71, vcc
	global_load_dword v14, v[6:7], off offset:2048
	v_add_co_u32_e32 v6, vcc, s13, v70
	s_mov_b32 s13, 0x46000
	s_nop 0
	v_addc_co_u32_e32 v7, vcc, 0, v71, vcc
	global_load_dword v15, v[6:7], off offset:3072
	v_add_co_u32_e32 v6, vcc, s13, v70
	s_mov_b32 s13, 0x47000
	s_nop 0
	v_addc_co_u32_e32 v7, vcc, 0, v71, vcc
	global_load_dword v10, v[6:7], off
	v_add_co_u32_e32 v6, vcc, s13, v70
	s_mov_b32 s13, 0x48000
	s_nop 0
	v_addc_co_u32_e32 v7, vcc, 0, v71, vcc
	global_load_dword v11, v[6:7], off offset:1024
	v_add_co_u32_e32 v6, vcc, s13, v70
	s_mov_b32 s13, 0x49000
	s_nop 0
	v_addc_co_u32_e32 v7, vcc, 0, v71, vcc
	global_load_dword v16, v[6:7], off offset:2048
	v_add_co_u32_e32 v6, vcc, s13, v70
	s_mov_b32 s13, 0x4b000
	s_nop 0
	v_addc_co_u32_e32 v7, vcc, 0, v71, vcc
	global_load_dword v17, v[6:7], off offset:3072
	v_add_co_u32_e32 v6, vcc, s13, v70
	s_mov_b32 s13, 0x4c000
	s_nop 0
	v_addc_co_u32_e32 v7, vcc, 0, v71, vcc
	v_add_co_u32_e32 v12, vcc, s13, v70
	global_load_dword v6, v[6:7], off
	s_nop 0
	v_addc_co_u32_e32 v13, vcc, 0, v71, vcc
	global_load_dword v7, v[12:13], off offset:1024
	v_add_co_u32_e32 v12, vcc, 0x4d000, v70
	s_nop 1
	v_addc_co_u32_e32 v13, vcc, 0, v71, vcc
	v_add_co_u32_e32 v70, vcc, 0x4e000, v70
	global_load_dword v12, v[12:13], off offset:2048
	s_nop 0
	v_addc_co_u32_e32 v71, vcc, 0, v71, vcc
	global_load_dword v13, v[70:71], off offset:3072
	s_cbranch_scc1 .LBB0_874
	s_lshl_b64 s[4:5], s[18:19], 2
	s_add_u32 s4, s42, s4
	s_addc_u32 s5, s43, s5
	global_load_dwordx4 v[70:73], v161, s[4:5]
	s_mov_b64 s[30:31], 0
	s_waitcnt vmcnt(0)
	v_pk_mul_f32 v[70:71], v[66:67], v[70:71]
	v_pk_mul_f32 v[72:73], v[68:69], v[72:73]

; #define LAS __attribute__((address_space(3)))
; __device__ __forceinline__ unsigned pk2(float lo, float hi) { f32x2 v = {lo, hi}; bf16x2_t b = __builtin_convertvector(v, bf16x2_t); return __builtin_bit_cast(unsigned, b); }
; __device__ __forceinline__ void transpose_item(const float* W, int K, int N, bf16_t* WT, const float* gk, int mode, LAS float* scr_, int item, int lane) {
;     LAS unsigned* scr = (LAS unsigned*)scr_;
;     const int nblk = N / 64, kb = item / nblk, nb = item % nblk, k0 = 64 * kb, n0 = 64 * nb;
;     const int sc = (mode == 1) ? (((n0 >> 7) & 1) * DFF + (n0 >> 8) * 128 + (n0 & 127)) : n0;
;     const float* src = W + (size_t)k0 * N + sc + lane;
;     float va[32], vb[32];
; #pragma unroll
;     for (int kp = 0; kp < 32; ++kp) { va[kp] = src[(size_t)(2 * kp) * N]; vb[kp] = src[(size_t)(2 * kp + 1) * N]; }
; #pragma unroll
;     for (int kp = 0; kp < 32; ++kp) {
;         float a = va[kp], b = vb[kp];
;         if (gk) { a *= gk[k0 + 2 * kp]; b *= gk[k0 + 2 * kp + 1]; }
;         scr[kp * 65 + lane] = pk2(a, b);
;     }
.LBB0_942:
	v_mov_b32_e32 v6, v161
	s_mul_i32 s18, s6, 0x1600000
	v_add_u32_e32 v6, 0, v6
	v_add_u32_e32 v6, 0x20198, v6
	s_nop 0
	s_mov_b64 s[30:31], -1
	s_waitcnt lgkmcnt(0)
	v_readlane_b32 s5, v251, 38
	v_mov_b32_e32 v6, v161
	v_readlane_b32 s4, v251, 39
	v_add_u32_e32 v6, 0, v6
	v_add_u32_e32 v6, 0x20190, v6
	s_nop 0
	s_add_u32 s21, s5, s18
	s_mul_hi_i32 s5, s6, 0x1600000
	s_addc_u32 s25, s4, s5
	s_mul_hi_i32 s18, s42, 0x2e8ba2e9
	v_readlane_b32 s4, v251, 36
	v_readlane_b32 s5, v251, 37
	s_add_u32 s44, s4, s12
	s_addc_u32 s45, s5, s13
	s_lshr_b32 s19, s18, 31
	s_ashr_i32 s18, s18, 4
	s_add_i32 s26, s18, s19
	s_mul_i32 s19, s26, 0xffffea00
	s_mul_i32 s24, s26, 0xfffff500
	s_add_i32 s43, s15, s19
	s_bfe_i32 s19, s42, 0x10001
	s_add_i32 s24, s29, s24
	s_and_b32 s19, s19, 0xb00
	s_and_b32 s24, s24, 0xffffff80
	s_lshl_b32 s18, s26, 6
	s_add_i32 s19, s19, s24
	s_and_b32 s24, s43, 64
	s_or_b32 s24, s19, s24
	s_ashr_i32 s19, s18, 31
	s_mul_i32 s26, s26, 0x160000
	s_mul_hi_i32 s28, s18, 0x5800
	s_add_u32 s21, s21, s26
	s_addc_u32 s26, s25, s28
	s_ashr_i32 s25, s24, 31
	s_lshl_b64 s[24:25], s[24:25], 2
	s_add_u32 s24, s21, s24
	s_addc_u32 s25, s26, s25
	v_lshl_add_u64 v[70:71], s[24:25], 0, v[160:161]
	s_movk_i32 s21, 0x5000
	v_add_co_u32_e32 v6, vcc, s21, v70
	s_mov_b32 s21, 0xb000
	s_nop 0
	v_addc_co_u32_e32 v7, vcc, 0, v71, vcc
	global_load_dword v67, v[6:7], off offset:2048
	v_add_co_u32_e32 v6, vcc, s21, v70
	global_load_dword v66, v160, s[24:25]
	s_nop 0
	v_addc_co_u32_e32 v7, vcc, 0, v71, vcc
	global_load_dword v68, v[6:7], off
	v_add_co_u32_e32 v6, vcc, s37, v70
	s_mov_b32 s21, 0x1b000
	s_nop 0
	v_addc_co_u32_e32 v7, vcc, 0, v71, vcc
	global_load_dword v69, v[6:7], off offset:2048
	v_add_co_u32_e32 v6, vcc, s47, v70
	s_cmp_lg_u64 s[4:5], 0
	s_nop 0
	v_addc_co_u32_e32 v7, vcc, 0, v71, vcc
	global_load_dword v58, v[6:7], off
	v_add_co_u32_e32 v6, vcc, s21, v70
	s_mov_b32 s21, 0x21000
	s_nop 0
	v_addc_co_u32_e32 v7, vcc, 0, v71, vcc
	global_load_dword v59, v[6:7], off offset:2048
	v_add_co_u32_e32 v6, vcc, s21, v70
	s_mov_b32 s21, 0x31000
	s_nop 0
	v_addc_co_u32_e32 v7, vcc, 0, v71, vcc
	global_load_dword v64, v[6:7], off
	v_add_co_u32_e32 v6, vcc, s73, v70
	s_cselect_b64 s[24:25], -1, 0
	s_nop 0
	v_addc_co_u32_e32 v7, vcc, 0, v71, vcc
	global_load_dword v65, v[6:7], off offset:2048
	v_add_co_u32_e32 v6, vcc, s82, v70
	s_cmp_eq_u64 s[4:5], 0
	s_nop 0
	v_addc_co_u32_e32 v7, vcc, 0, v71, vcc
	global_load_dword v60, v[6:7], off
	v_add_co_u32_e32 v6, vcc, s21, v70
	s_mov_b32 s21, 0x37000
	s_nop 0
	v_addc_co_u32_e32 v7, vcc, 0, v71, vcc
	global_load_dword v61, v[6:7], off offset:2048
	v_add_co_u32_e32 v6, vcc, s21, v70
	s_mov_b32 s21, 0x47000
	s_nop 0
	v_addc_co_u32_e32 v7, vcc, 0, v71, vcc
	global_load_dword v62, v[6:7], off
	v_add_co_u32_e32 v6, vcc, s90, v70
	s_nop 1
	v_addc_co_u32_e32 v7, vcc, 0, v71, vcc
	global_load_dword v63, v[6:7], off offset:2048
	v_add_co_u32_e32 v6, vcc, s93, v70
	s_nop 1
	v_addc_co_u32_e32 v7, vcc, 0, v71, vcc
	global_load_dword v48, v[6:7], off
	v_add_co_u32_e32 v6, vcc, s21, v70
	s_mov_b32 s21, 0x4d000
	s_nop 0
	v_addc_co_u32_e32 v7, vcc, 0, v71, vcc
	global_load_dword v49, v[6:7], off offset:2048
	v_add_co_u32_e32 v6, vcc, s21, v70
	s_mov_b32 s21, 0x52000
	s_nop 0
	v_addc_co_u32_e32 v7, vcc, 0, v71, vcc
	global_load_dword v54, v[6:7], off
	v_add_co_u32_e32 v6, vcc, s21, v70
	s_mov_b32 s21, 0x58000
	s_nop 0
	v_addc_co_u32_e32 v7, vcc, 0, v71, vcc
	global_load_dword v55, v[6:7], off offset:2048
	v_add_co_u32_e32 v6, vcc, s21, v70
	s_mov_b32 s21, 0x5d000
	s_nop 0
	v_addc_co_u32_e32 v7, vcc, 0, v71, vcc
	global_load_dword v52, v[6:7], off
	v_add_co_u32_e32 v6, vcc, s21, v70
	s_mov_b32 s21, 0x63000
	s_nop 0
	v_addc_co_u32_e32 v7, vcc, 0, v71, vcc
	global_load_dword v53, v[6:7], off offset:2048
	v_add_co_u32_e32 v6, vcc, s21, v70
	s_mov_b32 s21, 0x68000
	s_nop 0
	v_addc_co_u32_e32 v7, vcc, 0, v71, vcc
	global_load_dword v56, v[6:7], off
	v_add_co_u32_e32 v6, vcc, s21, v70
	s_mov_b32 s21, 0x6e000
	s_nop 0
	v_addc_co_u32_e32 v7, vcc, 0, v71, vcc
	global_load_dword v57, v[6:7], off offset:2048
	v_add_co_u32_e32 v6, vcc, s21, v70
	s_mov_b32 s21, 0x73000
	s_nop 0
	v_addc_co_u32_e32 v7, vcc, 0, v71, vcc
	global_load_dword v42, v[6:7], off
	v_add_co_u32_e32 v6, vcc, s21, v70
	s_mov_b32 s21, 0x79000
	s_nop 0
	v_addc_co_u32_e32 v7, vcc, 0, v71, vcc
	global_load_dword v43, v[6:7], off offset:2048
	v_add_co_u32_e32 v6, vcc, s21, v70
	s_mov_b32 s21, 0x7e000
	s_nop 0
	v_addc_co_u32_e32 v7, vcc, 0, v71, vcc
	global_load_dword v46, v[6:7], off
	v_add_co_u32_e32 v6, vcc, s21, v70
	s_mov_b32 s21, 0x84000
	s_nop 0
	v_addc_co_u32_e32 v7, vcc, 0, v71, vcc
	global_load_dword v47, v[6:7], off offset:2048
	v_add_co_u32_e32 v6, vcc, s21, v70
	s_mov_b32 s21, 0x89000
	s_nop 0
	v_addc_co_u32_e32 v7, vcc, 0, v71, vcc
	global_load_dword v44, v[6:7], off
	v_add_co_u32_e32 v6, vcc, s21, v70
	s_mov_b32 s21, 0x8f000
	s_nop 0
	v_addc_co_u32_e32 v7, vcc, 0, v71, vcc
	global_load_dword v45, v[6:7], off offset:2048
	v_add_co_u32_e32 v6, vcc, s21, v70
	s_mov_b32 s21, 0x94000
	s_nop 0
	v_addc_co_u32_e32 v7, vcc, 0, v71, vcc
	global_load_dword v50, v[6:7], off
	v_add_co_u32_e32 v6, vcc, s21, v70
	s_mov_b32 s21, 0x9a000
	s_nop 0
	v_addc_co_u32_e32 v7, vcc, 0, v71, vcc
	global_load_dword v51, v[6:7], off offset:2048
	v_add_co_u32_e32 v6, vcc, s21, v70
	s_mov_b32 s21, 0x9f000
	s_nop 0
	v_addc_co_u32_e32 v7, vcc, 0, v71, vcc
	global_load_dword v34, v[6:7], off
	v_add_co_u32_e32 v6, vcc, s21, v70
; #define LAS __attribute__((address_space(3)))
; __device__ __forceinline__ unsigned pk2(float lo, float hi) { f32x2 v = {lo, hi}; bf16x2_t b = __builtin_convertvector(v, bf16x2_t); return __builtin_bit_cast(unsigned, b); }
; __device__ __forceinline__ void transpose_item(const float* W, int K, int N, bf16_t* WT, const float* gk, int mode, LAS float* scr_, int item, int lane) {
;     LAS unsigned* scr = (LAS unsigned*)scr_;
;     const int nblk = N / 64, kb = item / nblk, nb = item % nblk, k0 = 64 * kb, n0 = 64 * nb;
;     const int sc = (mode == 1) ? (((n0 >> 7) & 1) * DFF + (n0 >> 8) * 128 + (n0 & 127)) : n0;
;     const float* src = W + (size_t)k0 * N + sc + lane;
;     float va[32], vb[32];
; #pragma unroll
;     for (int kp = 0; kp < 32; ++kp) { va[kp] = src[(size_t)(2 * kp) * N]; vb[kp] = src[(size_t)(2 * kp + 1) * N]; }
; #pragma unroll
;     for (int kp = 0; kp < 32; ++kp) {
;         float a = va[kp], b = vb[kp];
;         if (gk) { a *= gk[k0 + 2 * kp]; b *= gk[k0 + 2 * kp + 1]; }
;         scr[kp * 65 + lane] = pk2(a, b);
;     }
	s_mov_b32 s21, 0xa5000
	s_nop 0
	v_addc_co_u32_e32 v7, vcc, 0, v71, vcc
	global_load_dword v35, v[6:7], off offset:2048
	v_add_co_u32_e32 v6, vcc, s21, v70
	s_mov_b32 s21, 0xaa000
	s_nop 0
	v_addc_co_u32_e32 v7, vcc, 0, v71, vcc
	global_load_dword v40, v[6:7], off
	v_add_co_u32_e32 v6, vcc, s21, v70
	s_mov_b32 s21, 0xb5000
	s_nop 0
	v_addc_co_u32_e32 v7, vcc, 0, v71, vcc
	global_load_dword v41, v[6:7], off offset:2048
	v_add_co_u32_e32 v6, vcc, s95, v70
	s_nop 1
	v_addc_co_u32_e32 v7, vcc, 0, v71, vcc
	global_load_dword v36, v[6:7], off
	v_add_co_u32_e32 v6, vcc, s21, v70
	s_mov_b32 s21, 0xbb000
	s_nop 0
	v_addc_co_u32_e32 v7, vcc, 0, v71, vcc
	global_load_dword v37, v[6:7], off offset:2048
	v_add_co_u32_e32 v6, vcc, s21, v70
	s_mov_b32 s21, 0xc0000
	s_nop 0
	v_addc_co_u32_e32 v7, vcc, 0, v71, vcc
	global_load_dword v38, v[6:7], off
	v_add_co_u32_e32 v6, vcc, s21, v70
	s_mov_b32 s21, 0xcb000
	s_nop 0
	v_addc_co_u32_e32 v7, vcc, 0, v71, vcc
	global_load_dword v39, v[6:7], off offset:2048
	v_add_co_u32_e32 v6, vcc, s89, v70
	s_nop 1
	v_addc_co_u32_e32 v7, vcc, 0, v71, vcc
	global_load_dword v24, v[6:7], off
	v_add_co_u32_e32 v6, vcc, s21, v70
	s_mov_b32 s21, 0xd1000
	s_nop 0
	v_addc_co_u32_e32 v7, vcc, 0, v71, vcc
	global_load_dword v25, v[6:7], off offset:2048
	v_add_co_u32_e32 v6, vcc, s21, v70
	s_mov_b32 s21, 0xd6000
	s_nop 0
	v_addc_co_u32_e32 v7, vcc, 0, v71, vcc
	global_load_dword v30, v[6:7], off
	v_add_co_u32_e32 v6, vcc, s21, v70
	s_mov_b32 s21, 0xdc000
	s_nop 0
	v_addc_co_u32_e32 v7, vcc, 0, v71, vcc
	global_load_dword v31, v[6:7], off offset:2048
	v_add_co_u32_e32 v6, vcc, s21, v70
	s_mov_b32 s21, 0xe1000
	s_nop 0
	v_addc_co_u32_e32 v7, vcc, 0, v71, vcc
	global_load_dword v28, v[6:7], off
	v_add_co_u32_e32 v6, vcc, s21, v70
	s_mov_b32 s21, 0xe7000
	s_nop 0
	v_addc_co_u32_e32 v7, vcc, 0, v71, vcc
	global_load_dword v29, v[6:7], off offset:2048
	v_add_co_u32_e32 v6, vcc, s21, v70
	s_mov_b32 s21, 0xec000
	s_nop 0
	v_addc_co_u32_e32 v7, vcc, 0, v71, vcc
	global_load_dword v32, v[6:7], off
	v_add_co_u32_e32 v6, vcc, s21, v70
	s_mov_b32 s21, 0xf2000
	s_nop 0
	v_addc_co_u32_e32 v7, vcc, 0, v71, vcc
	global_load_dword v33, v[6:7], off offset:2048
	v_add_co_u32_e32 v6, vcc, s21, v70
	s_mov_b32 s21, 0xf7000
	s_nop 0
	v_addc_co_u32_e32 v7, vcc, 0, v71, vcc
	global_load_dword v16, v[6:7], off
	v_add_co_u32_e32 v6, vcc, s21, v70
	s_mov_b32 s21, 0xfd000
	s_nop 0
	v_addc_co_u32_e32 v7, vcc, 0, v71, vcc
	global_load_dword v17, v[6:7], off offset:2048
	v_add_co_u32_e32 v6, vcc, s21, v70
	s_mov_b32 s21, 0x102000
	s_nop 0
	v_addc_co_u32_e32 v7, vcc, 0, v71, vcc
	global_load_dword v22, v[6:7], off
	v_add_co_u32_e32 v6, vcc, s21, v70
	s_mov_b32 s21, 0x108000
	s_nop 0
	v_addc_co_u32_e32 v7, vcc, 0, v71, vcc
	global_load_dword v23, v[6:7], off offset:2048
	v_add_co_u32_e32 v6, vcc, s21, v70
	s_mov_b32 s21, 0x10d000
	s_nop 0
	v_addc_co_u32_e32 v7, vcc, 0, v71, vcc
	global_load_dword v20, v[6:7], off
	v_add_co_u32_e32 v6, vcc, s21, v70
	s_mov_b32 s21, 0x113000
	s_nop 0
	v_addc_co_u32_e32 v7, vcc, 0, v71, vcc
	global_load_dword v21, v[6:7], off offset:2048
	v_add_co_u32_e32 v6, vcc, s21, v70
	s_mov_b32 s21, 0x118000
	s_nop 0
	v_addc_co_u32_e32 v7, vcc, 0, v71, vcc
	global_load_dword v26, v[6:7], off
	v_add_co_u32_e32 v6, vcc, s21, v70
	s_mov_b32 s21, 0x11e000
	s_nop 0
	v_addc_co_u32_e32 v7, vcc, 0, v71, vcc
	global_load_dword v27, v[6:7], off offset:2048
	v_add_co_u32_e32 v6, vcc, s21, v70
	s_mov_b32 s21, 0x123000
	s_nop 0
	v_addc_co_u32_e32 v7, vcc, 0, v71, vcc
	global_load_dword v8, v[6:7], off
	v_add_co_u32_e32 v6, vcc, s21, v70
	s_mov_b32 s21, 0x129000
	s_nop 0
	v_addc_co_u32_e32 v7, vcc, 0, v71, vcc
	global_load_dword v9, v[6:7], off offset:2048
	v_add_co_u32_e32 v6, vcc, s21, v70
	s_mov_b32 s21, 0x12e000
	s_nop 0
	v_addc_co_u32_e32 v7, vcc, 0, v71, vcc
	global_load_dword v14, v[6:7], off
	v_add_co_u32_e32 v6, vcc, s21, v70
	s_mov_b32 s21, 0x134000
	s_nop 0
	v_addc_co_u32_e32 v7, vcc, 0, v71, vcc
	global_load_dword v15, v[6:7], off offset:2048
	v_add_co_u32_e32 v6, vcc, s21, v70
	s_mov_b32 s21, 0x139000
	s_nop 0
	v_addc_co_u32_e32 v7, vcc, 0, v71, vcc
	global_load_dword v10, v[6:7], off
	v_add_co_u32_e32 v6, vcc, s21, v70
	s_mov_b32 s21, 0x13f000
	s_nop 0
	v_addc_co_u32_e32 v7, vcc, 0, v71, vcc
	global_load_dword v11, v[6:7], off offset:2048
	v_add_co_u32_e32 v6, vcc, s21, v70
	s_mov_b32 s21, 0x144000
	s_nop 0
	v_addc_co_u32_e32 v7, vcc, 0, v71, vcc
	global_load_dword v18, v[6:7], off
	v_add_co_u32_e32 v6, vcc, s21, v70
	s_mov_b32 s21, 0x14a000
	s_nop 0
	v_addc_co_u32_e32 v7, vcc, 0, v71, vcc
	global_load_dword v19, v[6:7], off offset:2048
	v_add_co_u32_e32 v6, vcc, s21, v70
	s_mov_b32 s21, 0x14f000
	s_nop 0
	v_addc_co_u32_e32 v7, vcc, 0, v71, vcc
	v_add_co_u32_e32 v12, vcc, s21, v70
	global_load_dword v6, v[6:7], off
	s_nop 0
	v_addc_co_u32_e32 v13, vcc, 0, v71, vcc
	global_load_dword v7, v[12:13], off offset:2048
	v_add_co_u32_e32 v12, vcc, 0x155000, v70
	s_nop 1
	v_addc_co_u32_e32 v13, vcc, 0, v71, vcc
	v_add_co_u32_e32 v70, vcc, 0x15a000, v70
	global_load_dword v12, v[12:13], off
	s_nop 0
	v_addc_co_u32_e32 v71, vcc, 0, v71, vcc
	global_load_dword v13, v[70:71], off offset:2048
	s_cbranch_scc1 .LBB0_944
	s_lshl_b64 s[4:5], s[18:19], 2
	s_add_u32 s4, s44, s4
	s_addc_u32 s5, s45, s5
	global_load_dwordx4 v[70:73], v161, s[4:5]
	s_mov_b64 s[30:31], 0
	s_waitcnt vmcnt(0)
	v_pk_mul_f32 v[70:71], v[66:67], v[70:71]
	v_pk_mul_f32 v[72:73], v[68:69], v[72:73]

; #define LAS __attribute__((address_space(3)))
; __device__ __forceinline__ unsigned pk2(float lo, float hi) { f32x2 v = {lo, hi}; bf16x2_t b = __builtin_convertvector(v, bf16x2_t); return __builtin_bit_cast(unsigned, b); }
; __device__ __forceinline__ void transpose_item(const float* W, int K, int N, bf16_t* WT, const float* gk, int mode, LAS float* scr_, int item, int lane) {
;     LAS unsigned* scr = (LAS unsigned*)scr_;
;     const int nblk = N / 64, kb = item / nblk, nb = item % nblk, k0 = 64 * kb, n0 = 64 * nb;
;     const int sc = (mode == 1) ? (((n0 >> 7) & 1) * DFF + (n0 >> 8) * 128 + (n0 & 127)) : n0;
;     const float* src = W + (size_t)k0 * N + sc + lane;
;     float va[32], vb[32];
; #pragma unroll
;     for (int kp = 0; kp < 32; ++kp) { va[kp] = src[(size_t)(2 * kp) * N]; vb[kp] = src[(size_t)(2 * kp + 1) * N]; }
; #pragma unroll
;     for (int kp = 0; kp < 32; ++kp) {
;         float a = va[kp], b = vb[kp];
;         if (gk) { a *= gk[k0 + 2 * kp]; b *= gk[k0 + 2 * kp + 1]; }
;         scr[kp * 65 + lane] = pk2(a, b);
;     }
.LBB0_1012:
	v_mov_b32_e32 v6, v161
	s_nop 0
	v_add_u32_e32 v6, 0, v6
	v_add_u32_e32 v6, 0x201b0, v6
	s_nop 0
	s_waitcnt lgkmcnt(0)
	v_readlane_b32 s5, v251, 44
	v_mov_b32_e32 v6, v161
	v_readlane_b32 s4, v251, 45
	v_add_u32_e32 v6, 0, v6
	v_add_u32_e32 v6, 0x201a8, v6
	s_nop 0
	s_add_u32 s21, s5, s10
	s_addc_u32 s25, s4, s11
	v_readlane_b32 s4, v251, 42
	v_readlane_b32 s5, v251, 43
	s_add_u32 s43, s4, s12
	s_addc_u32 s44, s5, s13
	s_ashr_i32 s18, s29, 31
	s_lshr_b32 s18, s18, 28
	s_add_i32 s18, s29, s18
	s_ashr_i32 s19, s18, 4
	s_lshl_b32 s18, s19, 6
	s_lshl_b32 s42, s19, 10
	s_ashr_i32 s19, s18, 31
	s_sub_i32 s24, s15, s42
	s_lshl_b64 s[30:31], s[18:19], 12
	s_add_u32 s21, s21, s30
	s_addc_u32 s26, s25, s31
	s_ashr_i32 s25, s24, 31
	s_lshl_b64 s[24:25], s[24:25], 2
	s_add_u32 s24, s21, s24
	s_addc_u32 s25, s26, s25
	v_lshl_add_u64 v[70:71], s[24:25], 0, v[160:161]
	v_add_co_u32_e32 v6, vcc, s79, v70
	global_load_dword v66, v160, s[24:25]
	s_nop 0
	v_addc_co_u32_e32 v7, vcc, 0, v71, vcc
	global_load_dword v67, v[6:7], off offset:-4096
	global_load_dword v68, v[6:7], off
	v_add_co_u32_e32 v6, vcc, s88, v70
	s_mov_b32 s21, 0x3d000
	s_nop 0
	v_addc_co_u32_e32 v7, vcc, 0, v71, vcc
	global_load_dword v69, v[6:7], off offset:-4096
	global_load_dword v62, v[6:7], off
	v_add_co_u32_e32 v6, vcc, s80, v70
	s_cmp_lg_u64 s[4:5], 0
	s_nop 0
	v_addc_co_u32_e32 v7, vcc, 0, v71, vcc
	global_load_dword v63, v[6:7], off offset:-4096
	global_load_dword v64, v[6:7], off
	v_add_co_u32_e32 v6, vcc, s70, v70
	s_mov_b64 s[30:31], -1
	s_nop 0
	v_addc_co_u32_e32 v7, vcc, 0, v71, vcc
	global_load_dword v65, v[6:7], off offset:-4096
	global_load_dword v58, v[6:7], off
	v_add_co_u32_e32 v6, vcc, s71, v70
	s_cselect_b64 s[24:25], -1, 0
	s_nop 0
	v_addc_co_u32_e32 v7, vcc, 0, v71, vcc
	global_load_dword v59, v[6:7], off offset:-4096
	global_load_dword v60, v[6:7], off
	v_add_co_u32_e32 v6, vcc, s91, v70
	s_cmp_eq_u64 s[4:5], 0
	s_nop 0
	v_addc_co_u32_e32 v7, vcc, 0, v71, vcc
	global_load_dword v61, v[6:7], off offset:-4096
	global_load_dword v54, v[6:7], off
	v_add_co_u32_e32 v6, vcc, s92, v70
	s_nop 1
	v_addc_co_u32_e32 v7, vcc, 0, v71, vcc
	global_load_dword v55, v[6:7], off offset:-4096
	global_load_dword v56, v[6:7], off
	v_add_co_u32_e32 v6, vcc, s37, v70
	s_nop 1
	v_addc_co_u32_e32 v7, vcc, 0, v71, vcc
	global_load_dword v57, v[6:7], off offset:-4096
	global_load_dword v50, v[6:7], off
	v_add_co_u32_e32 v6, vcc, s94, v70
	s_nop 1
	v_addc_co_u32_e32 v7, vcc, 0, v71, vcc
	global_load_dword v51, v[6:7], off offset:-4096
	global_load_dword v52, v[6:7], off
	v_add_co_u32_e32 v6, vcc, s46, v70
	s_nop 1
	v_addc_co_u32_e32 v7, vcc, 0, v71, vcc
	global_load_dword v53, v[6:7], off offset:-4096
	global_load_dword v46, v[6:7], off
	v_add_co_u32_e32 v6, vcc, s47, v70
	s_nop 1
	v_addc_co_u32_e32 v7, vcc, 0, v71, vcc
	global_load_dword v47, v[6:7], off offset:-4096
	global_load_dword v48, v[6:7], off
	v_add_co_u32_e32 v6, vcc, s59, v70
	s_nop 1
	v_addc_co_u32_e32 v7, vcc, 0, v71, vcc
	global_load_dword v49, v[6:7], off offset:-4096
	global_load_dword v42, v[6:7], off
	v_add_co_u32_e32 v6, vcc, s81, v70
	s_nop 1
	v_addc_co_u32_e32 v7, vcc, 0, v71, vcc
	global_load_dword v43, v[6:7], off offset:-4096
	global_load_dword v44, v[6:7], off
	v_add_co_u32_e32 v6, vcc, s83, v70
	s_nop 1
	v_addc_co_u32_e32 v7, vcc, 0, v71, vcc
	global_load_dword v45, v[6:7], off offset:-4096
	global_load_dword v38, v[6:7], off
	v_add_co_u32_e32 v6, vcc, s27, v70
	s_nop 1
	v_addc_co_u32_e32 v7, vcc, 0, v71, vcc
	global_load_dword v39, v[6:7], off offset:-4096
	global_load_dword v40, v[6:7], off
	v_add_co_u32_e32 v6, vcc, s50, v70
	s_nop 1
	v_addc_co_u32_e32 v7, vcc, 0, v71, vcc
	global_load_dword v41, v[6:7], off offset:-4096
	global_load_dword v34, v[6:7], off
	v_add_co_u32_e32 v6, vcc, s53, v70
	s_nop 1
	v_addc_co_u32_e32 v7, vcc, 0, v71, vcc
	global_load_dword v35, v[6:7], off offset:-4096
	global_load_dword v36, v[6:7], off
	v_add_co_u32_e32 v6, vcc, s0, v70
	s_nop 1
	v_addc_co_u32_e32 v7, vcc, 0, v71, vcc
	global_load_dword v37, v[6:7], off offset:-4096
	global_load_dword v30, v[6:7], off
	v_add_co_u32_e32 v6, vcc, s73, v70
	s_nop 1
	v_addc_co_u32_e32 v7, vcc, 0, v71, vcc
	global_load_dword v31, v[6:7], off offset:-4096
	global_load_dword v32, v[6:7], off
	v_add_co_u32_e32 v6, vcc, s1, v70
	s_nop 1
	v_addc_co_u32_e32 v7, vcc, 0, v71, vcc
	global_load_dword v33, v[6:7], off offset:-4096
	global_load_dword v26, v[6:7], off
	v_add_co_u32_e32 v6, vcc, s72, v70
	s_nop 1
	v_addc_co_u32_e32 v7, vcc, 0, v71, vcc
	global_load_dword v27, v[6:7], off offset:-4096
	global_load_dword v28, v[6:7], off
	v_add_co_u32_e32 v6, vcc, s82, v70
	s_nop 1
	v_addc_co_u32_e32 v7, vcc, 0, v71, vcc
	global_load_dword v29, v[6:7], off offset:-4096
	global_load_dword v22, v[6:7], off
	v_add_co_u32_e32 v6, vcc, s33, v70
	s_nop 1
	v_addc_co_u32_e32 v7, vcc, 0, v71, vcc
	global_load_dword v23, v[6:7], off offset:-4096
	global_load_dword v24, v[6:7], off
	v_add_co_u32_e32 v6, vcc, s22, v70
	s_nop 1
	v_addc_co_u32_e32 v7, vcc, 0, v71, vcc
	global_load_dword v25, v[6:7], off offset:-4096
	global_load_dword v18, v[6:7], off
	v_add_co_u32_e32 v6, vcc, s38, v70
	s_nop 1
	v_addc_co_u32_e32 v7, vcc, 0, v71, vcc
	global_load_dword v19, v[6:7], off offset:-4096
	global_load_dword v20, v[6:7], off
	v_add_co_u32_e32 v6, vcc, s39, v70
	s_nop 1
	v_addc_co_u32_e32 v7, vcc, 0, v71, vcc
	global_load_dword v21, v[6:7], off offset:-4096
	global_load_dword v14, v[6:7], off
	v_add_co_u32_e32 v6, vcc, s56, v70
	s_nop 1
	v_addc_co_u32_e32 v7, vcc, 0, v71, vcc
	global_load_dword v15, v[6:7], off offset:-4096
	global_load_dword v16, v[6:7], off
	v_add_co_u32_e32 v6, vcc, s69, v70
	s_nop 1
	v_addc_co_u32_e32 v7, vcc, 0, v71, vcc
	v_add_co_u32_e32 v8, vcc, s87, v70
	global_load_dword v17, v[6:7], off offset:-4096
	s_nop 0
	global_load_dword v6, v[6:7], off
	v_addc_co_u32_e32 v9, vcc, 0, v71, vcc
	global_load_dword v7, v[8:9], off offset:-4096
	global_load_dword v12, v[8:9], off
	v_add_co_u32_e32 v8, vcc, 0x3b000, v70
	s_nop 1
	v_addc_co_u32_e32 v9, vcc, 0, v71, vcc
	v_add_co_u32_e32 v10, vcc, s21, v70
	global_load_dword v13, v[8:9], off
	s_nop 0
	v_addc_co_u32_e32 v11, vcc, 0, v71, vcc
	global_load_dword v8, v[10:11], off offset:-4096
	global_load_dword v9, v[10:11], off
	v_add_co_u32_e32 v10, vcc, 0x3e000, v70
	s_nop 1
	v_addc_co_u32_e32 v11, vcc, 0, v71, vcc
	v_add_co_u32_e32 v70, vcc, 0x3f000, v70
	global_load_dword v10, v[10:11], off
	s_nop 0
	v_addc_co_u32_e32 v71, vcc, 0, v71, vcc
	global_load_dword v11, v[70:71], off
	s_cbranch_scc1 .LBB0_1014
	s_lshl_b64 s[4:5], s[18:19], 2
	s_add_u32 s4, s43, s4
	s_addc_u32 s5, s44, s5
	global_load_dwordx4 v[70:73], v161, s[4:5]
	s_mov_b64 s[30:31], 0
	s_waitcnt vmcnt(0)
	v_pk_mul_f32 v[70:71], v[66:67], v[70:71]
	v_pk_mul_f32 v[72:73], v[68:69], v[72:73]

; #define PIN(i) ((const float*)ldq_(L, (i)))
; __device__ __forceinline__ unsigned pk2(float lo, float hi) { f32x2 v = {lo, hi}; bf16x2_t b = __builtin_convertvector(v, bf16x2_t); return __builtin_bit_cast(unsigned, b); }
; __device__ __forceinline__ void prep(const Params& p, LAS unsigned char* L, int wv, int vb, int nvb, int l, int mask) {
;     ...
;     if (mask & PM_POOL) {
;         for (int t = gt; t < 4 * 128 * 16; t += NGT) {
;             const int ko = t & 15, n = (t >> 4) & 127, g = (t >> 11) & 3;
;             const float* src = PIN(I_WPOOL) + ((size_t)(l * 4 + g) * 128 + 8 * ko) * 128 + n; const float sc = PIN(I_PSCALE)[l * 512 + g * 128 + n];
;             u32x4 o; o.x = pk2(src[0] * sc, src[128] * sc); o.y = pk2(src[256] * sc, src[384] * sc); o.z = pk2(src[512] * sc, src[640] * sc); o.w = pk2(src[768] * sc, src[896] * sc);
;             *(u32x4*)((bf16_t*)(wl + WL_POOL) + ((size_t)g * 128 + n) * 128 + 8 * ko) = o;
;         }
;     }
.LBB0_1081:
	v_mov_b32_e32 v2, v161
	v_add_u32_e32 v0, 0x1c000, v0
	v_add_u32_e32 v2, 0, v2
	v_add_u32_e32 v2, 0x20178, v2
	s_nop 0
	v_bfe_u32 v12, v0, 11, 2
	v_and_b32_e32 v13, 0x78, v1
	v_bfe_u32 v9, v0, 4, 7
	v_lshlrev_b32_e32 v160, 9, v13
	s_waitcnt lgkmcnt(0)
	v_readlane_b32 s14, v251, 30
	v_or_b32_e32 v2, s12, v12
	v_readlane_b32 s15, v251, 31
	v_ashrrev_i32_e32 v3, 31, v2
	v_lshlrev_b64 v[2:3], 16, v[2:3]
	v_lshl_add_u64 v[2:3], s[14:15], 0, v[2:3]
	v_lshl_add_u64 v[2:3], v[2:3], 0, v[160:161]
	v_lshlrev_b32_e32 v160, 2, v9
	v_lshl_add_u64 v[6:7], v[2:3], 0, v[160:161]
	v_mov_b32_e32 v2, v161
	v_lshlrev_b32_e32 v4, 7, v12
	v_add_u32_e32 v2, 0, v2
	v_add_u32_e32 v2, 0x20180, v2
	s_nop 0
	v_or3_b32 v4, v4, s13, v9
	v_ashrrev_i32_e32 v5, 31, v4
	v_cmp_lt_i32_e32 vcc, s18, v0
	v_add_u32_e32 v1, 0xe0000, v1
	v_readlane_b32 s14, v251, 33
	v_readlane_b32 s15, v251, 32
	s_or_b64 s[10:11], vcc, s[10:11]
	v_mov_b32_e32 v3, s14
	v_mov_b32_e32 v2, s15
	v_lshl_add_u64 v[2:3], v[4:5], 2, v[2:3]
	global_load_dword v8, v[2:3], off
	s_nop 0
	global_load_dword v2, v[6:7], off
	global_load_dword v3, v[6:7], off offset:512
	global_load_dword v4, v[6:7], off offset:1024
	global_load_dword v5, v[6:7], off offset:1536
	s_waitcnt vmcnt(2)
	v_pk_mul_f32 v[2:3], v[8:9], v[2:3] op_sel_hi:[0,1]
	s_waitcnt vmcnt(0)
	v_pk_mul_f32 v[4:5], v[8:9], v[4:5] op_sel_hi:[0,1]
	v_cvt_pk_bf16_f32 v2, v2, v3
	v_cvt_pk_bf16_f32 v3, v4, v5
	global_load_dword v4, v[6:7], off offset:2048
	global_load_dword v5, v[6:7], off offset:2560
	global_load_dword v10, v[6:7], off offset:3072
	global_load_dword v11, v[6:7], off offset:3584
	s_waitcnt vmcnt(2)
	v_pk_mul_f32 v[4:5], v[8:9], v[4:5] op_sel_hi:[0,1]
	s_waitcnt vmcnt(0)
	v_pk_mul_f32 v[6:7], v[8:9], v[10:11] op_sel_hi:[0,1]
	v_cvt_pk_bf16_f32 v4, v4, v5
	v_cvt_pk_bf16_f32 v5, v6, v7
	v_lshlrev_b32_e32 v6, 8, v9
	v_lshl_or_b32 v160, v12, 15, v6
	v_lshl_add_u64 v[6:7], s[8:9], 0, v[160:161]
	v_lshlrev_b32_e32 v160, 1, v13
	v_lshl_add_u64 v[6:7], v[6:7], 0, v[160:161]
	global_store_dwordx4 v[6:7], v[2:5], off
	s_andn2_b64 exec, exec, s[10:11]
	s_cbranch_execnz .LBB0_1081

; __device__ __forceinline__ unsigned xb_ld(unsigned* p)              { return __hip_atomic_load(p, __ATOMIC_RELAXED, __HIP_MEMORY_SCOPE_AGENT); }
; __device__ __forceinline__ unsigned xb_add(unsigned* p, unsigned v) { return __hip_atomic_fetch_add(p, v, __ATOMIC_RELAXED, __HIP_MEMORY_SCOPE_AGENT); }
; #define XB_SPIN(cond, bar) do { unsigned _sp = 0; while (cond) { __builtin_amdgcn_s_sleep(1); \
;     if ((++_sp & 255u) == 0u) { if (xb_ld(&(bar)[XB_TMO])) break; if (_sp > XB_SPIN_CAP) { atomicAdd(&(bar)[XB_TMO], 1u); break; } } } } while (0)
; __device__ __forceinline__ void xcd_barrier(const XcdBarrier& b, bool t0) {
;     asm volatile("s_waitcnt vmcnt(0)" ::: "memory");
;     __syncthreads();
;     if (t0) {
;         unsigned* bar = b.bar;
;         __builtin_amdgcn_s_waitcnt(0);
;         unsigned nloc = b.st[0], nx = b.st[1];
;         if (nloc == 0u) { xcd_barrier_complete(bar, b.x, nloc, nx); b.st[0] = nloc; b.st[1] = nx; }
;         const unsigned old = xb_add(&bar[XB_XSUB(b.x)], 1u);
;         const unsigned gen = old / nloc;
;         if (old + 1u == (gen + 1u) * nloc) {
;             __builtin_amdgcn_fence(__ATOMIC_RELEASE, "agent");
;             asm volatile("s_waitcnt vmcnt(0)" ::: "memory");
;             const unsigned og = xb_add(&bar[XB_TOP], 1u);
;             const unsigned tg = og / nx;
;             if (og + 1u == (tg + 1u) * nx) xb_add(&bar[XB_TOPGEN], 1u);
;             else XB_SPIN(xb_ld(&bar[XB_TOPGEN]) == tg, bar);
;             __builtin_amdgcn_fence(__ATOMIC_ACQUIRE, "agent");
;             xb_add(&bar[XB_XGEN(b.x)], 1u);
;             asm volatile("s_waitcnt vmcnt(0)" ::: "memory");
;         } else {
;             XB_SPIN(xb_ld(&bar[XB_XGEN(b.x)]) == gen, bar);
;             __builtin_amdgcn_fence(__ATOMIC_ACQUIRE, "agent");
;             asm volatile("s_waitcnt vmcnt(0)" ::: "memory");
;         }
;     }
;     __syncthreads();
.LBB0_1127:
	v_mov_b32_e32 v0, v161
	v_mov_b32_e32 v2, v183
	v_add_u32_e32 v0, 0, v0
	v_add_u32_e32 v0, 0x201c0, v0
	s_waitcnt lgkmcnt(0)
	s_nop 0
	s_getreg_b32 s8, hwreg(HW_REG_XCC_ID, 0, 4)
	s_waitcnt vmcnt(0)
	v_readlane_b32 s7, v251, 49
	v_readlane_b32 s6, v251, 48
	v_cmp_eq_u32_e32 vcc, 0, v2
	s_barrier
	s_and_saveexec_b64 s[4:5], vcc
	s_cbranch_execz .LBB0_1179
	v_readlane_b32 s9, v250, 17
	s_waitcnt vmcnt(0) expcnt(0) lgkmcnt(0)
	s_and_b32 s14, s8, 15
	v_mov_b32_e32 v0, s9
	ds_read_b32 v2, v0
	v_readlane_b32 s9, v250, 18
	s_waitcnt lgkmcnt(0)
	v_cmp_ne_u32_e32 vcc, 0, v2
	v_mov_b32_e32 v0, s9
	ds_read_b32 v0, v0
	s_cbranch_vccnz .LBB0_1143
	s_add_u32 s8, s6, 0x28680200
	s_addc_u32 s9, s7, 0
	s_add_u32 s10, s6, 0x28680400
	s_addc_u32 s11, s7, 0
	s_add_u32 s12, s6, 0x28680500
	s_addc_u32 s13, s7, 0
	s_add_u32 s18, s6, 0x28680600
	s_addc_u32 s19, s7, 0
	s_add_u32 s34, s6, 0x28680700
	s_addc_u32 s35, s7, 0
	s_add_u32 s40, s6, 0x28680800
	s_addc_u32 s41, s7, 0
	s_add_u32 s42, s6, 0x28680900
	s_addc_u32 s43, s7, 0
	s_add_u32 s44, s6, 0x28680a00
	s_addc_u32 s45, s7, 0
	s_add_u32 s48, s6, 0x28680b00
	s_addc_u32 s49, s7, 0
	s_add_u32 s50, s6, 0x28680c00
	s_addc_u32 s51, s7, 0
	s_add_u32 s52, s6, 0x28680d00
	s_addc_u32 s53, s7, 0
	s_add_u32 s56, s6, 0x28680e00
	s_addc_u32 s57, s7, 0
	s_add_u32 s60, s6, 0x28680f00
	s_addc_u32 s61, s7, 0
	s_add_u32 s62, s6, 0x28681000
	s_addc_u32 s63, s7, 0
	s_add_u32 s64, s6, 0x28681100
	s_addc_u32 s65, s7, 0
	s_add_u32 s88, s6, 0x28681200
	s_addc_u32 s89, s7, 0
	s_add_u32 s66, s6, 0x28681300
	s_addc_u32 s67, s7, 0
	s_mov_b32 s15, 1
	s_branch .LBB0_1131

; #define PG8_WAIT_V(n) asm volatile("s_waitcnt vmcnt(" #n ")" ::: "memory")
; #define PG8_BAR __builtin_amdgcn_s_barrier()
; template <class Epi, class Sched, bool ALIGN_EPI = false, bool SP2 = false>
; __device__ __forceinline__ void gemm_phase(PG8_LAS unsigned char* lds, const Gemm g, const Sched& S, const Epi& E, int wv) {
;     ...
;     const int tid = tid_, wid = __builtin_amdgcn_readfirstlane(tid >> 6), lane = tid & 63, wr = wid >> 2, wc = wid & 3, fr = lane & 15, fq = lane >> 4;
;     const int K = g.K, nt = K / BK;
;     unsigned voffA[2], voffB[2];
; #pragma unroll
;     for (int i = 0; i < 2; ++i) { int R, C; stage_rc(tid * 16 + i * 8192, R, C); const int Rb = Epi::PERM ? ((R & ~31) + perm32(R & 31)) : R;
;         voffA[i] = (unsigned)(R * K + C) * 2u; voffB[i] = (unsigned)(Rb * K + C) * 2u; }
;     const size_t kstep = (size_t)(BK * 2);
;     const size_t hstep = (size_t)HALF * K * 2;
;     const size_t tstep = 2 * hstep;
;     const unsigned ldsw = (unsigned)wid * 1024u;
;     const int aoff = lds_byte(wr * 64 + fr, fq * 8), boff = lds_byte(wc * 32 + fr, fq * 8);
;     ...
;     Unit cur, nxt; int ui = 0;
;     if (!S.next(0, cur)) return;
;     f32x4 acc[2][2][4][2];
; #pragma unroll
;     for (int a = 0; a < 2; ++a)
; #pragma unroll
;         for (int b = 0; b < 2; ++b)
; #pragma unroll
;             for (int m = 0; m < 4; ++m)
; #pragma unroll
;                 for (int n = 0; n < 2; ++n) acc[a][b][m][n] = (f32x4){0.f, 0.f, 0.f, 0.f};
;     bf16x8 At[4][2], B0[2][2], B1[2][2];
;     const char* cA = (const char*)g.A + (size_t)cur.pm * tstep; const char* cB = (const char*)g.Bt + (size_t)cur.pn * tstep;
;     S.a_ready(cur);
;     if constexpr (SP2) {
;         PG8_STAGE(PG8_SB(0, 0), cB, voffB); PG8_STAGE(PG8_SB(0, 1), cB + hstep, voffB); PG8_STAGE(PG8_SA(0, 0), cA, voffA); PG8_STAGE(PG8_SA(0, 1), cA + hstep, voffA);
;         if (wr == 1) PG8_BAR;
;         PG8_WAIT_V(2); PG8_BAR;
;         PG8_STAGE(PG8_SB(1, 0), cB + kstep, voffB); PG8_STAGE(PG8_SA(1, 0), cA + kstep, voffA); PG8_STAGE(PG8_SB(1, 1), cB + hstep + kstep, voffB);
; __global__ void __launch_bounds__(512, 2) hymba_fwd(Params p) {
;     ...
;         { PHASE_VARS pg8::Gemm g{xb, (const bf16_t*)(wl + WL_IN), MT, NIN, DM}; pg8::StaticOrder S; S.init(MT, NIN, G, c); EpiStore E{zb, NIN, sq + MT};
;           pg8::gemm_phase<EpiStore, pg8::StaticOrder, true, true>(L, g, S, E, wv); }
.LBB0_1179:
	s_or_b64 exec, exec, s[4:5]
	v_readlane_b32 s8, v250, 0
	s_mov_b64 s[4:5], 0
	s_waitcnt lgkmcnt(0)
	v_mov_b32_e32 v0, v161
	s_barrier
	v_readlane_b32 s10, v250, 3
	v_add_u32_e32 v0, 0, v0
	v_add_u32_e32 v0, 0x201c0, v0
	s_nop 0
	v_mov_b32_e32 v14, v183
	v_readlane_b32 s11, v250, 4
	s_andn2_b64 vcc, exec, s[10:11]
	v_readlane_b32 s6, v251, 48
	v_mov_b32_e32 v0, v161
	v_readlane_b32 s7, v251, 49
	v_add_u32_e32 v0, 0, v0
	v_add_u32_e32 v0, 0x201c8, v0
	ds_read_b64 v[0:1], v0
	s_nop 0
	v_readfirstlane_b32 s10, v14
	s_cbranch_vccnz .LBB0_1195
	s_waitcnt lgkmcnt(0)
	v_lshlrev_b32_e32 v0, 4, v14
	v_add_u32_e32 v1, 0x2000, v0
	v_ashrrev_i32_e32 v2, 31, v1
	v_lshrrev_b32_e32 v2, 22, v2
	v_add_u32_e32 v2, v1, v2
	v_ashrrev_i32_e32 v8, 10, v2
	v_mul_i32_i24_e32 v2, 0x400, v8
	v_sub_u32_e32 v1, v1, v2
	v_lshrrev_b32_e32 v2, 4, v1
	v_bitop3_b32 v1, v2, v1, 32 bitop3:0x6c
	s_add_u32 s6, s6, s4
	v_ashrrev_i32_e32 v2, 31, v1
	s_addc_u32 s7, s7, s5
	v_lshrrev_b32_e32 v2, 26, v2
	s_add_u32 s14, s6, 0x5200000
	v_add_u32_e32 v2, v1, v2
	v_lshlrev_b32_e32 v3, 3, v8
	s_addc_u32 s15, s7, 0
	s_mul_i32 s5, s8, 0x2900000
	v_ashrrev_i32_e32 v9, 6, v2
	v_and_b32_e32 v3, -16, v3
	s_mul_hi_i32 s4, s8, 0x2900000
	s_add_u32 s9, s6, s5
	v_add_u32_e32 v3, v9, v3
	s_addc_u32 s13, s7, s4
	v_and_b32_e32 v4, 3, v9
	s_mov_b32 s4, 0x1fffe0
	v_lshrrev_b32_e32 v5, 2, v3
	v_lshlrev_b32_e32 v6, 1, v3
	v_and_b32_e32 v2, 0xc0, v2
	v_and_or_b32 v4, v3, s4, v4
	v_and_b32_e32 v5, 4, v5
	v_and_b32_e32 v6, 24, v6
	v_sub_u32_e32 v1, v1, v2
	v_or3_b32 v4, v4, v5, v6
	v_lshlrev_b32_e32 v5, 5, v8
	v_ashrrev_i16_sdwa v1, v193, sext(v1) dst_sel:DWORD dst_unused:UNUSED_PAD src0_sel:DWORD src1_sel:BYTE_0
	v_and_b32_e32 v5, 32, v5
	v_bfe_i32 v10, v1, 0, 16
	v_add_lshl_u32 v1, v5, v10, 1
	v_lshl_add_u32 v128, v4, 11, v1
	v_lshl_add_u32 v130, v3, 11, v1
	v_bfe_i32 v1, v14, 27, 1
	v_lshrrev_b32_e32 v1, 22, v1
	v_add_u32_e32 v1, v0, v1
	v_and_b32_e32 v1, 0xfffffc00, v1
	v_sub_u32_e32 v0, v0, v1
	v_lshrrev_b32_e32 v1, 4, v0
	v_ashrrev_i32_e32 v2, 31, v14
	v_bitop3_b32 v0, v1, v0, 32 bitop3:0x6c
	v_lshrrev_b32_e32 v2, 26, v2
	v_ashrrev_i32_e32 v1, 31, v0
	v_add_u32_e32 v2, v14, v2
	v_lshrrev_b32_e32 v1, 26, v1
	v_ashrrev_i32_e32 v12, 6, v2
	v_add_u32_e32 v1, v0, v1
	v_lshlrev_b32_e32 v2, 3, v12
	v_ashrrev_i32_e32 v11, 6, v1
	v_and_b32_e32 v2, -16, v2
	v_add_u32_e32 v2, v11, v2
	s_add_u32 s16, s9, 0x1080000
	v_and_b32_e32 v3, 3, v11
	v_lshrrev_b32_e32 v4, 2, v2
	v_lshlrev_b32_e32 v5, 1, v2
	v_and_b32_e32 v1, 0xc0, v1
	s_addc_u32 s29, s13, 0
	s_ashr_i32 s11, s10, 6
	v_and_or_b32 v3, v2, s4, v3
	v_and_b32_e32 v4, 4, v4
	v_and_b32_e32 v5, 24, v5
	v_sub_u32_e32 v0, v0, v1
	s_ashr_i32 s12, s10, 8
	s_lshl_b32 s30, s11, 10
	v_or3_b32 v3, v3, v4, v5
	v_lshlrev_b32_e32 v4, 5, v12
	v_ashrrev_i16_sdwa v0, v193, sext(v0) dst_sel:DWORD dst_unused:UNUSED_PAD src0_sel:DWORD src1_sel:BYTE_0
	v_readlane_b32 s4, v250, 8
	v_and_b32_e32 v4, 32, v4
	v_bfe_i32 v13, v0, 0, 16
	v_readlane_b32 s5, v250, 9
	s_add_u32 s48, s16, s4
	v_add_lshl_u32 v0, v4, v13, 1
	s_addc_u32 s49, s29, s5
	s_add_i32 s31, s30, 0
	v_lshl_add_u32 v160, v3, 11, v0
	s_add_i32 m0, s31, 0x10000
	v_lshl_add_u32 v132, v2, 11, v0
	global_load_lds_dwordx4 v160, s[48:49]
	s_add_i32 m0, s31, 0x12000
	s_add_u32 s4, s48, 0x40000
	global_load_lds_dwordx4 v128, s[48:49]
	s_addc_u32 s5, s49, 0
	s_add_i32 m0, s31, 0x14000
	v_mov_b32_e32 v129, v161
	global_load_lds_dwordx4 v160, s[4:5]
	s_add_i32 m0, s31, 0x16000
	v_mov_b32_e32 v133, v161
	global_load_lds_dwordx4 v128, s[4:5]
	v_readlane_b32 s4, v250, 25
	v_readlane_b32 s5, v250, 26
	s_add_u32 s44, s14, s4
	s_addc_u32 s45, s15, s5
	s_add_i32 s52, s31, 0x2000
	s_mov_b32 m0, s31
	s_add_u32 s4, s44, 0x40000
	global_load_lds_dwordx4 v132, s[44:45]
	s_mov_b32 m0, s52
	s_addc_u32 s5, s45, 0
	s_add_i32 s53, s31, 0x4000
	global_load_lds_dwordx4 v130, s[44:45]
	s_mov_b32 m0, s53
	s_add_i32 s54, s31, 0x6000
	global_load_lds_dwordx4 v132, s[4:5]
	s_mov_b32 m0, s54
	v_mov_b32_e32 v131, v161
	global_load_lds_dwordx4 v130, s[4:5]
	s_cmp_eq_u32 s12, 1
	v_lshl_add_u64 v[6:7], s[48:49], 0, v[160:161]
	v_lshl_add_u64 v[4:5], s[48:49], 0, v[128:129]
	v_lshl_add_u64 v[0:1], s[44:45], 0, v[132:133]
	s_cselect_b64 s[4:5], -1, 0
	s_cmp_lg_u32 s12, 1
	v_lshl_add_u64 v[2:3], s[44:45], 0, v[130:131]
	s_cbranch_scc1 .LBB0_1182
	s_barrier

; __device__ __forceinline__ int tid_of(int wv) { return wv * 64 + (int)__builtin_amdgcn_mbcnt_hi(~0u, __builtin_amdgcn_mbcnt_lo(~0u, 0u)); }
; #define LAS __attribute__((address_space(3)))
; #define PIN(i) ((const float*)ldq_(L, (i)))
; #define PREP_CONV(bit, SRC, Kd, Nd, DST, GK, MODE) if (mask & (bit)) { for (int it = gw; it < ((Kd) / 64) * ((Nd) / 64); it += NGW) transpose_item((SRC), (Kd), (Nd), (bf16_t*)(wl + (DST)), (GK), (MODE), scr, it, lane); }
; __device__ __forceinline__ void prep(const Params& p, LAS unsigned char* L, int wv, int vb, int nvb, int l, int mask) {
;     int tid_ = tid_of(wv); asm volatile("" : "+v"(tid_));
;     const int tid = tid_, lane = tid & 63, wave = __builtin_amdgcn_readfirstlane(tid >> 6);
;     const int gw = vb * 8 + wave, NGW = nvb * 8; const int gt = vb * 512 + tid, NGT = nvb * 512;
;     LAS float* scr = (LAS float*)(L + wave * 16384);
;     unsigned char* ws = PWS; unsigned char* wl = ws + WS_W + (size_t)l * WL_STRIDE;
;     ...
;     PREP_CONV(PM_FFA_IN, PIN(I_WFFA_IN) + (size_t)l * DM * NFF2, DM, NFF2, WL_FFA_IN, PIN(I_NFFA) + l * DM, 1)
.LBB0_1195:
	v_readlane_b32 s4, v250, 0
	s_add_i32 s60, s4, 1
	s_mov_b32 s4, s60
	s_mov_b32 s5, s2
	s_mov_b32 s6, s20
	s_cmpk_eq_i32 s6, 0x100
	s_cselect_b64 s[6:7], -1, 0
	s_cmp_gt_i32 s5, 39
	s_cselect_b64 s[8:9], -1, 0
	s_and_b64 s[6:7], s[6:7], s[8:9]
	s_cmp_lt_i32 s4, 2
	s_cselect_b64 s[8:9], -1, 0
	s_and_b64 s[6:7], s[6:7], s[8:9]
	s_andn2_b64 vcc, exec, s[6:7]
	s_cbranch_vccnz .LBB0_1263
	s_waitcnt lgkmcnt(0)
	v_mov_b32_e32 v0, v183
	v_mov_b32_e32 v1, v161
	s_lshl_b32 s5, s5, 3
	v_add_u32_e32 v1, 0, v1
	v_add_u32_e32 v1, 0x201c0, v1
	s_nop 0
	v_readfirstlane_b32 s6, v0
	s_ashr_i32 s6, s6, 6
	s_add_i32 s5, s5, s6
	s_add_i32 s14, s5, 0xfffffec0
	v_readlane_b32 s5, v251, 49
	s_cmpk_gt_i32 s14, 0x57f
	v_readlane_b32 s7, v251, 48
	s_cbranch_scc1 .LBB0_1263
	s_mul_i32 s8, s4, 0x2900000
	s_mul_hi_i32 s9, s4, 0x2900000
	s_add_u32 s8, s7, s8
	s_addc_u32 s9, s5, s9
	s_lshl_b32 s5, s6, 14
	s_mul_hi_i32 s15, s4, 0x1600000
	s_mul_i32 s16, s4, 0x1600000
	s_lshl_b32 s4, s4, 10
	v_and_b32_e32 v1, 7, v0
	v_bfe_u32 v71, v0, 3, 3
	s_add_i32 s6, s5, 0
	v_and_b32_e32 v2, 63, v0
	s_ashr_i32 s5, s4, 31
	v_mul_u32_u24_e32 v3, 0x410, v1
	v_lshlrev_b32_e32 v160, 4, v1
	v_lshlrev_b32_e32 v4, 2, v71
	v_lshl_add_u32 v70, v2, 2, s6
	v_lshl_add_u64 v[0:1], s[8:9], 0, v[160:161]
	v_add3_u32 v72, s6, v3, v4
	s_lshl_b32 s18, s14, 6
	s_lshl_b32 s19, s14, 5
	s_lshl_b64 s[6:7], s[4:5], 2
	v_lshlrev_b32_e32 v160, 2, v2
	s_branch .LBB0_1199

; #define LAS __attribute__((address_space(3)))
; __device__ __forceinline__ unsigned pk2(float lo, float hi) { f32x2 v = {lo, hi}; bf16x2_t b = __builtin_convertvector(v, bf16x2_t); return __builtin_bit_cast(unsigned, b); }
; __device__ __forceinline__ void transpose_item(const float* W, int K, int N, bf16_t* WT, const float* gk, int mode, LAS float* scr_, int item, int lane) {
;     LAS unsigned* scr = (LAS unsigned*)scr_;
;     const int nblk = N / 64, kb = item / nblk, nb = item % nblk, k0 = 64 * kb, n0 = 64 * nb;
;     const int sc = (mode == 1) ? (((n0 >> 7) & 1) * DFF + (n0 >> 8) * 128 + (n0 & 127)) : n0;
;     const float* src = W + (size_t)k0 * N + sc + lane;
;     float va[32], vb[32];
; #pragma unroll
;     for (int kp = 0; kp < 32; ++kp) { va[kp] = src[(size_t)(2 * kp) * N]; vb[kp] = src[(size_t)(2 * kp + 1) * N]; }
; #pragma unroll
;     for (int kp = 0; kp < 32; ++kp) {
;         float a = va[kp], b = vb[kp];
;         if (gk) { a *= gk[k0 + 2 * kp]; b *= gk[k0 + 2 * kp + 1]; }
;         scr[kp * 65 + lane] = pk2(a, b);
;     }
.LBB0_1199:
	v_mov_b32_e32 v2, v161
	s_mul_hi_i32 s8, s14, 0x2e8ba2e9
	v_add_u32_e32 v2, 0, v2
	v_add_u32_e32 v2, 0x20140, v2
	s_nop 0
	s_waitcnt lgkmcnt(0)
	v_readlane_b32 s5, v251, 16
	v_mov_b32_e32 v2, v161
	v_readlane_b32 s4, v251, 17
	v_add_u32_e32 v2, 0, v2
	v_add_u32_e32 v2, 0x20138, v2
	s_nop 0
	s_add_u32 s11, s5, s16
	s_addc_u32 s12, s4, s15
	v_readlane_b32 s4, v251, 14
	v_readlane_b32 s5, v251, 15
	s_add_u32 s25, s4, s6
	s_addc_u32 s29, s5, s7
	s_lshr_b32 s9, s8, 31
	s_ashr_i32 s8, s8, 4
	s_add_i32 s13, s8, s9
	s_mul_i32 s9, s13, 0xffffea00
	s_mul_i32 s10, s13, 0xfffff500
	s_add_i32 s24, s18, s9
	s_bfe_i32 s9, s14, 0x10001
	s_add_i32 s10, s19, s10
	s_and_b32 s9, s9, 0xb00
	s_and_b32 s10, s10, 0xffffff80
	s_lshl_b32 s8, s13, 6
	s_add_i32 s9, s9, s10
	s_and_b32 s10, s24, 64
	s_or_b32 s10, s9, s10
	s_ashr_i32 s9, s8, 31
	s_mul_i32 s13, s13, 0x160000
	s_mul_hi_i32 s21, s8, 0x5800
	s_add_u32 s13, s11, s13
	s_addc_u32 s12, s12, s21
	s_ashr_i32 s11, s10, 31
	s_lshl_b64 s[10:11], s[10:11], 2
	s_add_u32 s10, s13, s10
	s_addc_u32 s11, s12, s11
	s_waitcnt vmcnt(9)
	v_lshl_add_u64 v[66:67], s[10:11], 0, v[160:161]
	global_load_dword v62, v160, s[10:11]
	s_movk_i32 s10, 0x5000
	v_add_co_u32_e32 v2, vcc, s10, v66
	s_mov_b32 s10, 0xb000
	s_nop 0
	v_addc_co_u32_e32 v3, vcc, 0, v67, vcc
	global_load_dword v63, v[2:3], off offset:2048
	v_add_co_u32_e32 v2, vcc, s10, v66
	s_mov_b32 s10, 0x1b000
	s_nop 0
	v_addc_co_u32_e32 v3, vcc, 0, v67, vcc
	global_load_dword v64, v[2:3], off
	v_add_co_u32_e32 v2, vcc, s37, v66
	s_cmp_lg_u64 s[4:5], 0
	s_nop 0
	v_addc_co_u32_e32 v3, vcc, 0, v67, vcc
	global_load_dword v65, v[2:3], off offset:2048
	v_add_co_u32_e32 v2, vcc, s47, v66
	s_mov_b64 s[12:13], -1
	s_nop 0
	v_addc_co_u32_e32 v3, vcc, 0, v67, vcc
	global_load_dword v54, v[2:3], off
	v_add_co_u32_e32 v2, vcc, s10, v66
	s_mov_b32 s10, 0x21000
	s_nop 0
	v_addc_co_u32_e32 v3, vcc, 0, v67, vcc
	global_load_dword v55, v[2:3], off offset:2048
	v_add_co_u32_e32 v2, vcc, s10, v66
	s_mov_b32 s10, 0x31000
	s_nop 0
	v_addc_co_u32_e32 v3, vcc, 0, v67, vcc
	global_load_dword v60, v[2:3], off
	v_add_co_u32_e32 v2, vcc, s73, v66
	s_nop 1
	v_addc_co_u32_e32 v3, vcc, 0, v67, vcc
	global_load_dword v61, v[2:3], off offset:2048
	v_add_co_u32_e32 v2, vcc, s82, v66
	s_nop 1
	v_addc_co_u32_e32 v3, vcc, 0, v67, vcc
	global_load_dword v56, v[2:3], off
	v_add_co_u32_e32 v2, vcc, s10, v66
	s_mov_b32 s10, 0x37000
	s_nop 0
	v_addc_co_u32_e32 v3, vcc, 0, v67, vcc
	global_load_dword v57, v[2:3], off offset:2048
	v_add_co_u32_e32 v2, vcc, s10, v66
	s_mov_b32 s10, 0x47000
	s_nop 0
	v_addc_co_u32_e32 v3, vcc, 0, v67, vcc
	global_load_dword v58, v[2:3], off
	v_add_co_u32_e32 v2, vcc, s90, v66
	s_nop 1
	v_addc_co_u32_e32 v3, vcc, 0, v67, vcc
	global_load_dword v59, v[2:3], off offset:2048
	v_add_co_u32_e32 v2, vcc, s93, v66
	s_nop 1
	v_addc_co_u32_e32 v3, vcc, 0, v67, vcc
	global_load_dword v44, v[2:3], off
	v_add_co_u32_e32 v2, vcc, s10, v66
	s_mov_b32 s10, 0x4d000
	s_nop 0
	v_addc_co_u32_e32 v3, vcc, 0, v67, vcc
	global_load_dword v45, v[2:3], off offset:2048
	v_add_co_u32_e32 v2, vcc, s10, v66
	s_mov_b32 s10, 0x52000
	s_nop 0
	v_addc_co_u32_e32 v3, vcc, 0, v67, vcc
	global_load_dword v50, v[2:3], off
	v_add_co_u32_e32 v2, vcc, s10, v66
	s_mov_b32 s10, 0x58000
	s_nop 0
	v_addc_co_u32_e32 v3, vcc, 0, v67, vcc
	global_load_dword v51, v[2:3], off offset:2048
	v_add_co_u32_e32 v2, vcc, s10, v66
	s_mov_b32 s10, 0x5d000
	s_nop 0
	v_addc_co_u32_e32 v3, vcc, 0, v67, vcc
	global_load_dword v48, v[2:3], off
	v_add_co_u32_e32 v2, vcc, s10, v66
	s_mov_b32 s10, 0x63000
	s_nop 0
	v_addc_co_u32_e32 v3, vcc, 0, v67, vcc
	global_load_dword v49, v[2:3], off offset:2048
	v_add_co_u32_e32 v2, vcc, s10, v66
	s_mov_b32 s10, 0x68000
	s_nop 0
	v_addc_co_u32_e32 v3, vcc, 0, v67, vcc
	global_load_dword v52, v[2:3], off
	v_add_co_u32_e32 v2, vcc, s10, v66
	s_mov_b32 s10, 0x6e000
	s_nop 0
	v_addc_co_u32_e32 v3, vcc, 0, v67, vcc
	global_load_dword v53, v[2:3], off offset:2048
	v_add_co_u32_e32 v2, vcc, s10, v66
	s_mov_b32 s10, 0x73000
	s_nop 0
	v_addc_co_u32_e32 v3, vcc, 0, v67, vcc
	global_load_dword v38, v[2:3], off
	v_add_co_u32_e32 v2, vcc, s10, v66
	s_mov_b32 s10, 0x79000
	s_nop 0
	v_addc_co_u32_e32 v3, vcc, 0, v67, vcc
	global_load_dword v39, v[2:3], off offset:2048
	v_add_co_u32_e32 v2, vcc, s10, v66
	s_mov_b32 s10, 0x7e000
	s_nop 0
	v_addc_co_u32_e32 v3, vcc, 0, v67, vcc
	global_load_dword v42, v[2:3], off
	v_add_co_u32_e32 v2, vcc, s10, v66
	s_mov_b32 s10, 0x84000
	s_nop 0
	v_addc_co_u32_e32 v3, vcc, 0, v67, vcc
	global_load_dword v43, v[2:3], off offset:2048
	v_add_co_u32_e32 v2, vcc, s10, v66
	s_mov_b32 s10, 0x89000
	s_nop 0
	v_addc_co_u32_e32 v3, vcc, 0, v67, vcc
	global_load_dword v40, v[2:3], off
	v_add_co_u32_e32 v2, vcc, s10, v66
	s_mov_b32 s10, 0x8f000
	s_nop 0
	v_addc_co_u32_e32 v3, vcc, 0, v67, vcc
	global_load_dword v41, v[2:3], off offset:2048
	v_add_co_u32_e32 v2, vcc, s10, v66
	s_mov_b32 s10, 0x94000
	s_nop 0
	v_addc_co_u32_e32 v3, vcc, 0, v67, vcc
	global_load_dword v46, v[2:3], off
	v_add_co_u32_e32 v2, vcc, s10, v66
	s_mov_b32 s10, 0x9a000
	s_nop 0
	v_addc_co_u32_e32 v3, vcc, 0, v67, vcc
	global_load_dword v47, v[2:3], off offset:2048
	v_add_co_u32_e32 v2, vcc, s10, v66
	s_mov_b32 s10, 0x9f000
	s_nop 0
	v_addc_co_u32_e32 v3, vcc, 0, v67, vcc
	global_load_dword v30, v[2:3], off
	v_add_co_u32_e32 v2, vcc, s10, v66
	s_mov_b32 s10, 0xa5000
	s_nop 0
	v_addc_co_u32_e32 v3, vcc, 0, v67, vcc
; #define LAS __attribute__((address_space(3)))
; __device__ __forceinline__ unsigned pk2(float lo, float hi) { f32x2 v = {lo, hi}; bf16x2_t b = __builtin_convertvector(v, bf16x2_t); return __builtin_bit_cast(unsigned, b); }
; __device__ __forceinline__ void transpose_item(const float* W, int K, int N, bf16_t* WT, const float* gk, int mode, LAS float* scr_, int item, int lane) {
;     LAS unsigned* scr = (LAS unsigned*)scr_;
;     const int nblk = N / 64, kb = item / nblk, nb = item % nblk, k0 = 64 * kb, n0 = 64 * nb;
;     const int sc = (mode == 1) ? (((n0 >> 7) & 1) * DFF + (n0 >> 8) * 128 + (n0 & 127)) : n0;
;     const float* src = W + (size_t)k0 * N + sc + lane;
;     float va[32], vb[32];
; #pragma unroll
;     for (int kp = 0; kp < 32; ++kp) { va[kp] = src[(size_t)(2 * kp) * N]; vb[kp] = src[(size_t)(2 * kp + 1) * N]; }
; #pragma unroll
;     for (int kp = 0; kp < 32; ++kp) {
;         float a = va[kp], b = vb[kp];
;         if (gk) { a *= gk[k0 + 2 * kp]; b *= gk[k0 + 2 * kp + 1]; }
;         scr[kp * 65 + lane] = pk2(a, b);
;     }
	global_load_dword v31, v[2:3], off offset:2048
	v_add_co_u32_e32 v2, vcc, s10, v66
	s_mov_b32 s10, 0xaa000
	s_nop 0
	v_addc_co_u32_e32 v3, vcc, 0, v67, vcc
	global_load_dword v36, v[2:3], off
	v_add_co_u32_e32 v2, vcc, s10, v66
	s_mov_b32 s10, 0xb5000
	s_nop 0
	v_addc_co_u32_e32 v3, vcc, 0, v67, vcc
	global_load_dword v37, v[2:3], off offset:2048
	v_add_co_u32_e32 v2, vcc, s95, v66
	s_nop 1
	v_addc_co_u32_e32 v3, vcc, 0, v67, vcc
	global_load_dword v32, v[2:3], off
	v_add_co_u32_e32 v2, vcc, s10, v66
	s_mov_b32 s10, 0xbb000
	s_nop 0
	v_addc_co_u32_e32 v3, vcc, 0, v67, vcc
	global_load_dword v33, v[2:3], off offset:2048
	v_add_co_u32_e32 v2, vcc, s10, v66
	s_mov_b32 s10, 0xc0000
	s_nop 0
	v_addc_co_u32_e32 v3, vcc, 0, v67, vcc
	global_load_dword v34, v[2:3], off
	v_add_co_u32_e32 v2, vcc, s10, v66
	s_mov_b32 s10, 0xcb000
	s_nop 0
	v_addc_co_u32_e32 v3, vcc, 0, v67, vcc
	global_load_dword v35, v[2:3], off offset:2048
	v_add_co_u32_e32 v2, vcc, s89, v66
	s_nop 1
	v_addc_co_u32_e32 v3, vcc, 0, v67, vcc
	global_load_dword v20, v[2:3], off
	v_add_co_u32_e32 v2, vcc, s10, v66
	s_mov_b32 s10, 0xd1000
	s_nop 0
	v_addc_co_u32_e32 v3, vcc, 0, v67, vcc
	global_load_dword v21, v[2:3], off offset:2048
	v_add_co_u32_e32 v2, vcc, s10, v66
	s_mov_b32 s10, 0xd6000
	s_nop 0
	v_addc_co_u32_e32 v3, vcc, 0, v67, vcc
	global_load_dword v26, v[2:3], off
	v_add_co_u32_e32 v2, vcc, s10, v66
	s_mov_b32 s10, 0xdc000
	s_nop 0
	v_addc_co_u32_e32 v3, vcc, 0, v67, vcc
	global_load_dword v27, v[2:3], off offset:2048
	v_add_co_u32_e32 v2, vcc, s10, v66
	s_mov_b32 s10, 0xe1000
	s_nop 0
	v_addc_co_u32_e32 v3, vcc, 0, v67, vcc
	global_load_dword v24, v[2:3], off
	v_add_co_u32_e32 v2, vcc, s10, v66
	s_mov_b32 s10, 0xe7000
	s_nop 0
	v_addc_co_u32_e32 v3, vcc, 0, v67, vcc
	global_load_dword v25, v[2:3], off offset:2048
	v_add_co_u32_e32 v2, vcc, s10, v66
	s_mov_b32 s10, 0xec000
	s_nop 0
	v_addc_co_u32_e32 v3, vcc, 0, v67, vcc
	global_load_dword v28, v[2:3], off
	v_add_co_u32_e32 v2, vcc, s10, v66
	s_mov_b32 s10, 0xf2000
	s_nop 0
	v_addc_co_u32_e32 v3, vcc, 0, v67, vcc
	global_load_dword v29, v[2:3], off offset:2048
	v_add_co_u32_e32 v2, vcc, s10, v66
	s_mov_b32 s10, 0xf7000
	s_nop 0
	v_addc_co_u32_e32 v3, vcc, 0, v67, vcc
	global_load_dword v12, v[2:3], off
	v_add_co_u32_e32 v2, vcc, s10, v66
	s_mov_b32 s10, 0xfd000
	s_nop 0
	v_addc_co_u32_e32 v3, vcc, 0, v67, vcc
	global_load_dword v13, v[2:3], off offset:2048
	v_add_co_u32_e32 v2, vcc, s10, v66
	s_mov_b32 s10, 0x102000
	s_nop 0
	v_addc_co_u32_e32 v3, vcc, 0, v67, vcc
	global_load_dword v18, v[2:3], off
	v_add_co_u32_e32 v2, vcc, s10, v66
	s_mov_b32 s10, 0x108000
	s_nop 0
	v_addc_co_u32_e32 v3, vcc, 0, v67, vcc
	global_load_dword v19, v[2:3], off offset:2048
	v_add_co_u32_e32 v2, vcc, s10, v66
	s_mov_b32 s10, 0x10d000
	s_nop 0
	v_addc_co_u32_e32 v3, vcc, 0, v67, vcc
	global_load_dword v16, v[2:3], off
	v_add_co_u32_e32 v2, vcc, s10, v66
	s_mov_b32 s10, 0x113000
	s_nop 0
	v_addc_co_u32_e32 v3, vcc, 0, v67, vcc
	global_load_dword v17, v[2:3], off offset:2048
	v_add_co_u32_e32 v2, vcc, s10, v66
	s_mov_b32 s10, 0x118000
	s_nop 0
	v_addc_co_u32_e32 v3, vcc, 0, v67, vcc
	global_load_dword v22, v[2:3], off
	v_add_co_u32_e32 v2, vcc, s10, v66
	s_mov_b32 s10, 0x11e000
	s_nop 0
	v_addc_co_u32_e32 v3, vcc, 0, v67, vcc
	global_load_dword v23, v[2:3], off offset:2048
	v_add_co_u32_e32 v2, vcc, s10, v66
	s_mov_b32 s10, 0x123000
	s_nop 0
	v_addc_co_u32_e32 v3, vcc, 0, v67, vcc
	global_load_dword v4, v[2:3], off
	v_add_co_u32_e32 v2, vcc, s10, v66
	s_mov_b32 s10, 0x129000
	s_nop 0
	v_addc_co_u32_e32 v3, vcc, 0, v67, vcc
	global_load_dword v5, v[2:3], off offset:2048
	v_add_co_u32_e32 v2, vcc, s10, v66
	s_mov_b32 s10, 0x12e000
	s_nop 0
	v_addc_co_u32_e32 v3, vcc, 0, v67, vcc
	global_load_dword v10, v[2:3], off
	v_add_co_u32_e32 v2, vcc, s10, v66
	s_mov_b32 s10, 0x134000
	s_nop 0
	v_addc_co_u32_e32 v3, vcc, 0, v67, vcc
	global_load_dword v11, v[2:3], off offset:2048
	v_add_co_u32_e32 v2, vcc, s10, v66
	s_mov_b32 s10, 0x139000
	s_nop 0
	v_addc_co_u32_e32 v3, vcc, 0, v67, vcc
	global_load_dword v6, v[2:3], off
	v_add_co_u32_e32 v2, vcc, s10, v66
	s_mov_b32 s10, 0x13f000
	s_nop 0
	v_addc_co_u32_e32 v3, vcc, 0, v67, vcc
	global_load_dword v7, v[2:3], off offset:2048
	v_add_co_u32_e32 v2, vcc, s10, v66
	s_mov_b32 s10, 0x144000
	s_nop 0
	v_addc_co_u32_e32 v3, vcc, 0, v67, vcc
	global_load_dword v14, v[2:3], off
	v_add_co_u32_e32 v2, vcc, s10, v66
	s_mov_b32 s10, 0x14a000
	s_nop 0
	v_addc_co_u32_e32 v3, vcc, 0, v67, vcc
	global_load_dword v15, v[2:3], off offset:2048
	v_add_co_u32_e32 v2, vcc, s10, v66
	s_mov_b32 s10, 0x14f000
	s_nop 0
	v_addc_co_u32_e32 v3, vcc, 0, v67, vcc
	v_add_co_u32_e32 v8, vcc, s10, v66
	global_load_dword v2, v[2:3], off
	s_nop 0
	v_addc_co_u32_e32 v9, vcc, 0, v67, vcc
	global_load_dword v3, v[8:9], off offset:2048
	v_add_co_u32_e32 v8, vcc, 0x155000, v66
	s_cselect_b64 s[10:11], -1, 0
	s_nop 0
	v_addc_co_u32_e32 v9, vcc, 0, v67, vcc
	v_add_co_u32_e32 v66, vcc, 0x15a000, v66
	global_load_dword v8, v[8:9], off
	s_nop 0
	v_addc_co_u32_e32 v67, vcc, 0, v67, vcc
	global_load_dword v9, v[66:67], off offset:2048
	s_cmp_eq_u64 s[4:5], 0
	s_cbranch_scc1 .LBB0_1201
	s_lshl_b64 s[4:5], s[8:9], 2
	s_add_u32 s4, s25, s4
	s_addc_u32 s5, s29, s5
	global_load_dwordx4 v[66:69], v161, s[4:5]
	s_mov_b64 s[12:13], 0
	s_waitcnt vmcnt(0)
	v_pk_mul_f32 v[66:67], v[62:63], v[66:67]
	v_pk_mul_f32 v[68:69], v[64:65], v[68:69]

; __device__ __forceinline__ unsigned xb_ld(unsigned* p)              { return __hip_atomic_load(p, __ATOMIC_RELAXED, __HIP_MEMORY_SCOPE_AGENT); }
; __device__ __forceinline__ unsigned xb_add(unsigned* p, unsigned v) { return __hip_atomic_fetch_add(p, v, __ATOMIC_RELAXED, __HIP_MEMORY_SCOPE_AGENT); }
; #define XB_SPIN(cond, bar) do { unsigned _sp = 0; while (cond) { __builtin_amdgcn_s_sleep(1); \
;     if ((++_sp & 255u) == 0u) { if (xb_ld(&(bar)[XB_TMO])) break; if (_sp > XB_SPIN_CAP) { atomicAdd(&(bar)[XB_TMO], 1u); break; } } } } while (0)
; __device__ __forceinline__ void xcd_barrier(const XcdBarrier& b, bool t0) {
;     asm volatile("s_waitcnt vmcnt(0)" ::: "memory");
;     __syncthreads();
;     if (t0) {
;         unsigned* bar = b.bar;
;         __builtin_amdgcn_s_waitcnt(0);
;         unsigned nloc = b.st[0], nx = b.st[1];
;         if (nloc == 0u) { xcd_barrier_complete(bar, b.x, nloc, nx); b.st[0] = nloc; b.st[1] = nx; }
;         const unsigned old = xb_add(&bar[XB_XSUB(b.x)], 1u);
;         const unsigned gen = old / nloc;
;         if (old + 1u == (gen + 1u) * nloc) {
;             __builtin_amdgcn_fence(__ATOMIC_RELEASE, "agent");
;             asm volatile("s_waitcnt vmcnt(0)" ::: "memory");
;             const unsigned og = xb_add(&bar[XB_TOP], 1u);
;             const unsigned tg = og / nx;
;             if (og + 1u == (tg + 1u) * nx) xb_add(&bar[XB_TOPGEN], 1u);
;             else XB_SPIN(xb_ld(&bar[XB_TOPGEN]) == tg, bar);
;             __builtin_amdgcn_fence(__ATOMIC_ACQUIRE, "agent");
;             xb_add(&bar[XB_XGEN(b.x)], 1u);
;             asm volatile("s_waitcnt vmcnt(0)" ::: "memory");
;         } else {
;             XB_SPIN(xb_ld(&bar[XB_XGEN(b.x)]) == gen, bar);
;             __builtin_amdgcn_fence(__ATOMIC_ACQUIRE, "agent");
;             asm volatile("s_waitcnt vmcnt(0)" ::: "memory");
;         }
;     }
;     __syncthreads();
.LBB0_1263:
	s_waitcnt lgkmcnt(0)
	v_mov_b32_e32 v0, v161
	v_mov_b32_e32 v2, v183
	v_add_u32_e32 v0, 0, v0
	v_add_u32_e32 v0, 0x201c0, v0
	s_nop 0
	s_getreg_b32 s8, hwreg(HW_REG_XCC_ID, 0, 4)
	s_waitcnt vmcnt(0)
	v_readlane_b32 s7, v251, 49
	v_readlane_b32 s6, v251, 48
	v_cmp_eq_u32_e32 vcc, 0, v2
	s_barrier
	s_and_saveexec_b64 s[4:5], vcc
	s_mov_b32 s0, s60
	s_cbranch_execz .LBB0_1315
	v_readlane_b32 s9, v250, 17
	s_waitcnt vmcnt(0) expcnt(0) lgkmcnt(0)
	s_and_b32 s14, s8, 15
	v_mov_b32_e32 v0, s9
	ds_read_b32 v2, v0
	v_readlane_b32 s9, v250, 18
	s_waitcnt lgkmcnt(0)
	v_cmp_ne_u32_e32 vcc, 0, v2
	v_mov_b32_e32 v0, s9
	ds_read_b32 v0, v0
	s_cbranch_vccnz .LBB0_1279
	s_add_u32 s8, s6, 0x28680200
	s_addc_u32 s9, s7, 0
	s_add_u32 s10, s6, 0x28680400
	s_addc_u32 s11, s7, 0
	s_add_u32 s12, s6, 0x28680500
	s_addc_u32 s13, s7, 0
	s_add_u32 s18, s6, 0x28680600
	s_addc_u32 s19, s7, 0
	s_add_u32 s34, s6, 0x28680700
	s_addc_u32 s35, s7, 0
	s_add_u32 s40, s6, 0x28680800
	s_addc_u32 s41, s7, 0
	s_add_u32 s42, s6, 0x28680900
	s_addc_u32 s43, s7, 0
	s_add_u32 s44, s6, 0x28680a00
	s_addc_u32 s45, s7, 0
	s_add_u32 s48, s6, 0x28680b00
	s_addc_u32 s49, s7, 0
	s_add_u32 s50, s6, 0x28680c00
	s_addc_u32 s51, s7, 0
	s_add_u32 s52, s6, 0x28680d00
	s_addc_u32 s53, s7, 0
	s_add_u32 s56, s6, 0x28680e00
	s_addc_u32 s57, s7, 0
	s_add_u32 s60, s6, 0x28680f00
	s_addc_u32 s61, s7, 0
	s_add_u32 s62, s6, 0x28681000
	s_addc_u32 s63, s7, 0
	s_add_u32 s64, s6, 0x28681100
	s_addc_u32 s65, s7, 0
	s_add_u32 s66, s6, 0x28681200
	s_addc_u32 s67, s7, 0
	s_add_u32 s24, s6, 0x28681300
	s_addc_u32 s25, s7, 0
	s_mov_b32 s15, 1
	s_branch .LBB0_1267

; #define LAS __attribute__((address_space(3)))
; #define PIN(i) ((const float*)ldq_(L, (i)))
; __device__ __forceinline__ bf16x8 pack8(const float* v) { u32x4 w; w.x = pk2(v[0], v[1]); w.y = pk2(v[2], v[3]); w.z = pk2(v[4], v[5]); w.w = pk2(v[6], v[7]); return __builtin_bit_cast(bf16x8, w); }
; __device__ __forceinline__ void unpack8(u32x4 w, float* v) { v[0] = bflo(w.x); v[1] = bfhi(w.x); v[2] = bflo(w.y); v[3] = bfhi(w.y); v[4] = bflo(w.z); v[5] = bfhi(w.z); v[6] = bflo(w.w); v[7] = bfhi(w.w); }
; __device__ __forceinline__ void mixer_unit(const Params& p, int layer, int cu, LAS unsigned char* L, int wv) {
;     ...
;         float kn[8];
; #pragma unroll
;         for (int i = 0; i < 8; ++i) kn[i] = PIN(I_KN)[layer * 64 + sub * 8 + i];
; #pragma unroll
;         for (int ps = 0; ps < 12; ++ps) if (ps < npass) {
;             const int kk = klo + 16 * ps + rsub;
;             float v[8]; unpack8(raw[ps], v);
;             float ss = 0.f;
; #pragma unroll
;             for (int i = 0; i < 8; ++i) ss += v[i] * v[i];
;             ss += __shfl_xor(ss, 1); ss += __shfl_xor(ss, 2); ss += __shfl_xor(ss, 4);
;             const float rs = __builtin_amdgcn_rsqf(ss * (1.0f / 64.0f) + EPS);
; #pragma unroll
;             for (int i = 0; i < 8; ++i) { if (isK) v[i] = v[i] * rs * kn[i]; }
;             *(LAS bf16x8*)(L + (isK ? LK_OFF : LV_OFF) + ((kvh * 192 + kk) * KROW + sub * 8) * 2) = pack8(v);
;             int orow = -1;
;             if (is_s) orow = kk - 64; else if (c >= 30 && kk >= 128) orow = (c - 30) * 64 + (kk - 128);
;             if (orow >= 0 && !(isK && sub < 2)) {
;                 float* dst = POUT + (isK ? (is_s ? O_KS : O_KP) : (is_s ? O_VS : O_VP)) + ((((size_t)layer * NB + b) * 128 + orow) * 2 + kvh) * 64 + sub * 8;
;                 *(f32x4*)dst = (f32x4){v[0], v[1], v[2], v[3]}; *(f32x4*)(dst + 4) = (f32x4){v[4], v[5], v[6], v[7]};
;             }
;         }
.LBB0_1348:
	v_mov_b32_e32 v48, v161
	v_or_b32_e32 v160, s63, v54
	v_add_u32_e32 v48, s85, v48
	s_waitcnt vmcnt(16)
	s_nop 0
	s_cmp_gt_u32 s76, 29
	s_mov_b64 s[60:61], -1
	s_waitcnt lgkmcnt(0)
	v_readlane_b32 s19, v251, 27
	v_readlane_b32 s18, v251, 26
	v_lshlrev_b64 v[48:49], 2, v[160:161]
	s_waitcnt vmcnt(14)
	v_lshl_add_u64 v[50:51], s[18:19], 0, v[48:49]
	global_load_dword v58, v[50:51], off
	v_mov_b32_e32 v50, v161
	s_nop 0
	v_add_u32_e32 v50, s85, v50
	s_nop 0
	v_readlane_b32 s19, v251, 27
	v_readlane_b32 s18, v251, 26
	s_nop 1
	v_lshl_add_u64 v[50:51], s[18:19], 0, v[48:49]
	global_load_dword v59, v[50:51], off offset:4
	v_mov_b32_e32 v50, v161
	s_nop 0
	v_add_u32_e32 v50, s85, v50
	s_nop 0
	v_readlane_b32 s19, v251, 27
	v_readlane_b32 s18, v251, 26
	s_nop 1
	v_lshl_add_u64 v[50:51], s[18:19], 0, v[48:49]
	global_load_dword v60, v[50:51], off offset:8
	v_mov_b32_e32 v50, v161
	s_nop 0
	v_add_u32_e32 v50, s85, v50
	s_nop 0
	v_readlane_b32 s19, v251, 27
	v_readlane_b32 s18, v251, 26
	s_nop 1
	v_lshl_add_u64 v[50:51], s[18:19], 0, v[48:49]
	global_load_dword v61, v[50:51], off offset:12
	v_mov_b32_e32 v50, v161
	s_nop 0
	v_add_u32_e32 v50, s85, v50
	s_nop 0
	v_readlane_b32 s19, v251, 27
	v_readlane_b32 s18, v251, 26
	s_nop 1
	v_lshl_add_u64 v[50:51], s[18:19], 0, v[48:49]
	global_load_dword v62, v[50:51], off offset:16
	v_mov_b32_e32 v50, v161
	s_nop 0
	v_add_u32_e32 v50, s85, v50
	s_nop 0
	v_readlane_b32 s19, v251, 27
	v_readlane_b32 s18, v251, 26
	s_nop 1
	v_lshl_add_u64 v[50:51], s[18:19], 0, v[48:49]
	global_load_dword v63, v[50:51], off offset:20
	v_mov_b32_e32 v50, v161
	s_nop 0
	v_add_u32_e32 v50, s85, v50
	s_nop 0
	v_readlane_b32 s19, v251, 27
	v_readlane_b32 s18, v251, 26
	s_nop 1
	v_lshl_add_u64 v[50:51], s[18:19], 0, v[48:49]
	global_load_dword v65, v[50:51], off offset:24
	v_mov_b32_e32 v50, v161
	s_nop 0
	v_add_u32_e32 v50, s85, v50
	s_nop 0
	v_readlane_b32 s19, v251, 27
	v_readlane_b32 s18, v251, 26
	s_waitcnt vmcnt(10)
	v_lshlrev_b32_e32 v50, 16, v45
	v_and_b32_e32 v51, 0xffff0000, v45
	v_lshl_add_u64 v[48:49], s[18:19], 0, v[48:49]
	global_load_dword v67, v[48:49], off offset:28
	v_cndmask_b32_e64 v48, v198, 0, s[8:9]
	v_and_b32_e32 v49, 0xffff0000, v44
	v_add_u32_e32 v66, 0, v48
	v_lshlrev_b32_e32 v48, 16, v44
	v_mul_f32_e32 v70, v49, v49
	v_fmac_f32_e32 v70, v48, v48
	v_fmac_f32_e32 v70, v50, v50
	v_and_b32_e32 v44, 0xffff0000, v46
	v_lshlrev_b32_e32 v45, 16, v46
	v_fmac_f32_e32 v70, v51, v51
	v_pk_mov_b32 v[56:57], v[44:45], v[44:45] op_sel:[1,0]
	v_pk_mul_f32 v[44:45], v[44:45], v[44:45]
	s_cselect_b64 s[18:19], -1, 0
	v_add_f32_e32 v45, v45, v70
	v_add_f32_e32 v70, v44, v45
	v_and_b32_e32 v44, 0xffff0000, v47
	v_lshlrev_b32_e32 v45, 16, v47
	v_pk_mov_b32 v[46:47], v[44:45], v[44:45] op_sel:[1,0]
	v_pk_mul_f32 v[44:45], v[44:45], v[44:45]
	s_or_b32 s13, s77, 0xfffff800
	v_add_f32_e32 v45, v45, v70
	v_add_f32_e32 v44, v44, v45
	s_and_b64 vcc, exec, s[40:41]
	s_nop 1
	v_add_f32_dpp v44, v44, v44 quad_perm:[1,0,3,2] row_mask:0xf bank_mask:0xf
	s_nop 1
	v_add_f32_dpp v44, v44, v44 quad_perm:[2,3,0,1] row_mask:0xf bank_mask:0xf
	s_nop 1
	v_add_f32_dpp v44, v44, v44 row_half_mirror row_mask:0xf bank_mask:0xf
	s_nop 0
	v_fmamk_f32 v44, v44, 0x3c800000, v189
	v_rsq_f32_e32 v44, v44
	s_nop 0
	v_mul_f32_e32 v73, v44, v56
	v_mul_f32_e32 v45, v44, v48
	v_mul_f32_e32 v70, v44, v49
	v_mul_f32_e32 v71, v44, v50
	v_mul_f32_e32 v72, v44, v51
	s_waitcnt vmcnt(3)
	v_mul_f32_e32 v73, v62, v73
	v_mul_f32_e32 v74, v44, v57
	v_mul_f32_e32 v75, v44, v46
	v_mul_f32_e32 v44, v44, v47
	v_mul_f32_e32 v45, v58, v45
	v_mul_f32_e32 v70, v59, v70
	v_mul_f32_e32 v71, v60, v71
	v_mul_f32_e32 v72, v61, v72
	s_waitcnt vmcnt(2)
	v_mul_f32_e32 v74, v63, v74
	v_cndmask_b32_e64 v49, v49, v70, s[8:9]
	v_cndmask_b32_e64 v48, v48, v45, s[8:9]
	v_cndmask_b32_e64 v50, v50, v71, s[8:9]
	v_cndmask_b32_e64 v51, v51, v72, s[8:9]
	v_cndmask_b32_e64 v45, v57, v74, s[8:9]
	s_waitcnt vmcnt(1)
	v_mul_f32_e32 v75, v65, v75
	v_cndmask_b32_e64 v46, v46, v75, s[8:9]
	v_cvt_pk_bf16_f32 v70, v48, v49
	v_cvt_pk_bf16_f32 v71, v50, v51
	s_waitcnt vmcnt(0)
	v_mul_f32_e32 v76, v67, v44
	v_cndmask_b32_e64 v44, v56, v73, s[8:9]
	v_add_u32_e32 v56, v55, v64
	v_cndmask_b32_e64 v47, v47, v76, s[8:9]
	v_mad_u64_u32 v[56:57], s[24:25], v56, s86, v[54:55]
	v_cvt_pk_bf16_f32 v72, v44, v45
	v_cvt_pk_bf16_f32 v73, v46, v47
	v_lshl_add_u32 v56, v56, 1, v66
	ds_write_b128 v56, v[70:73]
	s_cbranch_vccz .LBB0_1350
	s_movk_i32 s16, 0x7f
	v_cmp_lt_i32_e32 vcc, s16, v64
	v_add_u32_e32 v56, s13, v64
	s_and_b64 vcc, s[18:19], vcc
	v_cndmask_b32_e32 v70, -1, v56, vcc
	s_mov_b64 s[60:61], 0

; #define PIN(i) ((const float*)ldq_(L, (i)))
; __device__ __forceinline__ void unpack8(u32x4 w, float* v) { v[0] = bflo(w.x); v[1] = bfhi(w.x); v[2] = bflo(w.y); v[3] = bfhi(w.y); v[4] = bflo(w.z); v[5] = bfhi(w.z); v[6] = bflo(w.w); v[7] = bfhi(w.w); }
; __device__ __forceinline__ void mixer_unit(const Params& p, int layer, int cu, LAS unsigned char* L, int wv) {
;     ...
;     bf16x8 qf[4][2];
;     {
;         float gq0[8], gq1[8];
; #pragma unroll
;         for (int i = 0; i < 8; ++i) { gq0[i] = PIN(I_QN)[layer * 64 + 8 * quad + i]; gq1[i] = PIN(I_QN)[layer * 64 + 32 + 8 * quad + i]; }
;         constexpr float QS = 0.125f * LOG2E;
; #pragma unroll
;         for (int qb = 0; qb < 4; ++qb) {
;             float v0[8], v1[8]; unpack8(qraw[qb][0], v0); unpack8(qraw[qb][1], v1);
;             float ss = 0.f;
; #pragma unroll
;             for (int i = 0; i < 8; ++i) ss += v0[i] * v0[i] + v1[i] * v1[i];
;             ss += __shfl_xor(ss, 16); ss += __shfl_xor(ss, 32);
;             const float rs = __builtin_amdgcn_rsqf(ss * (1.0f / 64.0f) + EPS);
;             float pv[8];
; #pragma unroll
;             for (int i = 0; i < 8; ++i) { v0[i] = v0[i] * rs * gq0[i]; v1[i] = v1[i] * rs * gq1[i] * QS; pv[i] = __shfl_xor(v0[i], 16); }
.LBB0_1416:
	s_or_b64 exec, exec, s[10:11]
	v_mov_b32_e32 v96, v161
	v_bfe_u32 v122, v178, 4, 2
	v_add_u32_e32 v96, s23, v96
	s_nop 0
	v_lshlrev_b32_e32 v180, 3, v122
	v_or_b32_e32 v160, s63, v180
	v_lshlrev_b64 v[100:101], 2, v[160:161]
	v_mov_b32_e32 v102, v161
	s_waitcnt lgkmcnt(0)
	v_readlane_b32 s9, v251, 25
	v_readlane_b32 s8, v251, 24
	v_mov_b32_e32 v104, v161
	v_mov_b32_e32 v106, v161
	v_lshl_add_u64 v[96:97], s[8:9], 0, v[100:101]
	global_load_dword v96, v[96:97], off
	v_mov_b32_e32 v97, v161
	s_waitcnt vmcnt(8)
	v_and_b32_e32 v108, 0xffff0000, v90
	v_add_u32_e32 v97, s23, v97
	s_nop 0
	v_mov_b32_e32 v97, v161
	v_lshlrev_b32_e32 v109, 16, v90
	v_and_b32_e32 v110, 0xffff0000, v91
	v_lshlrev_b32_e32 v111, 16, v91
	v_readlane_b32 s9, v251, 25
	v_readlane_b32 s8, v251, 24
	s_waitcnt vmcnt(7)
	v_and_b32_e32 v90, 0xffff0000, v95
	v_lshlrev_b32_e32 v91, 16, v95
	v_lshl_add_u64 v[98:99], s[8:9], 0, v[100:101]
	global_load_dword v132, v[98:99], off offset:128
	v_lshlrev_b32_e32 v116, 16, v88
	v_add_u32_e32 v97, s23, v97
	s_nop 0
	v_and_b32_e32 v117, 0xffff0000, v88
	v_lshlrev_b32_e32 v118, 16, v89
	v_and_b32_e32 v119, 0xffff0000, v89
	v_cmp_gt_u32_e32 vcc, 16, v181
	v_readlane_b32 s9, v251, 25
	v_readlane_b32 s8, v251, 24
	s_nop 1
	v_lshl_add_u64 v[98:99], s[8:9], 0, v[100:101]
	global_load_dword v97, v[98:99], off offset:4
	s_nop 0
	v_add_u32_e32 v98, s23, v102
	s_nop 0
	v_mov_b32_e32 v102, v161
	v_readlane_b32 s9, v251, 25
	v_readlane_b32 s8, v251, 24
	s_nop 1
	v_lshl_add_u64 v[98:99], s[8:9], 0, v[100:101]
	global_load_dword v133, v[98:99], off offset:132
	s_nop 0
	v_add_u32_e32 v98, s23, v102
	s_nop 0
	v_mov_b32_e32 v102, v161
	v_readlane_b32 s9, v251, 25
	v_readlane_b32 s8, v251, 24
	s_nop 1
	v_lshl_add_u64 v[98:99], s[8:9], 0, v[100:101]
	global_load_dword v98, v[98:99], off offset:8
	s_nop 0
	v_add_u32_e32 v99, s23, v102
	s_nop 0
	v_mov_b32_e32 v99, v161
	v_readlane_b32 s9, v251, 25
	v_readlane_b32 s8, v251, 24
	s_nop 1
	v_lshl_add_u64 v[102:103], s[8:9], 0, v[100:101]
	global_load_dword v134, v[102:103], off offset:136
	s_nop 0
	v_add_u32_e32 v99, s23, v99
	s_nop 0
	v_readlane_b32 s9, v251, 25
	v_readlane_b32 s8, v251, 24
	s_nop 1
	v_lshl_add_u64 v[102:103], s[8:9], 0, v[100:101]
	global_load_dword v99, v[102:103], off offset:12
	s_nop 0
	v_add_u32_e32 v102, s23, v104
	s_nop 0
	v_mov_b32_e32 v104, v161
	v_readlane_b32 s9, v251, 25
	v_readlane_b32 s8, v251, 24
	s_nop 1
	v_lshl_add_u64 v[102:103], s[8:9], 0, v[100:101]
	global_load_dword v135, v[102:103], off offset:140
	s_nop 0
	v_add_u32_e32 v102, s23, v104
	s_nop 0
	v_mov_b32_e32 v104, v161
	v_readlane_b32 s9, v251, 25
	v_readlane_b32 s8, v251, 24
	s_nop 1
	v_lshl_add_u64 v[102:103], s[8:9], 0, v[100:101]
	global_load_dword v102, v[102:103], off offset:16
	s_nop 0
	v_add_u32_e32 v103, s23, v104
	s_nop 0
	v_mov_b32_e32 v103, v161
	v_readlane_b32 s9, v251, 25
	v_readlane_b32 s8, v251, 24
	s_nop 1
	v_lshl_add_u64 v[104:105], s[8:9], 0, v[100:101]
	global_load_dword v137, v[104:105], off offset:144
	s_nop 0
	v_add_u32_e32 v103, s23, v103
	s_nop 0
	v_readlane_b32 s9, v251, 25
	v_readlane_b32 s8, v251, 24
	s_nop 1
	v_lshl_add_u64 v[104:105], s[8:9], 0, v[100:101]
	global_load_dword v103, v[104:105], off offset:20
	s_nop 0
	v_add_u32_e32 v104, s23, v106
	s_nop 0
	v_mov_b32_e32 v106, v161
	v_readlane_b32 s9, v251, 25
	v_readlane_b32 s8, v251, 24
	s_nop 1
	v_lshl_add_u64 v[104:105], s[8:9], 0, v[100:101]
	global_load_dword v136, v[104:105], off offset:148
	s_nop 0
	v_add_u32_e32 v104, s23, v106
	s_nop 0
	v_mov_b32_e32 v106, v161
	v_readlane_b32 s9, v251, 25
	v_readlane_b32 s8, v251, 24
	s_nop 1
	v_lshl_add_u64 v[104:105], s[8:9], 0, v[100:101]
	global_load_dword v112, v[104:105], off offset:24
	s_nop 0
	v_add_u32_e32 v104, s23, v106
	s_nop 0
	v_mov_b32_e32 v106, v161
	v_readlane_b32 s9, v251, 25
	v_readlane_b32 s8, v251, 24
	s_nop 1
	v_lshl_add_u64 v[104:105], s[8:9], 0, v[100:101]
	global_load_dword v139, v[104:105], off offset:152
	s_nop 0
	v_add_u32_e32 v104, s23, v106
	s_nop 0
	v_mov_b32_e32 v106, v161
	v_readlane_b32 s9, v251, 25
	v_readlane_b32 s8, v251, 24
	s_nop 1
	v_lshl_add_u64 v[104:105], s[8:9], 0, v[100:101]
	global_load_dword v113, v[104:105], off offset:28
	s_nop 0
	v_add_u32_e32 v104, s23, v106
	s_nop 0
	v_readlane_b32 s9, v251, 25
	v_readlane_b32 s8, v251, 24
	s_nop 1
	v_lshl_add_u64 v[100:101], s[8:9], 0, v[100:101]
	global_load_dword v138, v[100:101], off offset:156
	v_and_b32_e32 v100, 0xffff0000, v94
	v_lshlrev_b32_e32 v101, 16, v94
	v_pk_mul_f32 v[104:105], v[100:101], v[100:101]
	v_pk_mul_f32 v[94:95], v[90:91], v[90:91]
	v_pk_fma_f32 v[106:107], v[108:109], v[108:109], v[104:105]
	v_lshlrev_b32_e32 v104, 16, v92
	v_and_b32_e32 v105, 0xffff0000, v92
	v_pk_fma_f32 v[114:115], v[110:111], v[110:111], v[94:95]
	v_lshlrev_b32_e32 v94, 16, v93
	v_and_b32_e32 v95, 0xffff0000, v93
	v_pk_mul_f32 v[92:93], v[104:105], v[104:105]
	v_pk_mul_f32 v[88:89], v[94:95], v[94:95]
	v_pk_fma_f32 v[92:93], v[116:117], v[116:117], v[92:93]
	v_pk_fma_f32 v[88:89], v[118:119], v[118:119], v[88:89]
	v_add_f32_e32 v92, v92, v93
	v_add_f32_e32 v88, v88, v92
	v_add_f32_e32 v88, v89, v88
	v_add_f32_e32 v88, v107, v88
	v_add_f32_e32 v88, v106, v88
	v_add_f32_e32 v88, v115, v88
	v_add_f32_e32 v88, v114, v88
	ds_bpermute_b32 v89, v184, v88
	s_waitcnt lgkmcnt(0)
	v_add_f32_e32 v88, v88, v89
	ds_bpermute_b32 v89, v185, v88
	s_waitcnt lgkmcnt(0)
	v_add_f32_e32 v88, v88, v89
	v_fmamk_f32 v88, v88, 0x3c800000, v189
	v_rsq_f32_e32 v92, v88
	s_nop 0
	v_pk_mul_f32 v[88:89], v[92:93], v[116:117] op_sel_hi:[0,1]
	v_pk_mul_f32 v[106:107], v[92:93], v[118:119] op_sel_hi:[0,1]
	v_pk_mul_f32 v[108:109], v[92:93], v[108:109] op_sel_hi:[0,1]
	v_pk_mul_f32 v[110:111], v[92:93], v[110:111] op_sel_hi:[0,1]
	s_waitcnt vmcnt(13)
	v_pk_mul_f32 v[88:89], v[96:97], v[88:89]
	s_waitcnt vmcnt(9)
	v_pk_mul_f32 v[106:107], v[98:99], v[106:107]
	s_waitcnt vmcnt(5)
	v_pk_mul_f32 v[108:109], v[102:103], v[108:109] op_sel:[0,1] op_sel_hi:[1,0]
	ds_bpermute_b32 v120, v184, v88
	ds_bpermute_b32 v121, v184, v89
	ds_bpermute_b32 v118, v184, v106
	ds_bpermute_b32 v119, v184, v107
	ds_bpermute_b32 v116, v184, v108
	ds_bpermute_b32 v117, v184, v109
	s_waitcnt vmcnt(1)
	v_pk_mul_f32 v[110:111], v[112:113], v[110:111] op_sel:[0,1] op_sel_hi:[1,0]
	ds_bpermute_b32 v114, v184, v110
	ds_bpermute_b32 v115, v184, v111
	s_and_saveexec_b64 s[8:9], s[6:7]
	s_cbranch_execz .LBB0_1418
; __device__ __forceinline__ void mixer_unit(const Params& p, int layer, int cu, LAS unsigned char* L, int wv) {
;     ...
;             if (quad < 2) {
;                 const f32x4 c0 = rq[qb][0], c1 = rq[qb][1], s0 = rq[qb][2], s1 = rq[qb][3];
; #pragma unroll
;                 for (int i = 0; i < 8; ++i) { const float cs = i < 4 ? c0[i & 3] : c1[i & 3], sn = i < 4 ? s0[i & 3] : s1[i & 3]; v0[i] = (quad == 0) ? v0[i] * cs - pv[i] * sn : v0[i] * cs + pv[i] * sn; }
;             }
	s_waitcnt lgkmcnt(6)
	v_pk_mul_f32 v[84:85], v[84:85], v[120:121]
	s_waitcnt lgkmcnt(4)
	v_pk_mul_f32 v[86:87], v[86:87], v[118:119]
	s_waitcnt lgkmcnt(2)
	v_pk_mul_f32 v[80:81], v[80:81], v[116:117]
	s_waitcnt lgkmcnt(0)
	v_pk_mul_f32 v[82:83], v[82:83], v[114:115]
	v_cndmask_b32_e64 v85, v85, -v85, vcc
	v_cndmask_b32_e64 v84, v84, -v84, vcc
	v_cndmask_b32_e64 v87, v87, -v87, vcc
	v_cndmask_b32_e64 v86, v86, -v86, vcc
	v_cndmask_b32_e64 v81, v81, -v81, vcc
	v_cndmask_b32_e64 v80, v80, -v80, vcc
	v_cndmask_b32_e64 v83, v83, -v83, vcc
	v_cndmask_b32_e64 v82, v82, -v82, vcc
	v_pk_fma_f32 v[88:89], v[72:73], v[88:89], v[84:85]
	v_pk_fma_f32 v[106:107], v[74:75], v[106:107], v[86:87]
	v_pk_fma_f32 v[108:109], v[76:77], v[108:109], v[80:81]
	v_pk_fma_f32 v[110:111], v[78:79], v[110:111], v[82:83]

; #define LAS __attribute__((address_space(3)))
; #define PIN(i) ((const float*)ldq_(L, (i)))
; __device__ __forceinline__ bf16x8 pack8(const float* v) { u32x4 w; w.x = pk2(v[0], v[1]); w.y = pk2(v[2], v[3]); w.z = pk2(v[4], v[5]); w.w = pk2(v[6], v[7]); return __builtin_bit_cast(bf16x8, w); }
; __device__ __forceinline__ void mixer_unit(const Params& p, int layer, int cu, LAS unsigned char* L, int wv) {
;     ...
; #pragma unroll
;             for (int i = 0; i < 8; ++i) v0[i] *= QS;
;             qf[qb][0] = pack8(v0); qf[qb][1] = pack8(v1);
;         }
;     }
;     __syncthreads();
;     {
;         const float sinkv = PIN(I_SINK)[layer * 8 + h] * LOG2E;
;         const LAS unsigned char* Kb = L + LK_OFF + ((kvhq * 192 + q16) * KROW + 8 * quad) * 2;
;         const LAS unsigned char* Vb = L + LV_OFF + ((kvhq * 192 + 4 * quad + (q16 >> 2)) * KROW + 4 * (q16 & 3)) * 2;
; #pragma unroll
;         for (int pr = 0; pr < 2; ++pr) {
;             f32x4 s[2][12];
; #pragma unroll
;             for (int kt = 0; kt < 12; ++kt) {
;                 if (16 * kt >= kstart) {
;                     const bf16x8 k0 = *(const LAS bf16x8*)(Kb + kt * 16 * KROW * 2), k1 = *(const LAS bf16x8*)(Kb + kt * 16 * KROW * 2 + 64);
; #pragma unroll
;                     for (int e = 0; e < 2; ++e) { s[e][kt] = __builtin_amdgcn_mfma_f32_16x16x32_bf16(k0, qf[2 * pr + e][0], (f32x4){0.f, 0.f, 0.f, 0.f}, 0, 0, 0);
;                         s[e][kt] = __builtin_amdgcn_mfma_f32_16x16x32_bf16(k1, qf[2 * pr + e][1], s[e][kt], 0, 0, 0); }
;                 } else { s[0][kt] = (f32x4){-1e30f, -1e30f, -1e30f, -1e30f}; s[1][kt] = s[0][kt]; }
.LBB0_1424:
	s_or_b64 exec, exec, s[8:9]
	v_mov_b32_e32 v69, v68
	s_waitcnt lgkmcnt(0)
	v_pk_mul_f32 v[0:1], v[68:69], v[74:75]
	v_pk_mul_f32 v[4:5], v[68:69], v[72:73]
	v_pk_mul_f32 v[0:1], v[132:133], v[0:1]
	v_pk_mul_f32 v[4:5], v[136:137], v[4:5]
	v_pk_mul_f32 v[6:7], v[68:69], v[66:67]
	v_pk_mul_f32 v[0:1], v[0:1], s[78:79] op_sel_hi:[1,0]
	v_pk_mul_f32 v[4:5], v[4:5], s[78:79] op_sel_hi:[1,0]
	s_waitcnt vmcnt(0)
	v_pk_mul_f32 v[6:7], v[138:139], v[6:7]
	v_cvt_pk_bf16_f32 v32, v0, v1
	v_pk_mul_f32 v[6:7], v[6:7], s[78:79] op_sel_hi:[1,0]
	v_pk_mov_b32 v[0:1], v[4:5], v[4:5] op_sel:[1,0]
	v_mov_b32_e32 v93, v92
	v_cvt_pk_bf16_f32 v34, v0, v1
	v_pk_mov_b32 v[0:1], v[6:7], v[6:7] op_sel:[1,0]
	v_pk_mul_f32 v[4:5], v[92:93], v[100:101]
	v_cvt_pk_bf16_f32 v35, v0, v1
	v_pk_mul_f32 v[0:1], v[92:93], v[104:105]
	v_pk_mul_f32 v[4:5], v[136:137], v[4:5]
	v_pk_mul_f32 v[0:1], v[132:133], v[0:1]
	v_pk_mul_f32 v[6:7], v[92:93], v[90:91]
	v_pk_mul_f32 v[0:1], v[0:1], s[78:79] op_sel_hi:[1,0]
	v_pk_mul_f32 v[4:5], v[4:5], s[78:79] op_sel_hi:[1,0]
	v_pk_mul_f32 v[6:7], v[138:139], v[6:7]
	v_cvt_pk_bf16_f32 v40, v0, v1
	v_pk_mul_f32 v[6:7], v[6:7], s[78:79] op_sel_hi:[1,0]
	v_pk_mov_b32 v[0:1], v[4:5], v[4:5] op_sel:[1,0]
	s_nop 0
	v_cvt_pk_bf16_f32 v42, v0, v1
	v_pk_mov_b32 v[0:1], v[6:7], v[6:7] op_sel:[1,0]
	s_barrier
	v_cvt_pk_bf16_f32 v43, v0, v1
	v_mov_b32_e32 v0, v161
	s_ashr_i32 s52, s66, 6
	v_add_u32_e32 v0, 0, v0
	v_add_u32_e32 v0, 0x20170, v0
	s_nop 0
	s_add_i32 s6, s52, s64
	s_ashr_i32 s7, s6, 31
	s_ashr_i32 s16, s66, 8
	s_lshl_b64 s[6:7], s[6:7], 2
	v_readlane_b32 s9, v251, 28
	v_readlane_b32 s8, v251, 29
	s_add_u32 s6, s9, s6
	s_addc_u32 s7, s8, s7
	global_load_dword v0, v161, s[6:7]
	v_pk_mul_f32 v[2:3], v[68:69], v[70:71]
	s_mulk_i32 s16, 0xc0
	v_pk_mul_f32 v[2:3], v[134:135], v[2:3]
	v_or_b32_e32 v1, s16, v179
	v_pk_mul_f32 v[2:3], v[2:3], s[78:79] op_sel_hi:[1,0]
	v_pk_mul_f32 v[8:9], v[64:65], s[78:79] op_sel_hi:[1,0]
	v_cvt_pk_bf16_f32 v33, v2, v3
	v_pk_mul_f32 v[2:3], v[92:93], v[94:95]
	v_pk_mul_f32 v[10:11], v[76:77], s[78:79] op_sel_hi:[1,0]
	v_pk_mul_f32 v[12:13], v[78:79], s[78:79] op_sel_hi:[1,0]
	v_pk_mul_f32 v[14:15], v[80:81], s[78:79] op_sel_hi:[1,0]
	v_pk_mul_f32 v[2:3], v[134:135], v[2:3]
	v_mul_lo_u32 v1, v1, s86
	v_cvt_pk_bf16_f32 v36, v8, v9
	v_cvt_pk_bf16_f32 v37, v10, v11
	v_cvt_pk_bf16_f32 v38, v12, v13
	v_cvt_pk_bf16_f32 v39, v14, v15
	v_pk_mul_f32 v[2:3], v[2:3], s[78:79] op_sel_hi:[1,0]
	v_pk_mul_f32 v[8:9], v[88:89], s[78:79] op_sel_hi:[1,0]
	v_pk_mul_f32 v[10:11], v[106:107], s[78:79] op_sel_hi:[1,0]
	v_pk_mul_f32 v[12:13], v[108:109], s[78:79] op_sel_hi:[1,0]
	v_pk_mul_f32 v[14:15], v[110:111], s[78:79] op_sel_hi:[1,0]
	v_add_lshl_u32 v1, v1, v180, 1
	s_cmp_eq_u32 s15, 0
	v_cvt_pk_bf16_f32 v44, v8, v9
	v_cvt_pk_bf16_f32 v45, v10, v11
	v_cvt_pk_bf16_f32 v46, v12, v13
	v_cvt_pk_bf16_f32 v47, v14, v15
	v_cvt_pk_bf16_f32 v41, v2, v3
	v_mov_b32_e32 v48, 0xf149f2ca
	s_cselect_b64 s[8:9], -1, 0
	s_cmp_lg_u32 s15, 0
	v_add_u32_e32 v127, 0, v1
	v_mov_b32_e32 v52, 0xf149f2ca
	v_mov_b32_e32 v53, 0xf149f2ca
	v_mov_b32_e32 v54, 0xf149f2ca
	v_mov_b32_e32 v55, 0xf149f2ca
	v_mov_b32_e32 v80, 0xf149f2ca
	v_mov_b32_e32 v81, 0xf149f2ca
	v_mov_b32_e32 v82, 0xf149f2ca
	v_mov_b32_e32 v83, 0xf149f2ca
	s_cbranch_scc1 .LBB0_1426
	ds_read_b128 v[2:5], v127
	ds_read_b128 v[6:9], v127 offset:64
	s_waitcnt lgkmcnt(1)
	v_mfma_f32_16x16x32_bf16 v[10:13], v[2:5], v[44:47], 0
	v_mfma_f32_16x16x32_bf16 v[2:5], v[2:5], v[36:39], 0
	s_waitcnt lgkmcnt(0)
	v_mfma_f32_16x16x32_bf16 v[80:83], v[6:9], v[40:43], v[10:13]
	v_mfma_f32_16x16x32_bf16 v[52:55], v[6:9], v[32:35], v[2:5]

; #define LAS __attribute__((address_space(3)))
; __device__ __forceinline__ unsigned pk2(float lo, float hi) { f32x2 v = {lo, hi}; bf16x2_t b = __builtin_convertvector(v, bf16x2_t); return __builtin_bit_cast(unsigned, b); }
; __device__ __forceinline__ void transpose_item(const float* W, int K, int N, bf16_t* WT, const float* gk, int mode, LAS float* scr_, int item, int lane) {
;     LAS unsigned* scr = (LAS unsigned*)scr_;
;     const int nblk = N / 64, kb = item / nblk, nb = item % nblk, k0 = 64 * kb, n0 = 64 * nb;
;     const int sc = (mode == 1) ? (((n0 >> 7) & 1) * DFF + (n0 >> 8) * 128 + (n0 & 127)) : n0;
;     const float* src = W + (size_t)k0 * N + sc + lane;
;     float va[32], vb[32];
; #pragma unroll
;     for (int kp = 0; kp < 32; ++kp) { va[kp] = src[(size_t)(2 * kp) * N]; vb[kp] = src[(size_t)(2 * kp + 1) * N]; }
; #pragma unroll
;     for (int kp = 0; kp < 32; ++kp) {
;         float a = va[kp], b = vb[kp];
;         if (gk) { a *= gk[k0 + 2 * kp]; b *= gk[k0 + 2 * kp + 1]; }
;         scr[kp * 65 + lane] = pk2(a, b);
;     }
.LBB0_1808:
	v_mov_b32_e32 v2, v161
	s_mul_i32 s12, s6, 0x500000
	v_add_u32_e32 v2, 0, v2
	v_add_u32_e32 v2, 0x20158, v2
	s_nop 0
	s_mov_b64 s[30:31], -1
	s_waitcnt lgkmcnt(0)
	v_readlane_b32 s5, v251, 22
	v_mov_b32_e32 v2, v161
	v_readlane_b32 s4, v251, 23
	v_add_u32_e32 v2, 0, v2
	v_add_u32_e32 v2, 0x20150, v2
	s_nop 0
	s_add_u32 s13, s5, s12
	s_mul_hi_i32 s5, s6, 0x500000
	s_addc_u32 s21, s4, s5
	s_mul_hi_i32 s12, s34, 0x66666667
	v_readlane_b32 s4, v251, 20
	v_readlane_b32 s5, v251, 21
	s_add_u32 s40, s4, s10
	s_addc_u32 s41, s5, s11
	s_lshr_b32 s18, s12, 31
	s_ashr_i32 s12, s12, 3
	s_add_i32 s24, s12, s18
	s_lshl_b32 s18, s24, 6
	s_mul_i32 s12, s24, 0xfffffb00
	s_add_i32 s12, s35, s12
	s_ashr_i32 s19, s18, 31
	s_mul_i32 s24, s24, 0x50000
	s_mul_hi_i32 s25, s18, 0x1400
	s_add_u32 s26, s13, s24
	s_addc_u32 s21, s21, s25
	s_ashr_i32 s13, s12, 31
	s_lshl_b64 s[24:25], s[12:13], 2
	s_add_u32 s24, s26, s24
	s_addc_u32 s25, s21, s25
	s_waitcnt vmcnt(9)
	v_lshl_add_u64 v[66:67], s[24:25], 0, v[160:161]
	s_movk_i32 s13, 0x1000
	v_add_co_u32_e32 v2, vcc, s13, v66
	s_movk_i32 s13, 0x3000
	s_nop 0
	v_addc_co_u32_e32 v3, vcc, 0, v67, vcc
	global_load_dword v63, v[2:3], off offset:1024
	v_add_co_u32_e32 v2, vcc, s79, v66
	global_load_dword v62, v160, s[24:25]
	s_nop 0
	v_addc_co_u32_e32 v3, vcc, 0, v67, vcc
	global_load_dword v64, v[2:3], off offset:2048
	v_add_co_u32_e32 v2, vcc, s13, v66
	s_movk_i32 s13, 0x5000
	s_nop 0
	v_addc_co_u32_e32 v3, vcc, 0, v67, vcc
	global_load_dword v65, v[2:3], off offset:3072
	v_add_co_u32_e32 v2, vcc, s13, v66
	s_movk_i32 s13, 0x7000
	s_nop 0
	v_addc_co_u32_e32 v3, vcc, 0, v67, vcc
	global_load_dword v54, v[2:3], off
	v_add_co_u32_e32 v2, vcc, s80, v66
	s_cmp_lg_u64 s[4:5], 0
	s_nop 0
	v_addc_co_u32_e32 v3, vcc, 0, v67, vcc
	global_load_dword v55, v[2:3], off offset:1024
	v_add_co_u32_e32 v2, vcc, s13, v66
	s_mov_b32 s13, 0xb000
	s_nop 0
	v_addc_co_u32_e32 v3, vcc, 0, v67, vcc
	global_load_dword v60, v[2:3], off offset:2048
	v_add_co_u32_e32 v2, vcc, s70, v66
	s_cselect_b64 s[24:25], -1, 0
	s_nop 0
	v_addc_co_u32_e32 v3, vcc, 0, v67, vcc
	global_load_dword v61, v[2:3], off offset:3072
	v_add_co_u32_e32 v2, vcc, s71, v66
	s_cmp_eq_u64 s[4:5], 0
	s_nop 0
	v_addc_co_u32_e32 v3, vcc, 0, v67, vcc
	global_load_dword v56, v[2:3], off
	v_add_co_u32_e32 v2, vcc, s13, v66
	s_mov_b32 s13, 0xd000
	s_nop 0
	v_addc_co_u32_e32 v3, vcc, 0, v67, vcc
	global_load_dword v57, v[2:3], off offset:1024
	v_add_co_u32_e32 v2, vcc, s91, v66
	s_nop 1
	v_addc_co_u32_e32 v3, vcc, 0, v67, vcc
	global_load_dword v58, v[2:3], off offset:2048
	v_add_co_u32_e32 v2, vcc, s13, v66
	s_mov_b32 s13, 0xf000
	s_nop 0
	v_addc_co_u32_e32 v3, vcc, 0, v67, vcc
	global_load_dword v59, v[2:3], off offset:3072
	v_add_co_u32_e32 v2, vcc, s13, v66
	s_mov_b32 s13, 0x11000
	s_nop 0
	v_addc_co_u32_e32 v3, vcc, 0, v67, vcc
	global_load_dword v46, v[2:3], off
	v_add_co_u32_e32 v2, vcc, s37, v66
	s_nop 1
	v_addc_co_u32_e32 v3, vcc, 0, v67, vcc
	global_load_dword v47, v[2:3], off offset:1024
	v_add_co_u32_e32 v2, vcc, s13, v66
	s_mov_b32 s13, 0x15000
	s_nop 0
	v_addc_co_u32_e32 v3, vcc, 0, v67, vcc
	global_load_dword v52, v[2:3], off offset:2048
	v_add_co_u32_e32 v2, vcc, s94, v66
	s_nop 1
	v_addc_co_u32_e32 v3, vcc, 0, v67, vcc
	global_load_dword v53, v[2:3], off offset:3072
	v_add_co_u32_e32 v2, vcc, s46, v66
	s_nop 1
	v_addc_co_u32_e32 v3, vcc, 0, v67, vcc
	global_load_dword v48, v[2:3], off
	v_add_co_u32_e32 v2, vcc, s13, v66
	s_mov_b32 s13, 0x17000
	s_nop 0
	v_addc_co_u32_e32 v3, vcc, 0, v67, vcc
	global_load_dword v49, v[2:3], off offset:1024
	v_add_co_u32_e32 v2, vcc, s47, v66
	s_nop 1
	v_addc_co_u32_e32 v3, vcc, 0, v67, vcc
	global_load_dword v50, v[2:3], off offset:2048
	v_add_co_u32_e32 v2, vcc, s13, v66
	s_mov_b32 s13, 0x19000
	s_nop 0
	v_addc_co_u32_e32 v3, vcc, 0, v67, vcc
	global_load_dword v51, v[2:3], off offset:3072
	v_add_co_u32_e32 v2, vcc, s13, v66
	s_mov_b32 s13, 0x1b000
	s_nop 0
	v_addc_co_u32_e32 v3, vcc, 0, v67, vcc
	global_load_dword v38, v[2:3], off
	v_add_co_u32_e32 v2, vcc, s81, v66
	s_nop 1
	v_addc_co_u32_e32 v3, vcc, 0, v67, vcc
	global_load_dword v39, v[2:3], off offset:1024
	v_add_co_u32_e32 v2, vcc, s13, v66
	s_mov_b32 s13, 0x1f000
	s_nop 0
	v_addc_co_u32_e32 v3, vcc, 0, v67, vcc
	global_load_dword v44, v[2:3], off offset:2048
	v_add_co_u32_e32 v2, vcc, s83, v66
	s_nop 1
	v_addc_co_u32_e32 v3, vcc, 0, v67, vcc
	global_load_dword v45, v[2:3], off offset:3072
	v_add_co_u32_e32 v2, vcc, s27, v66
	s_nop 1
	v_addc_co_u32_e32 v3, vcc, 0, v67, vcc
	global_load_dword v40, v[2:3], off
	v_add_co_u32_e32 v2, vcc, s13, v66
	s_mov_b32 s13, 0x21000
	s_nop 0
	v_addc_co_u32_e32 v3, vcc, 0, v67, vcc
	global_load_dword v41, v[2:3], off offset:1024
	v_add_co_u32_e32 v2, vcc, s50, v66
	s_nop 1
	v_addc_co_u32_e32 v3, vcc, 0, v67, vcc
	global_load_dword v42, v[2:3], off offset:2048
	v_add_co_u32_e32 v2, vcc, s13, v66
	s_mov_b32 s13, 0x23000
	s_nop 0
	v_addc_co_u32_e32 v3, vcc, 0, v67, vcc
	global_load_dword v43, v[2:3], off offset:3072
	v_add_co_u32_e32 v2, vcc, s13, v66
	s_mov_b32 s13, 0x25000
	s_nop 0
	v_addc_co_u32_e32 v3, vcc, 0, v67, vcc
	global_load_dword v30, v[2:3], off
	v_add_co_u32_e32 v2, vcc, s28, v66
	s_nop 1
; #define LAS __attribute__((address_space(3)))
; __device__ __forceinline__ unsigned pk2(float lo, float hi) { f32x2 v = {lo, hi}; bf16x2_t b = __builtin_convertvector(v, bf16x2_t); return __builtin_bit_cast(unsigned, b); }
; __device__ __forceinline__ void transpose_item(const float* W, int K, int N, bf16_t* WT, const float* gk, int mode, LAS float* scr_, int item, int lane) {
;     LAS unsigned* scr = (LAS unsigned*)scr_;
;     const int nblk = N / 64, kb = item / nblk, nb = item % nblk, k0 = 64 * kb, n0 = 64 * nb;
;     const int sc = (mode == 1) ? (((n0 >> 7) & 1) * DFF + (n0 >> 8) * 128 + (n0 & 127)) : n0;
;     const float* src = W + (size_t)k0 * N + sc + lane;
;     float va[32], vb[32];
; #pragma unroll
;     for (int kp = 0; kp < 32; ++kp) { va[kp] = src[(size_t)(2 * kp) * N]; vb[kp] = src[(size_t)(2 * kp + 1) * N]; }
; #pragma unroll
;     for (int kp = 0; kp < 32; ++kp) {
;         float a = va[kp], b = vb[kp];
;         if (gk) { a *= gk[k0 + 2 * kp]; b *= gk[k0 + 2 * kp + 1]; }
;         scr[kp * 65 + lane] = pk2(a, b);
;     }
	v_addc_co_u32_e32 v3, vcc, 0, v67, vcc
	global_load_dword v31, v[2:3], off offset:1024
	v_add_co_u32_e32 v2, vcc, s13, v66
	s_mov_b32 s13, 0x29000
	s_nop 0
	v_addc_co_u32_e32 v3, vcc, 0, v67, vcc
	global_load_dword v36, v[2:3], off offset:2048
	v_add_co_u32_e32 v2, vcc, s73, v66
	s_nop 1
	v_addc_co_u32_e32 v3, vcc, 0, v67, vcc
	global_load_dword v37, v[2:3], off offset:3072
	v_add_co_u32_e32 v2, vcc, s1, v66
	s_nop 1
	v_addc_co_u32_e32 v3, vcc, 0, v67, vcc
	global_load_dword v32, v[2:3], off
	v_add_co_u32_e32 v2, vcc, s13, v66
	s_mov_b32 s13, 0x2b000
	s_nop 0
	v_addc_co_u32_e32 v3, vcc, 0, v67, vcc
	global_load_dword v33, v[2:3], off offset:1024
	v_add_co_u32_e32 v2, vcc, s72, v66
	s_nop 1
	v_addc_co_u32_e32 v3, vcc, 0, v67, vcc
	global_load_dword v34, v[2:3], off offset:2048
	v_add_co_u32_e32 v2, vcc, s13, v66
	s_mov_b32 s13, 0x2d000
	s_nop 0
	v_addc_co_u32_e32 v3, vcc, 0, v67, vcc
	global_load_dword v35, v[2:3], off offset:3072
	v_add_co_u32_e32 v2, vcc, s13, v66
	s_mov_b32 s13, 0x2f000
	s_nop 0
	v_addc_co_u32_e32 v3, vcc, 0, v67, vcc
	global_load_dword v22, v[2:3], off
	v_add_co_u32_e32 v2, vcc, s33, v66
	s_nop 1
	v_addc_co_u32_e32 v3, vcc, 0, v67, vcc
	global_load_dword v23, v[2:3], off offset:1024
	v_add_co_u32_e32 v2, vcc, s13, v66
	s_mov_b32 s13, 0x33000
	s_nop 0
	v_addc_co_u32_e32 v3, vcc, 0, v67, vcc
	global_load_dword v28, v[2:3], off offset:2048
	v_add_co_u32_e32 v2, vcc, s22, v66
	s_nop 1
	v_addc_co_u32_e32 v3, vcc, 0, v67, vcc
	global_load_dword v29, v[2:3], off offset:3072
	v_add_co_u32_e32 v2, vcc, s38, v66
	s_nop 1
	v_addc_co_u32_e32 v3, vcc, 0, v67, vcc
	global_load_dword v24, v[2:3], off
	v_add_co_u32_e32 v2, vcc, s13, v66
	s_mov_b32 s13, 0x35000
	s_nop 0
	v_addc_co_u32_e32 v3, vcc, 0, v67, vcc
	global_load_dword v25, v[2:3], off offset:1024
	v_add_co_u32_e32 v2, vcc, s39, v66
	s_nop 1
	v_addc_co_u32_e32 v3, vcc, 0, v67, vcc
	global_load_dword v26, v[2:3], off offset:2048
	v_add_co_u32_e32 v2, vcc, s13, v66
	s_mov_b32 s13, 0x37000
	s_nop 0
	v_addc_co_u32_e32 v3, vcc, 0, v67, vcc
	global_load_dword v27, v[2:3], off offset:3072
	v_add_co_u32_e32 v2, vcc, s13, v66
	s_mov_b32 s13, 0x39000
	s_nop 0
	v_addc_co_u32_e32 v3, vcc, 0, v67, vcc
	global_load_dword v14, v[2:3], off
	v_add_co_u32_e32 v2, vcc, s69, v66
	s_nop 1
	v_addc_co_u32_e32 v3, vcc, 0, v67, vcc
	global_load_dword v15, v[2:3], off offset:1024
	v_add_co_u32_e32 v2, vcc, s13, v66
	s_mov_b32 s13, 0x3d000
	s_nop 0
	v_addc_co_u32_e32 v3, vcc, 0, v67, vcc
	global_load_dword v20, v[2:3], off offset:2048
	v_add_co_u32_e32 v2, vcc, s87, v66
	s_nop 1
	v_addc_co_u32_e32 v3, vcc, 0, v67, vcc
	global_load_dword v21, v[2:3], off offset:3072
	v_add_co_u32_e32 v2, vcc, s90, v66
	s_nop 1
	v_addc_co_u32_e32 v3, vcc, 0, v67, vcc
	global_load_dword v16, v[2:3], off
	v_add_co_u32_e32 v2, vcc, s13, v66
	s_mov_b32 s13, 0x41000
	s_nop 0
	v_addc_co_u32_e32 v3, vcc, 0, v67, vcc
	global_load_dword v17, v[2:3], off offset:1024
	v_add_co_u32_e32 v2, vcc, s51, v66
	s_nop 1
	v_addc_co_u32_e32 v3, vcc, 0, v67, vcc
	global_load_dword v18, v[2:3], off offset:2048
	v_add_co_u32_e32 v2, vcc, s52, v66
	s_nop 1
	v_addc_co_u32_e32 v3, vcc, 0, v67, vcc
	global_load_dword v19, v[2:3], off offset:3072
	v_add_co_u32_e32 v2, vcc, s13, v66
	s_mov_b32 s13, 0x43000
	s_nop 0
	v_addc_co_u32_e32 v3, vcc, 0, v67, vcc
	global_load_dword v4, v[2:3], off
	v_add_co_u32_e32 v2, vcc, s93, v66
	s_nop 1
	v_addc_co_u32_e32 v3, vcc, 0, v67, vcc
	global_load_dword v5, v[2:3], off offset:1024
	v_add_co_u32_e32 v2, vcc, s13, v66
	s_mov_b32 s13, 0x44000
	s_nop 0
	v_addc_co_u32_e32 v3, vcc, 0, v67, vcc
	global_load_dword v10, v[2:3], off offset:2048
	v_add_co_u32_e32 v2, vcc, s13, v66
	s_mov_b32 s13, 0x46000
	s_nop 0
	v_addc_co_u32_e32 v3, vcc, 0, v67, vcc
	global_load_dword v11, v[2:3], off offset:3072
	v_add_co_u32_e32 v2, vcc, s13, v66
	s_mov_b32 s13, 0x47000
	s_nop 0
	v_addc_co_u32_e32 v3, vcc, 0, v67, vcc
	global_load_dword v6, v[2:3], off
	v_add_co_u32_e32 v2, vcc, s13, v66
	s_mov_b32 s13, 0x48000
	s_nop 0
	v_addc_co_u32_e32 v3, vcc, 0, v67, vcc
	global_load_dword v7, v[2:3], off offset:1024
	v_add_co_u32_e32 v2, vcc, s13, v66
	s_mov_b32 s13, 0x49000
	s_nop 0
	v_addc_co_u32_e32 v3, vcc, 0, v67, vcc
	global_load_dword v12, v[2:3], off offset:2048
	v_add_co_u32_e32 v2, vcc, s13, v66
	s_mov_b32 s13, 0x4b000
	s_nop 0
	v_addc_co_u32_e32 v3, vcc, 0, v67, vcc
	global_load_dword v13, v[2:3], off offset:3072
	v_add_co_u32_e32 v2, vcc, s13, v66
	s_mov_b32 s13, 0x4c000
	s_nop 0
	v_addc_co_u32_e32 v3, vcc, 0, v67, vcc
	v_add_co_u32_e32 v8, vcc, s13, v66
	global_load_dword v2, v[2:3], off
	s_nop 0
	v_addc_co_u32_e32 v9, vcc, 0, v67, vcc
	global_load_dword v3, v[8:9], off offset:1024
	v_add_co_u32_e32 v8, vcc, 0x4d000, v66
	s_nop 1
	v_addc_co_u32_e32 v9, vcc, 0, v67, vcc
	v_add_co_u32_e32 v66, vcc, 0x4e000, v66
	global_load_dword v8, v[8:9], off offset:2048
	s_nop 0
	v_addc_co_u32_e32 v67, vcc, 0, v67, vcc
	global_load_dword v9, v[66:67], off offset:3072
	s_cbranch_scc1 .LBB0_1810
	s_lshl_b64 s[4:5], s[18:19], 2
	s_add_u32 s4, s40, s4
	s_addc_u32 s5, s41, s5
	global_load_dwordx4 v[66:69], v161, s[4:5]
	s_mov_b64 s[30:31], 0
	s_waitcnt vmcnt(0)
	v_pk_mul_f32 v[66:67], v[62:63], v[66:67]
	v_pk_mul_f32 v[68:69], v[64:65], v[68:69]

; #define PIN(i) ((const float*)ldq_(L, (i)))
; __device__ __forceinline__ unsigned pk2(float lo, float hi) { f32x2 v = {lo, hi}; bf16x2_t b = __builtin_convertvector(v, bf16x2_t); return __builtin_bit_cast(unsigned, b); }
; __device__ __forceinline__ void prep(const Params& p, LAS unsigned char* L, int wv, int vb, int nvb, int l, int mask) {
;     ...
;     if (mask & PM_POOL) {
;         for (int t = gt; t < 4 * 128 * 16; t += NGT) {
;             const int ko = t & 15, n = (t >> 4) & 127, g = (t >> 11) & 3;
;             const float* src = PIN(I_WPOOL) + ((size_t)(l * 4 + g) * 128 + 8 * ko) * 128 + n; const float sc = PIN(I_PSCALE)[l * 512 + g * 128 + n];
;             u32x4 o; o.x = pk2(src[0] * sc, src[128] * sc); o.y = pk2(src[256] * sc, src[384] * sc); o.z = pk2(src[512] * sc, src[640] * sc); o.w = pk2(src[768] * sc, src[896] * sc);
;             *(u32x4*)((bf16_t*)(wl + WL_POOL) + ((size_t)g * 128 + n) * 128 + 8 * ko) = o;
;         }
;     }
.LBB0_1874:
	v_mov_b32_e32 v4, v161
	v_add_u32_e32 v2, 0x1c000, v2
	v_add_u32_e32 v4, 0, v4
	v_add_u32_e32 v4, 0x20178, v4
	s_nop 0
	v_bfe_u32 v14, v2, 11, 2
	v_and_b32_e32 v15, 0x78, v3
	v_bfe_u32 v11, v2, 4, 7
	v_lshlrev_b32_e32 v160, 9, v15
	s_waitcnt lgkmcnt(0)
	v_readlane_b32 s18, v251, 30
	v_or_b32_e32 v4, s12, v14
	v_readlane_b32 s19, v251, 31
	v_ashrrev_i32_e32 v5, 31, v4
	v_lshlrev_b64 v[4:5], 16, v[4:5]
	v_lshl_add_u64 v[4:5], s[18:19], 0, v[4:5]
	v_lshl_add_u64 v[4:5], v[4:5], 0, v[160:161]
	v_lshlrev_b32_e32 v160, 2, v11
	v_lshl_add_u64 v[8:9], v[4:5], 0, v[160:161]
	v_mov_b32_e32 v4, v161
	v_lshlrev_b32_e32 v6, 7, v14
	v_add_u32_e32 v4, 0, v4
	v_add_u32_e32 v4, 0x20180, v4
	s_nop 0
	v_or3_b32 v6, v6, s13, v11
	v_ashrrev_i32_e32 v7, 31, v6
	v_cmp_lt_i32_e32 vcc, s21, v2
	v_add_u32_e32 v3, 0xe0000, v3
	v_readlane_b32 s16, v251, 33
	v_readlane_b32 s18, v251, 32
	s_or_b64 s[10:11], vcc, s[10:11]
	v_mov_b32_e32 v5, s16
	v_mov_b32_e32 v4, s18
	v_lshl_add_u64 v[4:5], v[6:7], 2, v[4:5]
	global_load_dword v10, v[4:5], off
	s_nop 0
	global_load_dword v4, v[8:9], off
	global_load_dword v5, v[8:9], off offset:512
	global_load_dword v6, v[8:9], off offset:1024
	global_load_dword v7, v[8:9], off offset:1536
	s_waitcnt vmcnt(2)
	v_pk_mul_f32 v[4:5], v[10:11], v[4:5] op_sel_hi:[0,1]
	s_waitcnt vmcnt(0)
	v_pk_mul_f32 v[6:7], v[10:11], v[6:7] op_sel_hi:[0,1]
	v_cvt_pk_bf16_f32 v4, v4, v5
	v_cvt_pk_bf16_f32 v5, v6, v7
	global_load_dword v6, v[8:9], off offset:2048
	global_load_dword v7, v[8:9], off offset:2560
	global_load_dword v12, v[8:9], off offset:3072
	global_load_dword v13, v[8:9], off offset:3584
	s_waitcnt vmcnt(2)
	v_pk_mul_f32 v[6:7], v[10:11], v[6:7] op_sel_hi:[0,1]
	s_waitcnt vmcnt(0)
	v_pk_mul_f32 v[8:9], v[10:11], v[12:13] op_sel_hi:[0,1]
	v_cvt_pk_bf16_f32 v6, v6, v7
	v_cvt_pk_bf16_f32 v7, v8, v9
	v_lshlrev_b32_e32 v8, 8, v11
	v_lshl_or_b32 v160, v14, 15, v8
	v_lshl_add_u64 v[8:9], s[8:9], 0, v[160:161]
	v_lshlrev_b32_e32 v160, 1, v15
	v_lshl_add_u64 v[8:9], v[8:9], 0, v[160:161]
	global_store_dwordx4 v[8:9], v[4:7], off
	s_andn2_b64 exec, exec, s[10:11]
	s_cbranch_execnz .LBB0_1874

; #define PG8_WAIT_V(n) asm volatile("s_waitcnt vmcnt(" #n ")" ::: "memory")
; template <class Epi, class Sched, bool ALIGN_EPI = false, bool SP2 = false>
; __device__ __forceinline__ void gemm_phase(PG8_LAS unsigned char* lds, const Gemm g, const Sched& S, const Epi& E, int wv) {
;     ...
;     const int tid = tid_, wid = __builtin_amdgcn_readfirstlane(tid >> 6), lane = tid & 63, wr = wid >> 2, wc = wid & 3, fr = lane & 15, fq = lane >> 4;
;     const int K = g.K, nt = K / BK;
;     unsigned voffA[2], voffB[2];
; #pragma unroll
;     for (int i = 0; i < 2; ++i) { int R, C; stage_rc(tid * 16 + i * 8192, R, C); const int Rb = Epi::PERM ? ((R & ~31) + perm32(R & 31)) : R;
;         voffA[i] = (unsigned)(R * K + C) * 2u; voffB[i] = (unsigned)(Rb * K + C) * 2u; }
;     const size_t kstep = (size_t)(BK * 2);
;     const size_t hstep = (size_t)HALF * K * 2;
;     const size_t tstep = 2 * hstep;
;     const unsigned ldsw = (unsigned)wid * 1024u;
;     const int aoff = lds_byte(wr * 64 + fr, fq * 8), boff = lds_byte(wc * 32 + fr, fq * 8);
;     ...
;     Unit cur, nxt; int ui = 0;
;     if (!S.next(0, cur)) return;
;     f32x4 acc[2][2][4][2];
; #pragma unroll
;     for (int a = 0; a < 2; ++a)
; #pragma unroll
;         for (int b = 0; b < 2; ++b)
; #pragma unroll
;             for (int m = 0; m < 4; ++m)
; #pragma unroll
;                 for (int n = 0; n < 2; ++n) acc[a][b][m][n] = (f32x4){0.f, 0.f, 0.f, 0.f};
;     bf16x8 At[4][2], B0[2][2], B1[2][2];
;     const char* cA = (const char*)g.A + (size_t)cur.pm * tstep; const char* cB = (const char*)g.Bt + (size_t)cur.pn * tstep;
;     S.a_ready(cur);
;     if constexpr (SP2) {
;         PG8_STAGE(PG8_SB(0, 0), cB, voffB); PG8_STAGE(PG8_SB(0, 1), cB + hstep, voffB); PG8_STAGE(PG8_SA(0, 0), cA, voffA); PG8_STAGE(PG8_SA(0, 1), cA + hstep, voffA);
;         if (wr == 1) PG8_BAR;
;         PG8_WAIT_V(2); PG8_BAR;
;         PG8_STAGE(PG8_SB(1, 0), cB + kstep, voffB); PG8_STAGE(PG8_SA(1, 0), cA + kstep, voffA); PG8_STAGE(PG8_SB(1, 1), cB + hstep + kstep, voffB);
; __global__ void __launch_bounds__(512, 2) hymba_fwd(Params p) {
;     ...
;         { PHASE_VARS pg8::Gemm g{mixb, (const bf16_t*)(wl + WL_OUT), MT, DM, DM}; pg8::StaticOrder S; S.init(MT, DM, G, c);
;           EpiResid<0> E{xb, xb, nullptr, sq + 2 * MT, 1.0f, nullptr, nullptr};
;           pg8::gemm_phase<EpiResid<0>, pg8::StaticOrder, true, true>(L, g, S, E, wv); }
.LBB0_1947:
	s_or_b64 exec, exec, s[4:5]
	v_readlane_b32 s10, v250, 0
	s_mov_b64 s[4:5], 0
	s_waitcnt lgkmcnt(0)
	v_mov_b32_e32 v0, v161
	s_barrier
	v_readlane_b32 s8, v250, 42
	v_add_u32_e32 v0, 0, v0
	v_add_u32_e32 v0, 0x201c0, v0
	s_nop 0
	v_mov_b32_e32 v14, v183
	v_readlane_b32 s9, v250, 43
	s_and_b64 vcc, exec, s[8:9]
	v_readlane_b32 s7, v251, 48
	v_mov_b32_e32 v0, v161
	v_readlane_b32 s6, v251, 49
	v_add_u32_e32 v0, 0, v0
	v_add_u32_e32 v0, 0x201c8, v0
	ds_read_b64 v[0:1], v0
	s_nop 0
	v_readfirstlane_b32 s12, v14
	s_cbranch_vccnz .LBB0_1979
	s_waitcnt lgkmcnt(0)
	v_lshlrev_b32_e32 v0, 4, v14
	v_add_u32_e32 v1, 0x2000, v0
	v_ashrrev_i32_e32 v2, 31, v1
	v_lshrrev_b32_e32 v2, 22, v2
	v_add_u32_e32 v2, v1, v2
	v_ashrrev_i32_e32 v8, 10, v2
	v_mul_i32_i24_e32 v2, 0x400, v8
	v_sub_u32_e32 v1, v1, v2
	v_lshrrev_b32_e32 v2, 4, v1
	v_bitop3_b32 v1, v2, v1, 32 bitop3:0x6c
	s_add_u32 s8, s7, s4
	v_ashrrev_i32_e32 v2, 31, v1
	s_addc_u32 s9, s6, s5
	v_lshrrev_b32_e32 v2, 26, v2
	s_add_u32 s14, s8, 0x17b00000
	v_add_u32_e32 v2, v1, v2
	v_lshlrev_b32_e32 v3, 3, v8
	s_addc_u32 s15, s9, 0
	s_mul_i32 s5, s10, 0x2900000
	v_ashrrev_i32_e32 v9, 6, v2
	v_and_b32_e32 v3, -16, v3
	s_mul_hi_i32 s4, s10, 0x2900000
	s_add_u32 s11, s8, s5
	v_add_u32_e32 v3, v9, v3
	s_addc_u32 s19, s9, s4
	v_and_b32_e32 v4, 3, v9
	s_mov_b32 s4, 0x1fffe0
	v_lshrrev_b32_e32 v5, 2, v3
	v_lshlrev_b32_e32 v6, 1, v3
	v_and_b32_e32 v2, 0xc0, v2
	v_and_or_b32 v4, v3, s4, v4
	v_and_b32_e32 v5, 4, v5
	v_and_b32_e32 v6, 24, v6
	v_sub_u32_e32 v1, v1, v2
	v_or3_b32 v4, v4, v5, v6
	v_lshlrev_b32_e32 v5, 5, v8
	v_ashrrev_i16_sdwa v1, v193, sext(v1) dst_sel:DWORD dst_unused:UNUSED_PAD src0_sel:DWORD src1_sel:BYTE_0
	v_and_b32_e32 v5, 32, v5
	v_bfe_i32 v10, v1, 0, 16
	v_add_lshl_u32 v1, v5, v10, 1
	v_lshl_add_u32 v152, v4, 11, v1
	v_lshl_add_u32 v154, v3, 11, v1
	v_bfe_i32 v1, v14, 27, 1
	v_lshrrev_b32_e32 v1, 22, v1
	v_add_u32_e32 v1, v0, v1
	v_and_b32_e32 v1, 0xfffffc00, v1
	v_sub_u32_e32 v0, v0, v1
	v_lshrrev_b32_e32 v1, 4, v0
	v_ashrrev_i32_e32 v2, 31, v14
	v_bitop3_b32 v0, v1, v0, 32 bitop3:0x6c
	v_lshrrev_b32_e32 v2, 26, v2
	v_ashrrev_i32_e32 v1, 31, v0
	v_add_u32_e32 v2, v14, v2
	v_lshrrev_b32_e32 v1, 26, v1
	v_ashrrev_i32_e32 v12, 6, v2
	v_add_u32_e32 v1, v0, v1
	v_lshlrev_b32_e32 v2, 3, v12
	v_ashrrev_i32_e32 v11, 6, v1
	v_and_b32_e32 v2, -16, v2
	v_add_u32_e32 v2, v11, v2
	s_add_u32 s16, s11, 0x1300000
	v_and_b32_e32 v3, 3, v11
	v_lshrrev_b32_e32 v4, 2, v2
	v_lshlrev_b32_e32 v5, 1, v2
	v_and_b32_e32 v1, 0xc0, v1
	s_addc_u32 s29, s19, 0
	s_ashr_i32 s13, s12, 6
	v_and_or_b32 v3, v2, s4, v3
	v_and_b32_e32 v4, 4, v4
	v_and_b32_e32 v5, 24, v5
	v_sub_u32_e32 v0, v0, v1
	s_ashr_i32 s18, s12, 8
	s_lshl_b32 s30, s13, 10
	v_or3_b32 v3, v3, v4, v5
	v_lshlrev_b32_e32 v4, 5, v12
	v_ashrrev_i16_sdwa v0, v193, sext(v0) dst_sel:DWORD dst_unused:UNUSED_PAD src0_sel:DWORD src1_sel:BYTE_0
	v_readlane_b32 s4, v250, 15
	v_and_b32_e32 v4, 32, v4
	v_bfe_i32 v13, v0, 0, 16
	v_readlane_b32 s5, v250, 16
	s_add_u32 s48, s16, s4
	v_add_lshl_u32 v0, v4, v13, 1
	s_addc_u32 s49, s29, s5
	s_add_i32 s31, s30, 0
	v_lshl_add_u32 v160, v3, 11, v0
	s_add_i32 m0, s31, 0x10000
	v_lshl_add_u32 v156, v2, 11, v0
	global_load_lds_dwordx4 v160, s[48:49]
	s_add_i32 m0, s31, 0x12000
	s_add_u32 s4, s48, 0x40000
	global_load_lds_dwordx4 v152, s[48:49]
	s_addc_u32 s5, s49, 0
	s_add_i32 m0, s31, 0x14000
	v_mov_b32_e32 v153, v161
	global_load_lds_dwordx4 v160, s[4:5]
	s_add_i32 m0, s31, 0x16000
	v_mov_b32_e32 v157, v161
	global_load_lds_dwordx4 v152, s[4:5]
	v_readlane_b32 s4, v250, 29
	v_readlane_b32 s5, v250, 30
	s_add_u32 s4, s14, s4
	s_addc_u32 s5, s15, s5
	s_add_i32 s52, s31, 0x2000
	s_mov_b32 m0, s31
	s_add_u32 s6, s4, 0x40000
	global_load_lds_dwordx4 v156, s[4:5]
	s_mov_b32 m0, s52
	s_addc_u32 s7, s5, 0
	s_add_i32 s53, s31, 0x4000
	global_load_lds_dwordx4 v154, s[4:5]
	s_mov_b32 m0, s53
	s_add_i32 s54, s31, 0x6000
	global_load_lds_dwordx4 v156, s[6:7]
	s_mov_b32 m0, s54
	v_mov_b32_e32 v155, v161
	global_load_lds_dwordx4 v154, s[6:7]
	s_cmp_eq_u32 s18, 1
	v_lshl_add_u64 v[6:7], s[48:49], 0, v[160:161]
	v_lshl_add_u64 v[4:5], s[48:49], 0, v[152:153]
	v_lshl_add_u64 v[0:1], s[4:5], 0, v[156:157]
	s_cselect_b64 s[6:7], -1, 0
	s_cmp_lg_u32 s18, 1
	v_lshl_add_u64 v[2:3], s[4:5], 0, v[154:155]
	s_cbranch_scc1 .LBB0_1950
	s_barrier

; __device__ __forceinline__ int tid_of(int wv) { return wv * 64 + (int)__builtin_amdgcn_mbcnt_hi(~0u, __builtin_amdgcn_mbcnt_lo(~0u, 0u)); }
; #define LAS __attribute__((address_space(3)))
; #define PIN(i) ((const float*)ldq_(L, (i)))
; #define PREP_CONV(bit, SRC, Kd, Nd, DST, GK, MODE) if (mask & (bit)) { for (int it = gw; it < ((Kd) / 64) * ((Nd) / 64); it += NGW) transpose_item((SRC), (Kd), (Nd), (bf16_t*)(wl + (DST)), (GK), (MODE), scr, it, lane); }
; __device__ __forceinline__ void prep(const Params& p, LAS unsigned char* L, int wv, int vb, int nvb, int l, int mask) {
;     int tid_ = tid_of(wv); asm volatile("" : "+v"(tid_));
;     const int tid = tid_, lane = tid & 63, wave = __builtin_amdgcn_readfirstlane(tid >> 6);
;     const int gw = vb * 8 + wave, NGW = nvb * 8; const int gt = vb * 512 + tid, NGT = nvb * 512;
;     LAS float* scr = (LAS float*)(L + wave * 16384);
;     unsigned char* ws = PWS; unsigned char* wl = ws + WS_W + (size_t)l * WL_STRIDE;
;     ...
;     PREP_CONV(PM_FFA_IN, PIN(I_WFFA_IN) + (size_t)l * DM * NFF2, DM, NFF2, WL_FFA_IN, PIN(I_NFFA) + l * DM, 1)
;     PREP_CONV(PM_FFA_OUT, PIN(I_WFFA_OUT) + (size_t)l * DFF * DM, DFF, DM, WL_FFA_OUT, nullptr, 0)
;     PREP_CONV(PM_WIN, PIN(I_WIN) + (size_t)l * DM * NIN, DM, NIN, WL_IN, PIN(I_NMIX) + l * DM, 0)
;     PREP_CONV(PM_WOUT, PIN(I_WOUT) + (size_t)l * DM * DM, DM, DM, WL_OUT, nullptr, 0)
;     PREP_CONV(PM_FFB_IN, PIN(I_WFFB_IN) + (size_t)l * DM * NFF2, DM, NFF2, WL_FFB_IN, PIN(I_NFFB) + l * DM, 1)
.LBB0_1979:
	s_mov_b32 s6, s20
	s_mov_b32 s4, s60
	s_mov_b32 s5, s2
	s_cmpk_eq_i32 s6, 0x100
	s_cselect_b64 s[6:7], -1, 0
	s_cmp_gt_i32 s5, 31
	s_cselect_b64 s[8:9], -1, 0
	s_and_b64 s[6:7], s[6:7], s[8:9]
	s_cmp_lt_i32 s4, 2
	s_cselect_b64 s[8:9], -1, 0
	s_and_b64 s[6:7], s[6:7], s[8:9]
	s_andn2_b64 vcc, exec, s[6:7]
	s_cbranch_vccnz .LBB0_2047
	s_waitcnt lgkmcnt(0)
	v_mov_b32_e32 v0, v183
	v_mov_b32_e32 v1, v161
	s_lshl_b32 s5, s5, 3
	v_add_u32_e32 v1, 0, v1
	v_add_u32_e32 v1, 0x201c0, v1
	s_nop 0
	v_readfirstlane_b32 s6, v0
	s_ashr_i32 s6, s6, 6
	s_add_i32 s5, s5, s6
	s_add_i32 s14, s5, 0xffffff00
	v_readlane_b32 s5, v251, 49
	s_cmpk_gt_i32 s14, 0x57f
	v_readlane_b32 s7, v251, 48
	s_cbranch_scc1 .LBB0_2047
	s_mul_i32 s8, s4, 0x2900000
	s_mul_hi_i32 s9, s4, 0x2900000
	s_add_u32 s8, s7, s8
	v_and_b32_e32 v1, 7, v0
	s_addc_u32 s9, s5, s9
	s_lshl_b32 s5, s6, 14
	s_mul_hi_i32 s15, s4, 0x1600000
	s_mul_i32 s16, s4, 0x1600000
	s_lshl_b32 s4, s4, 10
	v_bfe_u32 v71, v0, 3, 3
	v_lshlrev_b32_e32 v160, 4, v1
	s_add_i32 s6, s5, 0
	v_and_b32_e32 v2, 63, v0
	s_ashr_i32 s5, s4, 31
	v_mul_u32_u24_e32 v3, 0x410, v1
	v_lshl_add_u64 v[0:1], s[8:9], 0, v[160:161]
	s_mov_b64 s[8:9], 0x1500000
	v_lshlrev_b32_e32 v4, 2, v71
	v_lshl_add_u32 v70, v2, 2, s6
	v_lshl_add_u64 v[0:1], v[0:1], 0, s[8:9]
	v_add3_u32 v72, s6, v3, v4
	s_lshl_b32 s18, s14, 6
	s_lshl_b32 s19, s14, 5
	s_lshl_b64 s[6:7], s[4:5], 2
	v_lshlrev_b32_e32 v160, 2, v2
	s_branch .LBB0_1983

; #define LAS __attribute__((address_space(3)))
; __device__ __forceinline__ unsigned pk2(float lo, float hi) { f32x2 v = {lo, hi}; bf16x2_t b = __builtin_convertvector(v, bf16x2_t); return __builtin_bit_cast(unsigned, b); }
; __device__ __forceinline__ void transpose_item(const float* W, int K, int N, bf16_t* WT, const float* gk, int mode, LAS float* scr_, int item, int lane) {
;     LAS unsigned* scr = (LAS unsigned*)scr_;
;     const int nblk = N / 64, kb = item / nblk, nb = item % nblk, k0 = 64 * kb, n0 = 64 * nb;
;     const int sc = (mode == 1) ? (((n0 >> 7) & 1) * DFF + (n0 >> 8) * 128 + (n0 & 127)) : n0;
;     const float* src = W + (size_t)k0 * N + sc + lane;
;     float va[32], vb[32];
; #pragma unroll
;     for (int kp = 0; kp < 32; ++kp) { va[kp] = src[(size_t)(2 * kp) * N]; vb[kp] = src[(size_t)(2 * kp + 1) * N]; }
; #pragma unroll
;     for (int kp = 0; kp < 32; ++kp) {
;         float a = va[kp], b = vb[kp];
;         if (gk) { a *= gk[k0 + 2 * kp]; b *= gk[k0 + 2 * kp + 1]; }
;         scr[kp * 65 + lane] = pk2(a, b);
;     }
.LBB0_1983:
	v_mov_b32_e32 v2, v161
	s_mul_hi_i32 s8, s14, 0x2e8ba2e9
	v_add_u32_e32 v2, 0, v2
	v_add_u32_e32 v2, 0x20198, v2
	s_nop 0
	s_waitcnt lgkmcnt(0)
	v_readlane_b32 s5, v251, 38
	v_mov_b32_e32 v2, v161
	v_readlane_b32 s4, v251, 39
	v_add_u32_e32 v2, 0, v2
	v_add_u32_e32 v2, 0x20190, v2
	s_nop 0
	s_add_u32 s11, s5, s16
	s_addc_u32 s12, s4, s15
	v_readlane_b32 s4, v251, 36
	v_readlane_b32 s5, v251, 37
	s_add_u32 s25, s4, s6
	s_addc_u32 s29, s5, s7
	s_lshr_b32 s9, s8, 31
	s_ashr_i32 s8, s8, 4
	s_add_i32 s13, s8, s9
	s_mul_i32 s9, s13, 0xffffea00
	s_mul_i32 s10, s13, 0xfffff500
	s_add_i32 s24, s18, s9
	s_bfe_i32 s9, s14, 0x10001
	s_add_i32 s10, s19, s10
	s_and_b32 s9, s9, 0xb00
	s_and_b32 s10, s10, 0xffffff80
	s_lshl_b32 s8, s13, 6
	s_add_i32 s9, s9, s10
	s_and_b32 s10, s24, 64
	s_or_b32 s10, s9, s10
	s_ashr_i32 s9, s8, 31
	s_mul_i32 s13, s13, 0x160000
	s_mul_hi_i32 s21, s8, 0x5800
	s_add_u32 s13, s11, s13
	s_addc_u32 s12, s12, s21
	s_ashr_i32 s11, s10, 31
	s_lshl_b64 s[10:11], s[10:11], 2
	s_add_u32 s10, s13, s10
	s_addc_u32 s11, s12, s11
	s_waitcnt vmcnt(9)
	v_lshl_add_u64 v[66:67], s[10:11], 0, v[160:161]
	global_load_dword v62, v160, s[10:11]
	s_movk_i32 s10, 0x5000
	v_add_co_u32_e32 v2, vcc, s10, v66
	s_mov_b32 s10, 0xb000
	s_nop 0
	v_addc_co_u32_e32 v3, vcc, 0, v67, vcc
	global_load_dword v63, v[2:3], off offset:2048
	v_add_co_u32_e32 v2, vcc, s10, v66
	s_mov_b32 s10, 0x1b000
	s_nop 0
	v_addc_co_u32_e32 v3, vcc, 0, v67, vcc
	global_load_dword v64, v[2:3], off
	v_add_co_u32_e32 v2, vcc, s37, v66
	s_cmp_lg_u64 s[4:5], 0
	s_nop 0
	v_addc_co_u32_e32 v3, vcc, 0, v67, vcc
	global_load_dword v65, v[2:3], off offset:2048
	v_add_co_u32_e32 v2, vcc, s47, v66
	s_mov_b64 s[12:13], -1
	s_nop 0
	v_addc_co_u32_e32 v3, vcc, 0, v67, vcc
	global_load_dword v54, v[2:3], off
	v_add_co_u32_e32 v2, vcc, s10, v66
	s_mov_b32 s10, 0x21000
	s_nop 0
	v_addc_co_u32_e32 v3, vcc, 0, v67, vcc
	global_load_dword v55, v[2:3], off offset:2048
	v_add_co_u32_e32 v2, vcc, s10, v66
	s_mov_b32 s10, 0x31000
	s_nop 0
	v_addc_co_u32_e32 v3, vcc, 0, v67, vcc
	global_load_dword v60, v[2:3], off
	v_add_co_u32_e32 v2, vcc, s73, v66
	s_nop 1
	v_addc_co_u32_e32 v3, vcc, 0, v67, vcc
	global_load_dword v61, v[2:3], off offset:2048
	v_add_co_u32_e32 v2, vcc, s82, v66
	s_nop 1
	v_addc_co_u32_e32 v3, vcc, 0, v67, vcc
	global_load_dword v56, v[2:3], off
	v_add_co_u32_e32 v2, vcc, s10, v66
	s_mov_b32 s10, 0x37000
	s_nop 0
	v_addc_co_u32_e32 v3, vcc, 0, v67, vcc
	global_load_dword v57, v[2:3], off offset:2048
	v_add_co_u32_e32 v2, vcc, s10, v66
	s_mov_b32 s10, 0x47000
	s_nop 0
	v_addc_co_u32_e32 v3, vcc, 0, v67, vcc
	global_load_dword v58, v[2:3], off
	v_add_co_u32_e32 v2, vcc, s90, v66
	s_nop 1
	v_addc_co_u32_e32 v3, vcc, 0, v67, vcc
	global_load_dword v59, v[2:3], off offset:2048
	v_add_co_u32_e32 v2, vcc, s93, v66
	s_nop 1
	v_addc_co_u32_e32 v3, vcc, 0, v67, vcc
	global_load_dword v44, v[2:3], off
	v_add_co_u32_e32 v2, vcc, s10, v66
	s_mov_b32 s10, 0x4d000
	s_nop 0
	v_addc_co_u32_e32 v3, vcc, 0, v67, vcc
	global_load_dword v45, v[2:3], off offset:2048
	v_add_co_u32_e32 v2, vcc, s10, v66
	s_mov_b32 s10, 0x52000
	s_nop 0
	v_addc_co_u32_e32 v3, vcc, 0, v67, vcc
	global_load_dword v50, v[2:3], off
	v_add_co_u32_e32 v2, vcc, s10, v66
	s_mov_b32 s10, 0x58000
	s_nop 0
	v_addc_co_u32_e32 v3, vcc, 0, v67, vcc
	global_load_dword v51, v[2:3], off offset:2048
	v_add_co_u32_e32 v2, vcc, s10, v66
	s_mov_b32 s10, 0x5d000
	s_nop 0
	v_addc_co_u32_e32 v3, vcc, 0, v67, vcc
	global_load_dword v48, v[2:3], off
	v_add_co_u32_e32 v2, vcc, s10, v66
	s_mov_b32 s10, 0x63000
	s_nop 0
	v_addc_co_u32_e32 v3, vcc, 0, v67, vcc
	global_load_dword v49, v[2:3], off offset:2048
	v_add_co_u32_e32 v2, vcc, s10, v66
	s_mov_b32 s10, 0x68000
	s_nop 0
	v_addc_co_u32_e32 v3, vcc, 0, v67, vcc
	global_load_dword v52, v[2:3], off
	v_add_co_u32_e32 v2, vcc, s10, v66
	s_mov_b32 s10, 0x6e000
	s_nop 0
	v_addc_co_u32_e32 v3, vcc, 0, v67, vcc
	global_load_dword v53, v[2:3], off offset:2048
	v_add_co_u32_e32 v2, vcc, s10, v66
	s_mov_b32 s10, 0x73000
	s_nop 0
	v_addc_co_u32_e32 v3, vcc, 0, v67, vcc
	global_load_dword v38, v[2:3], off
	v_add_co_u32_e32 v2, vcc, s10, v66
	s_mov_b32 s10, 0x79000
	s_nop 0
	v_addc_co_u32_e32 v3, vcc, 0, v67, vcc
	global_load_dword v39, v[2:3], off offset:2048
	v_add_co_u32_e32 v2, vcc, s10, v66
	s_mov_b32 s10, 0x7e000
	s_nop 0
	v_addc_co_u32_e32 v3, vcc, 0, v67, vcc
	global_load_dword v42, v[2:3], off
	v_add_co_u32_e32 v2, vcc, s10, v66
	s_mov_b32 s10, 0x84000
	s_nop 0
	v_addc_co_u32_e32 v3, vcc, 0, v67, vcc
	global_load_dword v43, v[2:3], off offset:2048
	v_add_co_u32_e32 v2, vcc, s10, v66
	s_mov_b32 s10, 0x89000
	s_nop 0
	v_addc_co_u32_e32 v3, vcc, 0, v67, vcc
	global_load_dword v40, v[2:3], off
	v_add_co_u32_e32 v2, vcc, s10, v66
	s_mov_b32 s10, 0x8f000
	s_nop 0
	v_addc_co_u32_e32 v3, vcc, 0, v67, vcc
	global_load_dword v41, v[2:3], off offset:2048
	v_add_co_u32_e32 v2, vcc, s10, v66
	s_mov_b32 s10, 0x94000
	s_nop 0
	v_addc_co_u32_e32 v3, vcc, 0, v67, vcc
	global_load_dword v46, v[2:3], off
	v_add_co_u32_e32 v2, vcc, s10, v66
	s_mov_b32 s10, 0x9a000
	s_nop 0
	v_addc_co_u32_e32 v3, vcc, 0, v67, vcc
	global_load_dword v47, v[2:3], off offset:2048
	v_add_co_u32_e32 v2, vcc, s10, v66
	s_mov_b32 s10, 0x9f000
	s_nop 0
	v_addc_co_u32_e32 v3, vcc, 0, v67, vcc
	global_load_dword v30, v[2:3], off
	v_add_co_u32_e32 v2, vcc, s10, v66
	s_mov_b32 s10, 0xa5000
	s_nop 0
	v_addc_co_u32_e32 v3, vcc, 0, v67, vcc
; #define LAS __attribute__((address_space(3)))
; __device__ __forceinline__ unsigned pk2(float lo, float hi) { f32x2 v = {lo, hi}; bf16x2_t b = __builtin_convertvector(v, bf16x2_t); return __builtin_bit_cast(unsigned, b); }
; __device__ __forceinline__ void transpose_item(const float* W, int K, int N, bf16_t* WT, const float* gk, int mode, LAS float* scr_, int item, int lane) {
;     LAS unsigned* scr = (LAS unsigned*)scr_;
;     const int nblk = N / 64, kb = item / nblk, nb = item % nblk, k0 = 64 * kb, n0 = 64 * nb;
;     const int sc = (mode == 1) ? (((n0 >> 7) & 1) * DFF + (n0 >> 8) * 128 + (n0 & 127)) : n0;
;     const float* src = W + (size_t)k0 * N + sc + lane;
;     float va[32], vb[32];
; #pragma unroll
;     for (int kp = 0; kp < 32; ++kp) { va[kp] = src[(size_t)(2 * kp) * N]; vb[kp] = src[(size_t)(2 * kp + 1) * N]; }
; #pragma unroll
;     for (int kp = 0; kp < 32; ++kp) {
;         float a = va[kp], b = vb[kp];
;         if (gk) { a *= gk[k0 + 2 * kp]; b *= gk[k0 + 2 * kp + 1]; }
;         scr[kp * 65 + lane] = pk2(a, b);
;     }
	global_load_dword v31, v[2:3], off offset:2048
	v_add_co_u32_e32 v2, vcc, s10, v66
	s_mov_b32 s10, 0xaa000
	s_nop 0
	v_addc_co_u32_e32 v3, vcc, 0, v67, vcc
	global_load_dword v36, v[2:3], off
	v_add_co_u32_e32 v2, vcc, s10, v66
	s_mov_b32 s10, 0xb5000
	s_nop 0
	v_addc_co_u32_e32 v3, vcc, 0, v67, vcc
	global_load_dword v37, v[2:3], off offset:2048
	v_add_co_u32_e32 v2, vcc, s95, v66
	s_nop 1
	v_addc_co_u32_e32 v3, vcc, 0, v67, vcc
	global_load_dword v32, v[2:3], off
	v_add_co_u32_e32 v2, vcc, s10, v66
	s_mov_b32 s10, 0xbb000
	s_nop 0
	v_addc_co_u32_e32 v3, vcc, 0, v67, vcc
	global_load_dword v33, v[2:3], off offset:2048
	v_add_co_u32_e32 v2, vcc, s10, v66
	s_mov_b32 s10, 0xc0000
	s_nop 0
	v_addc_co_u32_e32 v3, vcc, 0, v67, vcc
	global_load_dword v34, v[2:3], off
	v_add_co_u32_e32 v2, vcc, s10, v66
	s_mov_b32 s10, 0xcb000
	s_nop 0
	v_addc_co_u32_e32 v3, vcc, 0, v67, vcc
	global_load_dword v35, v[2:3], off offset:2048
	v_add_co_u32_e32 v2, vcc, s89, v66
	s_nop 1
	v_addc_co_u32_e32 v3, vcc, 0, v67, vcc
	global_load_dword v20, v[2:3], off
	v_add_co_u32_e32 v2, vcc, s10, v66
	s_mov_b32 s10, 0xd1000
	s_nop 0
	v_addc_co_u32_e32 v3, vcc, 0, v67, vcc
	global_load_dword v21, v[2:3], off offset:2048
	v_add_co_u32_e32 v2, vcc, s10, v66
	s_mov_b32 s10, 0xd6000
	s_nop 0
	v_addc_co_u32_e32 v3, vcc, 0, v67, vcc
	global_load_dword v26, v[2:3], off
	v_add_co_u32_e32 v2, vcc, s10, v66
	s_mov_b32 s10, 0xdc000
	s_nop 0
	v_addc_co_u32_e32 v3, vcc, 0, v67, vcc
	global_load_dword v27, v[2:3], off offset:2048
	v_add_co_u32_e32 v2, vcc, s10, v66
	s_mov_b32 s10, 0xe1000
	s_nop 0
	v_addc_co_u32_e32 v3, vcc, 0, v67, vcc
	global_load_dword v24, v[2:3], off
	v_add_co_u32_e32 v2, vcc, s10, v66
	s_mov_b32 s10, 0xe7000
	s_nop 0
	v_addc_co_u32_e32 v3, vcc, 0, v67, vcc
	global_load_dword v25, v[2:3], off offset:2048
	v_add_co_u32_e32 v2, vcc, s10, v66
	s_mov_b32 s10, 0xec000
	s_nop 0
	v_addc_co_u32_e32 v3, vcc, 0, v67, vcc
	global_load_dword v28, v[2:3], off
	v_add_co_u32_e32 v2, vcc, s10, v66
	s_mov_b32 s10, 0xf2000
	s_nop 0
	v_addc_co_u32_e32 v3, vcc, 0, v67, vcc
	global_load_dword v29, v[2:3], off offset:2048
	v_add_co_u32_e32 v2, vcc, s10, v66
	s_mov_b32 s10, 0xf7000
	s_nop 0
	v_addc_co_u32_e32 v3, vcc, 0, v67, vcc
	global_load_dword v12, v[2:3], off
	v_add_co_u32_e32 v2, vcc, s10, v66
	s_mov_b32 s10, 0xfd000
	s_nop 0
	v_addc_co_u32_e32 v3, vcc, 0, v67, vcc
	global_load_dword v13, v[2:3], off offset:2048
	v_add_co_u32_e32 v2, vcc, s10, v66
	s_mov_b32 s10, 0x102000
	s_nop 0
	v_addc_co_u32_e32 v3, vcc, 0, v67, vcc
	global_load_dword v18, v[2:3], off
	v_add_co_u32_e32 v2, vcc, s10, v66
	s_mov_b32 s10, 0x108000
	s_nop 0
	v_addc_co_u32_e32 v3, vcc, 0, v67, vcc
	global_load_dword v19, v[2:3], off offset:2048
	v_add_co_u32_e32 v2, vcc, s10, v66
	s_mov_b32 s10, 0x10d000
	s_nop 0
	v_addc_co_u32_e32 v3, vcc, 0, v67, vcc
	global_load_dword v16, v[2:3], off
	v_add_co_u32_e32 v2, vcc, s10, v66
	s_mov_b32 s10, 0x113000
	s_nop 0
	v_addc_co_u32_e32 v3, vcc, 0, v67, vcc
	global_load_dword v17, v[2:3], off offset:2048
	v_add_co_u32_e32 v2, vcc, s10, v66
	s_mov_b32 s10, 0x118000
	s_nop 0
	v_addc_co_u32_e32 v3, vcc, 0, v67, vcc
	global_load_dword v22, v[2:3], off
	v_add_co_u32_e32 v2, vcc, s10, v66
	s_mov_b32 s10, 0x11e000
	s_nop 0
	v_addc_co_u32_e32 v3, vcc, 0, v67, vcc
	global_load_dword v23, v[2:3], off offset:2048
	v_add_co_u32_e32 v2, vcc, s10, v66
	s_mov_b32 s10, 0x123000
	s_nop 0
	v_addc_co_u32_e32 v3, vcc, 0, v67, vcc
	global_load_dword v4, v[2:3], off
	v_add_co_u32_e32 v2, vcc, s10, v66
	s_mov_b32 s10, 0x129000
	s_nop 0
	v_addc_co_u32_e32 v3, vcc, 0, v67, vcc
	global_load_dword v5, v[2:3], off offset:2048
	v_add_co_u32_e32 v2, vcc, s10, v66
	s_mov_b32 s10, 0x12e000
	s_nop 0
	v_addc_co_u32_e32 v3, vcc, 0, v67, vcc
	global_load_dword v10, v[2:3], off
	v_add_co_u32_e32 v2, vcc, s10, v66
	s_mov_b32 s10, 0x134000
	s_nop 0
	v_addc_co_u32_e32 v3, vcc, 0, v67, vcc
	global_load_dword v11, v[2:3], off offset:2048
	v_add_co_u32_e32 v2, vcc, s10, v66
	s_mov_b32 s10, 0x139000
	s_nop 0
	v_addc_co_u32_e32 v3, vcc, 0, v67, vcc
	global_load_dword v6, v[2:3], off
	v_add_co_u32_e32 v2, vcc, s10, v66
	s_mov_b32 s10, 0x13f000
	s_nop 0
	v_addc_co_u32_e32 v3, vcc, 0, v67, vcc
	global_load_dword v7, v[2:3], off offset:2048
	v_add_co_u32_e32 v2, vcc, s10, v66
	s_mov_b32 s10, 0x144000
	s_nop 0
	v_addc_co_u32_e32 v3, vcc, 0, v67, vcc
	global_load_dword v14, v[2:3], off
	v_add_co_u32_e32 v2, vcc, s10, v66
	s_mov_b32 s10, 0x14a000
	s_nop 0
	v_addc_co_u32_e32 v3, vcc, 0, v67, vcc
	global_load_dword v15, v[2:3], off offset:2048
	v_add_co_u32_e32 v2, vcc, s10, v66
	s_mov_b32 s10, 0x14f000
	s_nop 0
	v_addc_co_u32_e32 v3, vcc, 0, v67, vcc
	v_add_co_u32_e32 v8, vcc, s10, v66
	global_load_dword v2, v[2:3], off
	s_nop 0
	v_addc_co_u32_e32 v9, vcc, 0, v67, vcc
	global_load_dword v3, v[8:9], off offset:2048
	v_add_co_u32_e32 v8, vcc, 0x155000, v66
	s_cselect_b64 s[10:11], -1, 0
	s_nop 0
	v_addc_co_u32_e32 v9, vcc, 0, v67, vcc
	v_add_co_u32_e32 v66, vcc, 0x15a000, v66
	global_load_dword v8, v[8:9], off
	s_nop 0
	v_addc_co_u32_e32 v67, vcc, 0, v67, vcc
	global_load_dword v9, v[66:67], off offset:2048
	s_cmp_eq_u64 s[4:5], 0
	s_cbranch_scc1 .LBB0_1985
	s_lshl_b64 s[4:5], s[8:9], 2
	s_add_u32 s4, s25, s4
	s_addc_u32 s5, s29, s5
	global_load_dwordx4 v[66:69], v161, s[4:5]
	s_mov_b64 s[12:13], 0
	s_waitcnt vmcnt(0)
	v_pk_mul_f32 v[66:67], v[62:63], v[66:67]
	v_pk_mul_f32 v[68:69], v[64:65], v[68:69]

; __device__ __forceinline__ unsigned xb_ld(unsigned* p)              { return __hip_atomic_load(p, __ATOMIC_RELAXED, __HIP_MEMORY_SCOPE_AGENT); }
; __device__ __forceinline__ unsigned xb_add(unsigned* p, unsigned v) { return __hip_atomic_fetch_add(p, v, __ATOMIC_RELAXED, __HIP_MEMORY_SCOPE_AGENT); }
; #define XB_SPIN(cond, bar) do { unsigned _sp = 0; while (cond) { __builtin_amdgcn_s_sleep(1); \
;     if ((++_sp & 255u) == 0u) { if (xb_ld(&(bar)[XB_TMO])) break; if (_sp > XB_SPIN_CAP) { atomicAdd(&(bar)[XB_TMO], 1u); break; } } } } while (0)
; __device__ __forceinline__ void xcd_barrier(const XcdBarrier& b, bool t0) {
;     asm volatile("s_waitcnt vmcnt(0)" ::: "memory");
;     __syncthreads();
;     if (t0) {
;         unsigned* bar = b.bar;
;         __builtin_amdgcn_s_waitcnt(0);
;         unsigned nloc = b.st[0], nx = b.st[1];
;         if (nloc == 0u) { xcd_barrier_complete(bar, b.x, nloc, nx); b.st[0] = nloc; b.st[1] = nx; }
;         const unsigned old = xb_add(&bar[XB_XSUB(b.x)], 1u);
;         const unsigned gen = old / nloc;
;         if (old + 1u == (gen + 1u) * nloc) {
;             __builtin_amdgcn_fence(__ATOMIC_RELEASE, "agent");
;             asm volatile("s_waitcnt vmcnt(0)" ::: "memory");
;             const unsigned og = xb_add(&bar[XB_TOP], 1u);
;             const unsigned tg = og / nx;
;             if (og + 1u == (tg + 1u) * nx) xb_add(&bar[XB_TOPGEN], 1u);
;             else XB_SPIN(xb_ld(&bar[XB_TOPGEN]) == tg, bar);
;             __builtin_amdgcn_fence(__ATOMIC_ACQUIRE, "agent");
;             xb_add(&bar[XB_XGEN(b.x)], 1u);
;             asm volatile("s_waitcnt vmcnt(0)" ::: "memory");
;         } else {
;             XB_SPIN(xb_ld(&bar[XB_XGEN(b.x)]) == gen, bar);
;             __builtin_amdgcn_fence(__ATOMIC_ACQUIRE, "agent");
;             asm volatile("s_waitcnt vmcnt(0)" ::: "memory");
;         }
;     }
;     __syncthreads();
.LBB0_2047:
	s_waitcnt lgkmcnt(0)
	v_mov_b32_e32 v0, v161
	v_mov_b32_e32 v2, v183
	v_add_u32_e32 v0, 0, v0
	v_add_u32_e32 v0, 0x201c0, v0
	s_nop 0
	s_getreg_b32 s8, hwreg(HW_REG_XCC_ID, 0, 4)
	s_waitcnt vmcnt(0)
	v_readlane_b32 s7, v251, 49
	v_readlane_b32 s6, v251, 48
	v_cmp_eq_u32_e32 vcc, 0, v2
	s_barrier
	s_and_saveexec_b64 s[4:5], vcc
	s_cbranch_execz .LBB0_2099
	v_readlane_b32 s9, v250, 17
	s_waitcnt vmcnt(0) expcnt(0) lgkmcnt(0)
	s_and_b32 s14, s8, 15
	v_mov_b32_e32 v0, s9
	ds_read_b32 v2, v0
	v_readlane_b32 s9, v250, 18
	s_waitcnt lgkmcnt(0)
	v_cmp_ne_u32_e32 vcc, 0, v2
	v_mov_b32_e32 v0, s9
	ds_read_b32 v0, v0
	s_cbranch_vccnz .LBB0_2063
	s_add_u32 s8, s6, 0x28680200
	s_addc_u32 s9, s7, 0
	s_add_u32 s10, s6, 0x28680400
	s_addc_u32 s11, s7, 0
	s_add_u32 s12, s6, 0x28680500
	s_addc_u32 s13, s7, 0
	s_add_u32 s18, s6, 0x28680600
	s_addc_u32 s19, s7, 0
	s_add_u32 s34, s6, 0x28680700
	s_addc_u32 s35, s7, 0
	s_add_u32 s40, s6, 0x28680800
	s_addc_u32 s41, s7, 0
	s_add_u32 s42, s6, 0x28680900
	s_addc_u32 s43, s7, 0
	s_add_u32 s44, s6, 0x28680a00
	s_addc_u32 s45, s7, 0
	s_add_u32 s48, s6, 0x28680b00
	s_addc_u32 s49, s7, 0
	s_add_u32 s50, s6, 0x28680c00
	s_addc_u32 s51, s7, 0
	s_add_u32 s52, s6, 0x28680d00
	s_addc_u32 s53, s7, 0
	s_add_u32 s56, s6, 0x28680e00
	s_addc_u32 s57, s7, 0
	s_add_u32 s60, s6, 0x28680f00
	s_addc_u32 s61, s7, 0
	s_add_u32 s62, s6, 0x28681000
	s_addc_u32 s63, s7, 0
	s_add_u32 s64, s6, 0x28681100
	s_addc_u32 s65, s7, 0
	s_add_u32 s66, s6, 0x28681200
	s_addc_u32 s67, s7, 0
	s_add_u32 s24, s6, 0x28681300
	s_addc_u32 s25, s7, 0
	s_mov_b32 s15, 1
	s_branch .LBB0_2051

; #define PG8_WAIT_V(n) asm volatile("s_waitcnt vmcnt(" #n ")" ::: "memory")
; #define PG8_BAR __builtin_amdgcn_s_barrier()
; template <class Epi, class Sched, bool ALIGN_EPI = false, bool SP2 = false>
; __device__ __forceinline__ void gemm_phase(PG8_LAS unsigned char* lds, const Gemm g, const Sched& S, const Epi& E, int wv) {
;     ...
;     const int tid = tid_, wid = __builtin_amdgcn_readfirstlane(tid >> 6), lane = tid & 63, wr = wid >> 2, wc = wid & 3, fr = lane & 15, fq = lane >> 4;
;     const int K = g.K, nt = K / BK;
;     unsigned voffA[2], voffB[2];
; #pragma unroll
;     for (int i = 0; i < 2; ++i) { int R, C; stage_rc(tid * 16 + i * 8192, R, C); const int Rb = Epi::PERM ? ((R & ~31) + perm32(R & 31)) : R;
;         voffA[i] = (unsigned)(R * K + C) * 2u; voffB[i] = (unsigned)(Rb * K + C) * 2u; }
;     const size_t kstep = (size_t)(BK * 2);
;     const size_t hstep = (size_t)HALF * K * 2;
;     const size_t tstep = 2 * hstep;
;     const unsigned ldsw = (unsigned)wid * 1024u;
;     const int aoff = lds_byte(wr * 64 + fr, fq * 8), boff = lds_byte(wc * 32 + fr, fq * 8);
;     ...
;     Unit cur, nxt; int ui = 0;
;     if (!S.next(0, cur)) return;
;     f32x4 acc[2][2][4][2];
; #pragma unroll
;     for (int a = 0; a < 2; ++a)
; #pragma unroll
;         for (int b = 0; b < 2; ++b)
; #pragma unroll
;             for (int m = 0; m < 4; ++m)
; #pragma unroll
;                 for (int n = 0; n < 2; ++n) acc[a][b][m][n] = (f32x4){0.f, 0.f, 0.f, 0.f};
;     bf16x8 At[4][2], B0[2][2], B1[2][2];
;     const char* cA = (const char*)g.A + (size_t)cur.pm * tstep; const char* cB = (const char*)g.Bt + (size_t)cur.pn * tstep;
;     S.a_ready(cur);
;     if constexpr (SP2) {
;         PG8_STAGE(PG8_SB(0, 0), cB, voffB); PG8_STAGE(PG8_SB(0, 1), cB + hstep, voffB); PG8_STAGE(PG8_SA(0, 0), cA, voffA); PG8_STAGE(PG8_SA(0, 1), cA + hstep, voffA);
;         if (wr == 1) PG8_BAR;
;         PG8_WAIT_V(2); PG8_BAR;
;         PG8_STAGE(PG8_SB(1, 0), cB + kstep, voffB); PG8_STAGE(PG8_SA(1, 0), cA + kstep, voffA); PG8_STAGE(PG8_SB(1, 1), cB + hstep + kstep, voffB);
; __global__ void __launch_bounds__(512, 2) hymba_fwd(Params p) {
;     ...
;         { PHASE_VARS pg8::Gemm g{xb, (const bf16_t*)(wl + WL_FFB_IN), MT, NFF2, DM}; pg8::StaticOrder S; S.init(MT, NFF2, G, c); EpiSwiglu E{act, sq + 2 * MT};
;           pg8::gemm_phase<EpiSwiglu, pg8::StaticOrder, true, true>(L, g, S, E, wv); }
.LBB0_2099:
	s_or_b64 exec, exec, s[4:5]
	v_readlane_b32 s8, v250, 0
	s_mov_b64 s[4:5], 0
	s_waitcnt lgkmcnt(0)
	v_mov_b32_e32 v0, v161
	s_barrier
	v_readlane_b32 s10, v250, 33
	v_add_u32_e32 v0, 0, v0
	v_add_u32_e32 v0, 0x201c0, v0
	s_nop 0
	v_mov_b32_e32 v14, v183
	v_readlane_b32 s11, v250, 34
	s_and_b64 vcc, exec, s[10:11]
	v_readlane_b32 s6, v251, 48
	v_mov_b32_e32 v0, v161
	v_readlane_b32 s7, v251, 49
	v_add_u32_e32 v0, 0, v0
	v_add_u32_e32 v0, 0x201c8, v0
	ds_read_b64 v[0:1], v0
	s_nop 0
	v_readfirstlane_b32 s10, v14
	s_cbranch_vccnz .LBB0_2115
	s_waitcnt lgkmcnt(0)
	v_lshlrev_b32_e32 v0, 4, v14
	v_add_u32_e32 v1, 0x2000, v0
	v_ashrrev_i32_e32 v2, 31, v1
	v_lshrrev_b32_e32 v2, 22, v2
	v_add_u32_e32 v2, v1, v2
	v_ashrrev_i32_e32 v8, 10, v2
	v_mul_i32_i24_e32 v2, 0x400, v8
	v_sub_u32_e32 v1, v1, v2
	v_lshrrev_b32_e32 v2, 4, v1
	v_bitop3_b32 v1, v2, v1, 32 bitop3:0x6c
	s_add_u32 s6, s6, s4
	v_ashrrev_i32_e32 v2, 31, v1
	s_addc_u32 s7, s7, s5
	v_lshrrev_b32_e32 v2, 26, v2
	s_add_u32 s14, s6, 0x5200000
	v_add_u32_e32 v2, v1, v2
	v_lshlrev_b32_e32 v3, 3, v8
	s_addc_u32 s15, s7, 0
	s_mul_i32 s5, s8, 0x2900000
	v_ashrrev_i32_e32 v9, 6, v2
	v_and_b32_e32 v3, -16, v3
	s_mul_hi_i32 s4, s8, 0x2900000
	s_add_u32 s9, s6, s5
	v_add_u32_e32 v3, v9, v3
	s_addc_u32 s13, s7, s4
	v_and_b32_e32 v4, 3, v9
	s_mov_b32 s4, 0x1fffe0
	v_lshrrev_b32_e32 v5, 2, v3
	v_lshlrev_b32_e32 v6, 1, v3
	v_and_b32_e32 v2, 0xc0, v2
	v_and_or_b32 v4, v3, s4, v4
	v_and_b32_e32 v5, 4, v5
	v_and_b32_e32 v6, 24, v6
	v_sub_u32_e32 v1, v1, v2
	v_or3_b32 v4, v4, v5, v6
	v_lshlrev_b32_e32 v5, 5, v8
	v_ashrrev_i16_sdwa v1, v193, sext(v1) dst_sel:DWORD dst_unused:UNUSED_PAD src0_sel:DWORD src1_sel:BYTE_0
	v_and_b32_e32 v5, 32, v5
	v_bfe_i32 v10, v1, 0, 16
	v_add_lshl_u32 v1, v5, v10, 1
	v_lshl_add_u32 v128, v4, 11, v1
	v_lshl_add_u32 v130, v3, 11, v1
	v_bfe_i32 v1, v14, 27, 1
	v_lshrrev_b32_e32 v1, 22, v1
	v_add_u32_e32 v1, v0, v1
	v_and_b32_e32 v1, 0xfffffc00, v1
	v_sub_u32_e32 v0, v0, v1
	v_lshrrev_b32_e32 v1, 4, v0
	v_ashrrev_i32_e32 v2, 31, v14
	v_bitop3_b32 v0, v1, v0, 32 bitop3:0x6c
	v_lshrrev_b32_e32 v2, 26, v2
	v_ashrrev_i32_e32 v1, 31, v0
	v_add_u32_e32 v2, v14, v2
	v_lshrrev_b32_e32 v1, 26, v1
	v_ashrrev_i32_e32 v12, 6, v2
	v_add_u32_e32 v1, v0, v1
	v_lshlrev_b32_e32 v2, 3, v12
	v_ashrrev_i32_e32 v11, 6, v1
	v_and_b32_e32 v2, -16, v2
	v_add_u32_e32 v2, v11, v2
	s_add_u32 s16, s9, 0x1500000
	v_and_b32_e32 v3, 3, v11
	v_lshrrev_b32_e32 v4, 2, v2
	v_lshlrev_b32_e32 v5, 1, v2
	v_and_b32_e32 v1, 0xc0, v1
	s_addc_u32 s29, s13, 0
	s_ashr_i32 s11, s10, 6
	v_and_or_b32 v3, v2, s4, v3
	v_and_b32_e32 v4, 4, v4
	v_and_b32_e32 v5, 24, v5
	v_sub_u32_e32 v0, v0, v1
	s_ashr_i32 s12, s10, 8
	s_lshl_b32 s30, s11, 10
	v_or3_b32 v3, v3, v4, v5
	v_lshlrev_b32_e32 v4, 5, v12
	v_ashrrev_i16_sdwa v0, v193, sext(v0) dst_sel:DWORD dst_unused:UNUSED_PAD src0_sel:DWORD src1_sel:BYTE_0
	v_readlane_b32 s4, v250, 5
	v_and_b32_e32 v4, 32, v4
	v_bfe_i32 v13, v0, 0, 16
	v_readlane_b32 s5, v250, 6
	s_add_u32 s48, s16, s4
	v_add_lshl_u32 v0, v4, v13, 1
	s_addc_u32 s49, s29, s5
	s_add_i32 s31, s30, 0
	v_lshl_add_u32 v160, v3, 11, v0
	s_add_i32 m0, s31, 0x10000
	v_lshl_add_u32 v132, v2, 11, v0
	global_load_lds_dwordx4 v160, s[48:49]
	s_add_i32 m0, s31, 0x12000
	s_add_u32 s4, s48, 0x40000
	global_load_lds_dwordx4 v128, s[48:49]
	s_addc_u32 s5, s49, 0
	s_add_i32 m0, s31, 0x14000
	v_mov_b32_e32 v129, v161
	global_load_lds_dwordx4 v160, s[4:5]
	s_add_i32 m0, s31, 0x16000
	v_mov_b32_e32 v133, v161
	global_load_lds_dwordx4 v128, s[4:5]
	v_readlane_b32 s4, v250, 21
	v_readlane_b32 s5, v250, 22
	s_add_u32 s44, s14, s4
	s_addc_u32 s45, s15, s5
	s_add_i32 s52, s31, 0x2000
	s_mov_b32 m0, s31
	s_add_u32 s4, s44, 0x40000
	global_load_lds_dwordx4 v132, s[44:45]
	s_mov_b32 m0, s52
	s_addc_u32 s5, s45, 0
	s_add_i32 s53, s31, 0x4000
	global_load_lds_dwordx4 v130, s[44:45]
	s_mov_b32 m0, s53
	s_add_i32 s54, s31, 0x6000
	global_load_lds_dwordx4 v132, s[4:5]
	s_mov_b32 m0, s54
	v_mov_b32_e32 v131, v161
	global_load_lds_dwordx4 v130, s[4:5]
	s_cmp_eq_u32 s12, 1
	v_lshl_add_u64 v[6:7], s[48:49], 0, v[160:161]
	v_lshl_add_u64 v[4:5], s[48:49], 0, v[128:129]
	v_lshl_add_u64 v[0:1], s[44:45], 0, v[132:133]
	s_cselect_b64 s[4:5], -1, 0
	s_cmp_lg_u32 s12, 1
	v_lshl_add_u64 v[2:3], s[44:45], 0, v[130:131]
	s_cbranch_scc1 .LBB0_2102
	s_barrier

; #define PG8_WAIT_V(n) asm volatile("s_waitcnt vmcnt(" #n ")" ::: "memory")
; template <class Epi, class Sched, bool ALIGN_EPI = false, bool SP2 = false>
; __device__ __forceinline__ void gemm_phase(PG8_LAS unsigned char* lds, const Gemm g, const Sched& S, const Epi& E, int wv) {
;     ...
;     const int tid = tid_, wid = __builtin_amdgcn_readfirstlane(tid >> 6), lane = tid & 63, wr = wid >> 2, wc = wid & 3, fr = lane & 15, fq = lane >> 4;
;     const int K = g.K, nt = K / BK;
;     unsigned voffA[2], voffB[2];
; #pragma unroll
;     for (int i = 0; i < 2; ++i) { int R, C; stage_rc(tid * 16 + i * 8192, R, C); const int Rb = Epi::PERM ? ((R & ~31) + perm32(R & 31)) : R;
;         voffA[i] = (unsigned)(R * K + C) * 2u; voffB[i] = (unsigned)(Rb * K + C) * 2u; }
;     const size_t kstep = (size_t)(BK * 2);
;     const size_t hstep = (size_t)HALF * K * 2;
;     const size_t tstep = 2 * hstep;
;     const unsigned ldsw = (unsigned)wid * 1024u;
;     const int aoff = lds_byte(wr * 64 + fr, fq * 8), boff = lds_byte(wc * 32 + fr, fq * 8);
;     ...
;     Unit cur, nxt; int ui = 0;
;     if (!S.next(0, cur)) return;
;     f32x4 acc[2][2][4][2];
; #pragma unroll
;     for (int a = 0; a < 2; ++a)
; #pragma unroll
;         for (int b = 0; b < 2; ++b)
; #pragma unroll
;             for (int m = 0; m < 4; ++m)
; #pragma unroll
;                 for (int n = 0; n < 2; ++n) acc[a][b][m][n] = (f32x4){0.f, 0.f, 0.f, 0.f};
;     bf16x8 At[4][2], B0[2][2], B1[2][2];
;     const char* cA = (const char*)g.A + (size_t)cur.pm * tstep; const char* cB = (const char*)g.Bt + (size_t)cur.pn * tstep;
;     S.a_ready(cur);
;     if constexpr (SP2) {
;         PG8_STAGE(PG8_SB(0, 0), cB, voffB); PG8_STAGE(PG8_SB(0, 1), cB + hstep, voffB); PG8_STAGE(PG8_SA(0, 0), cA, voffA); PG8_STAGE(PG8_SA(0, 1), cA + hstep, voffA);
;         if (wr == 1) PG8_BAR;
;         PG8_WAIT_V(2); PG8_BAR;
;         PG8_STAGE(PG8_SB(1, 0), cB + kstep, voffB); PG8_STAGE(PG8_SA(1, 0), cA + kstep, voffA); PG8_STAGE(PG8_SB(1, 1), cB + hstep + kstep, voffB);
; __global__ void __launch_bounds__(512, 2) hymba_fwd(Params p) {
;     ...
;         { PHASE_VARS pg8::Gemm g{act, (const bf16_t*)(wl + WL_FFB_OUT), MT, DM, DFF}; pg8::StaticOrder S; S.init(MT, DM, G, c);
;           EpiResid<0> E{xb, xb, nullptr, sq + 3 * MT, 0.5f, nullptr, nullptr};
;           pg8::gemm_phase<EpiResid<0>, pg8::StaticOrder, true, true>(L, g, S, E, wv); }
.LBB0_2167:
	s_or_b64 exec, exec, s[4:5]
	v_readlane_b32 s12, v250, 0
	s_mov_b64 s[4:5], 0
	s_waitcnt lgkmcnt(0)
	v_mov_b32_e32 v0, v161
	s_barrier
	v_readlane_b32 s8, v250, 42
	v_add_u32_e32 v0, 0, v0
	v_add_u32_e32 v0, 0x201c0, v0
	s_nop 0
	v_mov_b32_e32 v16, v183
	v_readlane_b32 s9, v250, 43
	s_and_b64 vcc, exec, s[8:9]
	v_readlane_b32 s7, v251, 48
	v_mov_b32_e32 v0, v161
	v_readlane_b32 s6, v251, 49
	v_add_u32_e32 v0, 0, v0
	v_add_u32_e32 v0, 0x201c8, v0
	ds_read_b64 v[0:1], v0
	s_nop 0
	v_readfirstlane_b32 s18, v16
	s_cbranch_vccnz .LBB0_2203
	s_waitcnt lgkmcnt(0)
	v_lshlrev_b32_e32 v0, 4, v16
	v_add_u32_e32 v1, 0x2000, v0
	v_ashrrev_i32_e32 v2, 31, v1
	v_lshrrev_b32_e32 v2, 22, v2
	v_add_u32_e32 v2, v1, v2
	v_ashrrev_i32_e32 v8, 10, v2
	v_mul_i32_i24_e32 v2, 0x400, v8
	v_sub_u32_e32 v1, v1, v2
	v_lshrrev_b32_e32 v2, 4, v1
	v_bitop3_b32 v1, v2, v1, 32 bitop3:0x6c
	v_ashrrev_i32_e32 v2, 31, v1
	v_lshrrev_b32_e32 v2, 26, v2
	v_add_u32_e32 v2, v1, v2
	v_lshlrev_b32_e32 v3, 3, v8
	v_ashrrev_i32_e32 v9, 6, v2
	v_and_b32_e32 v3, -16, v3
	s_add_u32 s10, s7, s4
	v_add_u32_e32 v3, v9, v3
	s_addc_u32 s11, s6, s5
	v_and_b32_e32 v4, 3, v9
	s_mov_b32 s6, 0xffffe0
	v_lshrrev_b32_e32 v5, 2, v3
	v_lshlrev_b32_e32 v6, 1, v3
	v_and_b32_e32 v2, 0xc0, v2
	v_and_or_b32 v4, v3, s6, v4
	v_and_b32_e32 v5, 4, v5
	v_and_b32_e32 v6, 24, v6
	v_sub_u32_e32 v1, v1, v2
	v_or3_b32 v4, v4, v5, v6
	v_lshlrev_b32_e32 v5, 5, v8
	v_ashrrev_i16_sdwa v1, v193, sext(v1) dst_sel:DWORD dst_unused:UNUSED_PAD src0_sel:DWORD src1_sel:BYTE_0
	v_and_b32_e32 v10, 32, v5
	v_bfe_i32 v11, v1, 0, 16
	s_movk_i32 s7, 0xb00
	v_mul_u32_u24_e32 v4, 0xb00, v4
	v_add_u32_e32 v1, v10, v11
	v_mul_lo_u32 v2, v3, s7
	v_add_lshl_u32 v152, v4, v1, 1
	v_add_lshl_u32 v154, v1, v2, 1
	v_bfe_i32 v1, v16, 27, 1
	v_lshrrev_b32_e32 v1, 22, v1
	v_add_u32_e32 v1, v0, v1
	v_and_b32_e32 v1, 0xfffffc00, v1
	v_sub_u32_e32 v0, v0, v1
	v_lshrrev_b32_e32 v1, 4, v0
	v_ashrrev_i32_e32 v2, 31, v16
	v_bitop3_b32 v0, v1, v0, 32 bitop3:0x6c
	v_lshrrev_b32_e32 v2, 26, v2
	v_ashrrev_i32_e32 v1, 31, v0
	v_add_u32_e32 v2, v16, v2
	s_add_u32 s14, s10, 0xd600000
	v_lshrrev_b32_e32 v1, 26, v1
	v_ashrrev_i32_e32 v13, 6, v2
	s_addc_u32 s15, s11, 0
	s_mul_i32 s5, s12, 0x2900000
	v_add_u32_e32 v1, v0, v1
	v_lshlrev_b32_e32 v2, 3, v13
	s_mul_hi_i32 s4, s12, 0x2900000
	s_add_u32 s13, s10, s5
	v_ashrrev_i32_e32 v12, 6, v1
	v_and_b32_e32 v2, -16, v2
	s_addc_u32 s19, s11, s4
	v_add_u32_e32 v2, v12, v2
	s_add_u32 s16, s13, 0x2000000
	v_and_b32_e32 v3, 3, v12
	v_lshrrev_b32_e32 v4, 2, v2
	v_lshlrev_b32_e32 v5, 1, v2
	v_and_b32_e32 v1, 0xc0, v1
	s_addc_u32 s29, s19, 0
	s_ashr_i32 s4, s18, 6
	v_and_or_b32 v3, v2, s6, v3
	v_and_b32_e32 v4, 4, v4
	v_and_b32_e32 v5, 24, v5
	v_sub_u32_e32 v0, v0, v1
	s_ashr_i32 s5, s18, 8
	s_lshl_b32 s30, s4, 10
	v_or3_b32 v3, v3, v4, v5
	v_lshlrev_b32_e32 v4, 5, v13
	v_ashrrev_i16_sdwa v0, v193, sext(v0) dst_sel:DWORD dst_unused:UNUSED_PAD src0_sel:DWORD src1_sel:BYTE_0
	v_readlane_b32 s6, v250, 14
	v_and_b32_e32 v14, 32, v4
	v_bfe_i32 v15, v0, 0, 16
	s_add_u32 s42, s16, s6
	v_readlane_b32 s6, v250, 12
	v_mul_u32_u24_e32 v3, 0xb00, v3
	v_add_u32_e32 v0, v14, v15
	s_addc_u32 s43, s29, s6
	s_add_i32 s31, s30, 0
	v_add_lshl_u32 v160, v3, v0, 1
	s_add_i32 m0, s31, 0x10000
	v_mul_lo_u32 v1, v2, s7
	global_load_lds_dwordx4 v160, s[42:43]
	s_add_i32 m0, s31, 0x12000
	s_add_u32 s6, s42, 0xb0000
	global_load_lds_dwordx4 v152, s[42:43]
	s_addc_u32 s7, s43, 0
	s_add_i32 m0, s31, 0x14000
	v_add_lshl_u32 v156, v0, v1, 1
	global_load_lds_dwordx4 v160, s[6:7]
	s_add_i32 m0, s31, 0x16000
	v_mov_b32_e32 v153, v161
	global_load_lds_dwordx4 v152, s[6:7]
	v_readlane_b32 s6, v250, 11
	s_add_u32 s6, s14, s6
	v_readlane_b32 s7, v250, 10
	s_addc_u32 s7, s15, s7
	s_add_i32 s50, s31, 0x2000
	s_mov_b32 m0, s31
	s_add_u32 s8, s6, 0xb0000
	s_addc_u32 s9, s7, 0
	global_load_lds_dwordx4 v156, s[6:7]
	s_mov_b32 m0, s50
	s_add_i32 s51, s31, 0x4000
	global_load_lds_dwordx4 v154, s[6:7]
	s_mov_b32 m0, s51
	s_add_i32 s52, s31, 0x6000
	global_load_lds_dwordx4 v156, s[8:9]
	s_mov_b32 m0, s52
	v_mov_b32_e32 v157, v161
	global_load_lds_dwordx4 v154, s[8:9]
	v_mov_b32_e32 v155, v161
	s_cmp_eq_u32 s5, 1
	v_lshl_add_u64 v[6:7], s[42:43], 0, v[160:161]
	v_lshl_add_u64 v[4:5], s[42:43], 0, v[152:153]
	v_lshl_add_u64 v[0:1], s[6:7], 0, v[156:157]
	s_cselect_b64 s[8:9], -1, 0
	s_cmp_lg_u32 s5, 1
	v_lshl_add_u64 v[2:3], s[6:7], 0, v[154:155]
	s_cbranch_scc1 .LBB0_2170
	s_barrier

; #define PG8_BAR __builtin_amdgcn_s_barrier()
; template <class Epi, class Sched, bool ALIGN_EPI = false, bool SP2 = false>
; __device__ __forceinline__ void gemm_phase(PG8_LAS unsigned char* lds, const Gemm g, const Sched& S, const Epi& E, int wv) {
;     ...
;     const int tid = tid_, wid = __builtin_amdgcn_readfirstlane(tid >> 6), lane = tid & 63, wr = wid >> 2, wc = wid & 3, fr = lane & 15, fq = lane >> 4;
;     const int K = g.K, nt = K / BK;
;     unsigned voffA[2], voffB[2];
; #pragma unroll
;     for (int i = 0; i < 2; ++i) { int R, C; stage_rc(tid * 16 + i * 8192, R, C); const int Rb = Epi::PERM ? ((R & ~31) + perm32(R & 31)) : R;
;         voffA[i] = (unsigned)(R * K + C) * 2u; voffB[i] = (unsigned)(Rb * K + C) * 2u; }
;     const size_t kstep = (size_t)(BK * 2);
;     const size_t hstep = (size_t)HALF * K * 2;
;     const size_t tstep = 2 * hstep;
;     const unsigned ldsw = (unsigned)wid * 1024u;
;     const int aoff = lds_byte(wr * 64 + fr, fq * 8), boff = lds_byte(wc * 32 + fr, fq * 8);
;     ...
;     Unit cur, nxt; int ui = 0;
;     if (!S.next(0, cur)) return;
;     f32x4 acc[2][2][4][2];
; #pragma unroll
;     for (int a = 0; a < 2; ++a)
; #pragma unroll
;         for (int b = 0; b < 2; ++b)
; #pragma unroll
;             for (int m = 0; m < 4; ++m)
; #pragma unroll
;                 for (int n = 0; n < 2; ++n) acc[a][b][m][n] = (f32x4){0.f, 0.f, 0.f, 0.f};
;     bf16x8 At[4][2], B0[2][2], B1[2][2];
;     const char* cA = (const char*)g.A + (size_t)cur.pm * tstep; const char* cB = (const char*)g.Bt + (size_t)cur.pn * tstep;
;     S.a_ready(cur);
;     if constexpr (SP2) {
;         PG8_STAGE(PG8_SB(0, 0), cB, voffB); PG8_STAGE(PG8_SB(0, 1), cB + hstep, voffB); PG8_STAGE(PG8_SA(0, 0), cA, voffA); PG8_STAGE(PG8_SA(0, 1), cA + hstep, voffA);
;         if (wr == 1) PG8_BAR;
;         PG8_WAIT_V(2); PG8_BAR;
;         PG8_STAGE(PG8_SB(1, 0), cB + kstep, voffB); PG8_STAGE(PG8_SA(1, 0), cA + kstep, voffA); PG8_STAGE(PG8_SB(1, 1), cB + hstep + kstep, voffB);
; __global__ void __launch_bounds__(512, 2) hymba_fwd(Params p) {
;     ...
;         if (Gf == 256 ? cf >= 32 : true) { PHASE_VARS pg8::Gemm g{(const bf16_t*)(ws + WS_PB) + (size_t)ly * MT * PED, (const bf16_t*)(wl + WL_PEU), MT, DM, PED}; pg8::StaticOrder S;
;           if (Gf == 256) S.init(MT, DM, 224, cf - 32); else S.init(MT, DM, Gf, cf);
;           EpiStore E{(bf16_t*)(ws + WS_U2), DM, nullptr};
.LBB0_2203:
	s_mov_b32 s12, s20
	s_mov_b32 s9, s2
	s_cmpk_lg_i32 s12, 0x100
	s_cselect_b64 s[4:5], -1, 0
	s_cmp_gt_i32 s9, 31
	s_cselect_b64 s[6:7], -1, 0
	s_or_b64 s[4:5], s[4:5], s[6:7]
	s_andn2_b64 vcc, exec, s[4:5]
	s_cbranch_vccnz .LBB0_2220
	v_readlane_b32 s8, v250, 0
	s_mov_b64 s[4:5], 0
	s_waitcnt lgkmcnt(0)
	v_mov_b32_e32 v0, v161
	s_sub_i32 s13, s9, 32
	v_add_u32_e32 v0, 0, v0
	v_add_u32_e32 v0, 0x201c0, v0
	s_nop 0
	s_cmpk_eq_i32 s12, 0x100
	s_cselect_b64 s[6:7], -1, 0
	s_and_b64 s[14:15], s[6:7], exec
	s_cselect_b32 s14, s13, s9
	v_readlane_b32 s11, v251, 48
	v_mov_b32_e32 v0, v161
	v_readlane_b32 s10, v251, 49
	v_add_u32_e32 v0, 0, v0
	v_add_u32_e32 v0, 0x201c8, v0
	ds_read_b64 v[0:1], v0
	v_mov_b32_e32 v8, v183
	s_cmpk_gt_i32 s14, 0x41f
	v_readfirstlane_b32 s9, v8
	s_cbranch_scc1 .LBB0_2220
	s_waitcnt lgkmcnt(0)
	v_lshlrev_b32_e32 v0, 4, v8
	v_add_u32_e32 v1, 0x2000, v0
	v_ashrrev_i32_e32 v2, 31, v1
	v_lshrrev_b32_e32 v2, 22, v2
	v_add_u32_e32 v2, v1, v2
	v_ashrrev_i32_e32 v2, 10, v2
	s_add_u32 s18, s11, s4
	v_mul_i32_i24_e32 v3, 0x400, v2
	s_addc_u32 s19, s10, s5
	s_mul_i32 s5, s8, 0x2900000
	v_sub_u32_e32 v1, v1, v3
	s_mul_hi_i32 s4, s8, 0x2900000
	s_add_u32 s5, s18, s5
	v_lshrrev_b32_e32 v3, 4, v1
	s_addc_u32 s4, s19, s4
	s_mul_hi_i32 s10, s8, 0x2100000
	s_mul_i32 s8, s8, 0x2100000
	v_bitop3_b32 v1, v3, v1, 32 bitop3:0x6c
	s_add_u32 s8, s18, s8
	v_ashrrev_i32_e32 v3, 31, v1
	s_addc_u32 s10, s19, s10
	v_lshrrev_b32_e32 v3, 26, v3
	s_add_u32 s15, s8, 0x24100000
	v_add_u32_e32 v3, v1, v3
	v_lshlrev_b32_e32 v5, 3, v2
	s_addc_u32 s16, s10, 0
	v_ashrrev_i32_e32 v4, 6, v3
	v_and_b32_e32 v5, -16, v5
	v_and_b32_e32 v3, 0xc0, v3
	s_add_u32 s24, s5, 0x2780000
	v_add_u32_e32 v5, v4, v5
	v_sub_u32_e32 v1, v1, v3
	s_addc_u32 s25, s4, 0
	v_and_b32_e32 v4, 3, v4
	s_mov_b32 s4, 0x7fffe0
	v_lshrrev_b32_e32 v6, 2, v5
	v_lshlrev_b32_e32 v7, 1, v5
	v_lshlrev_b32_e32 v2, 5, v2
	v_ashrrev_i16_sdwa v1, v193, sext(v1) dst_sel:DWORD dst_unused:UNUSED_PAD src0_sel:DWORD src1_sel:BYTE_0
	v_and_or_b32 v4, v5, s4, v4
	v_and_b32_e32 v6, 4, v6
	v_and_b32_e32 v7, 24, v7
	v_and_b32_e32 v2, 32, v2
	v_bfe_i32 v1, v1, 0, 16
	v_or3_b32 v4, v4, v6, v7
	v_add_lshl_u32 v1, v2, v1, 1
	v_lshl_add_u32 v128, v4, 9, v1
	v_lshl_add_u32 v130, v5, 9, v1
	v_bfe_i32 v1, v8, 27, 1
	v_lshrrev_b32_e32 v1, 22, v1
	v_add_u32_e32 v1, v0, v1
	v_and_b32_e32 v1, 0xfffffc00, v1
	v_sub_u32_e32 v0, v0, v1
	v_lshrrev_b32_e32 v1, 4, v0
	v_ashrrev_i32_e32 v3, 31, v8
	v_bitop3_b32 v0, v1, v0, 32 bitop3:0x6c
	v_lshrrev_b32_e32 v3, 26, v3
	v_ashrrev_i32_e32 v1, 31, v0
	v_add_u32_e32 v3, v8, v3
	v_lshrrev_b32_e32 v1, 26, v1
	v_ashrrev_i32_e32 v3, 6, v3
	v_add_u32_e32 v1, v0, v1
	v_lshlrev_b32_e32 v4, 3, v3
	v_ashrrev_i32_e32 v2, 6, v1
	v_and_b32_e32 v4, -16, v4
	v_add_u32_e32 v4, v2, v4
	v_and_b32_e32 v2, 3, v2
	v_and_or_b32 v2, v4, s4, v2
	s_ashr_i32 s4, s14, 31
	s_lshr_b32 s4, s4, 29
	s_add_i32 s4, s14, s4
	s_ashr_i32 s13, s9, 6
	s_ashr_i32 s5, s4, 3
	s_and_b32 s4, s4, -8
	s_ashr_i32 s21, s9, 8
	s_lshl_b32 s29, s13, 10
	s_sub_i32 s4, s14, s4
	s_cmp_lt_i32 s4, 0
	s_cselect_b32 s8, s55, 0x84
	s_mul_i32 s4, s4, s8
	s_add_i32 s4, s4, s5
	s_ashr_i32 s5, s4, 31
	s_lshr_b32 s5, s5, 27
	s_add_i32 s5, s4, s5
	s_ashr_i32 s8, s5, 5
	s_and_b32 s5, s5, 0xffe0
	s_sub_i32 s4, s4, s5
	s_bfe_i32 s5, s4, 0x80000
	s_bfe_u32 s5, s5, 0x3000c
	s_add_i32 s5, s4, s5
	s_lshl_b32 s10, s8, 3
	s_bfe_i32 s8, s5, 0x80000
	s_and_b32 s5, s5, 0xf8
	s_sub_i32 s4, s4, s5
	s_sext_i32_i16 s8, s8
	s_sext_i32_i8 s4, s4
	v_and_b32_e32 v1, 0xc0, v1
	s_lshr_b32 s8, s8, 3
	s_add_i32 s10, s10, s4
	v_sub_u32_e32 v0, v0, v1
	s_ashr_i32 s11, s10, 31
	s_bfe_i64 s[30:31], s[8:9], 0x100000
	v_lshrrev_b32_e32 v5, 2, v4
	v_lshlrev_b32_e32 v6, 1, v4
	v_lshlrev_b32_e32 v3, 5, v3
	v_ashrrev_i16_sdwa v0, v193, sext(v0) dst_sel:DWORD dst_unused:UNUSED_PAD src0_sel:DWORD src1_sel:BYTE_0
	s_lshl_b64 s[4:5], s[10:11], 17
	s_lshl_b64 s[30:31], s[30:31], 17
	v_and_b32_e32 v5, 4, v5
	v_and_b32_e32 v6, 24, v6
	v_and_b32_e32 v3, 32, v3
	v_bfe_i32 v0, v0, 0, 16
	s_add_u32 s34, s24, s30
	v_or3_b32 v2, v2, v5, v6
	v_add_lshl_u32 v0, v3, v0, 1
	s_addc_u32 s35, s25, s31
	s_add_i32 s80, s29, 0
	v_lshl_add_u32 v160, v2, 9, v0
	s_add_i32 m0, s80, 0x10000
	v_lshl_add_u32 v132, v4, 9, v0
	global_load_lds_dwordx4 v160, s[34:35]
	s_add_i32 m0, s80, 0x12000
	s_add_u32 s40, s34, 0x10000
	global_load_lds_dwordx4 v128, s[34:35]
	s_addc_u32 s41, s35, 0
	s_add_i32 m0, s80, 0x14000
	v_mov_b32_e32 v129, v161
	global_load_lds_dwordx4 v160, s[40:41]
	s_add_i32 m0, s80, 0x16000
	s_add_u32 s44, s15, s4
	s_addc_u32 s45, s16, s5
	s_add_i32 s31, s80, 0x2000
	global_load_lds_dwordx4 v128, s[40:41]
	s_mov_b32 m0, s80
	s_add_u32 s4, s44, 0x10000
	global_load_lds_dwordx4 v132, s[44:45]
	s_mov_b32 m0, s31
	s_addc_u32 s5, s45, 0
	s_add_i32 s54, s80, 0x4000
	global_load_lds_dwordx4 v130, s[44:45]
	s_mov_b32 m0, s54
	s_add_i32 s66, s80, 0x6000
	global_load_lds_dwordx4 v132, s[4:5]
	s_mov_b32 m0, s66
	v_mov_b32_e32 v133, v161
	global_load_lds_dwordx4 v130, s[4:5]
	v_mov_b32_e32 v131, v161
	s_cmp_eq_u32 s21, 1
	s_movk_i32 s68, 0x85
	v_lshl_add_u64 v[6:7], s[34:35], 0, v[160:161]
	v_lshl_add_u64 v[4:5], s[34:35], 0, v[128:129]
	v_lshl_add_u64 v[0:1], s[44:45], 0, v[132:133]
	s_cselect_b64 s[4:5], -1, 0
	s_cmp_lg_u32 s21, 1
	v_lshl_add_u64 v[2:3], s[44:45], 0, v[130:131]
	s_cbranch_scc1 .LBB0_2207
	s_barrier

; __device__ __forceinline__ int tid_of(int wv) { return wv * 64 + (int)__builtin_amdgcn_mbcnt_hi(~0u, __builtin_amdgcn_mbcnt_lo(~0u, 0u)); }
; #define LAS __attribute__((address_space(3)))
; #define PIN(i) ((const float*)ldq_(L, (i)))
; #define PREP_CONV(bit, SRC, Kd, Nd, DST, GK, MODE) if (mask & (bit)) { for (int it = gw; it < ((Kd) / 64) * ((Nd) / 64); it += NGW) transpose_item((SRC), (Kd), (Nd), (bf16_t*)(wl + (DST)), (GK), (MODE), scr, it, lane); }
; __device__ __forceinline__ void prep(const Params& p, LAS unsigned char* L, int wv, int vb, int nvb, int l, int mask) {
;     int tid_ = tid_of(wv); asm volatile("" : "+v"(tid_));
;     const int tid = tid_, lane = tid & 63, wave = __builtin_amdgcn_readfirstlane(tid >> 6);
;     const int gw = vb * 8 + wave, NGW = nvb * 8; const int gt = vb * 512 + tid, NGT = nvb * 512;
;     LAS float* scr = (LAS float*)(L + wave * 16384);
;     unsigned char* ws = PWS; unsigned char* wl = ws + WS_W + (size_t)l * WL_STRIDE;
;     ...
;     PREP_CONV(PM_FFA_IN, PIN(I_WFFA_IN) + (size_t)l * DM * NFF2, DM, NFF2, WL_FFA_IN, PIN(I_NFFA) + l * DM, 1)
;     PREP_CONV(PM_FFA_OUT, PIN(I_WFFA_OUT) + (size_t)l * DFF * DM, DFF, DM, WL_FFA_OUT, nullptr, 0)
;     PREP_CONV(PM_WIN, PIN(I_WIN) + (size_t)l * DM * NIN, DM, NIN, WL_IN, PIN(I_NMIX) + l * DM, 0)
;     PREP_CONV(PM_WOUT, PIN(I_WOUT) + (size_t)l * DM * DM, DM, DM, WL_OUT, nullptr, 0)
.LBB0_2384:
	s_mov_b32 s5, s20
	s_mov_b32 s4, s2
	s_cmpk_eq_i32 s5, 0x100
	s_cselect_b64 s[6:7], -1, 0
	s_cmp_gt_i32 s4, 31
	s_cselect_b64 s[8:9], -1, 0
	s_and_b64 s[6:7], s[6:7], s[8:9]
	s_cmp_lt_i32 s60, 2
	s_cselect_b64 s[8:9], -1, 0
	s_and_b64 s[6:7], s[6:7], s[8:9]
	s_andn2_b64 vcc, exec, s[6:7]
	s_mov_b32 s0, 0x24000
	s_cbranch_vccnz .LBB0_2461
	s_waitcnt lgkmcnt(0)
	v_mov_b32_e32 v1, v183
	v_mov_b32_e32 v2, v161
	s_lshl_b32 s4, s4, 3
	v_add_u32_e32 v2, 0, v2
	v_add_u32_e32 v2, 0x201c0, v2
	s_nop 0
	v_readfirstlane_b32 s5, v1
	s_ashr_i32 s5, s5, 6
	s_add_i32 s4, s4, s5
	s_add_i32 s16, s4, 0xffffff00
	s_lshl_b32 s4, s5, 14
	s_add_i32 s24, s4, 0
	v_readlane_b32 s5, v251, 48
	s_ashr_i32 s61, s60, 31
	s_mul_i32 s6, s60, 0x2900000
	v_readlane_b32 s4, v251, 49
	s_mul_hi_i32 s7, s60, 0x2900000
	s_add_u32 s6, s5, s6
	v_and_b32_e32 v0, 63, v1
	s_addc_u32 s7, s4, s7
	s_cmpk_lt_i32 s16, 0x100
	v_and_b32_e32 v2, 7, v1
	v_lshrrev_b32_e32 v74, 3, v0
	s_cselect_b64 s[4:5], -1, 0
	s_cmpk_gt_i32 s16, 0xff
	v_lshl_add_u32 v75, v0, 2, s24
	v_mul_u32_u24_e32 v1, 0x410, v2
	v_lshlrev_b32_e32 v2, 4, v2
	v_lshlrev_b32_e32 v76, 2, v74
	s_cbranch_scc1 .LBB0_2388
	v_mov_b32_e32 v3, v161
	v_lshl_add_u64 v[4:5], s[6:7], 0, v[2:3]
	s_mov_b64 s[10:11], 0x1300000
	s_lshl_b64 s[8:9], s[60:61], 22
	v_lshl_add_u64 v[4:5], v[4:5], 0, s[10:11]
	v_add3_u32 v3, s24, v1, v76
	s_lshl_b32 s14, s16, 6
	v_lshlrev_b32_e32 v160, 2, v0
	s_mov_b32 s15, s16

; #define LAS __attribute__((address_space(3)))
; #define PIN(i) ((const float*)ldq_(L, (i)))
; __device__ __forceinline__ unsigned pk2(float lo, float hi) { f32x2 v = {lo, hi}; bf16x2_t b = __builtin_convertvector(v, bf16x2_t); return __builtin_bit_cast(unsigned, b); }
; #define PREP_CONV(bit, SRC, Kd, Nd, DST, GK, MODE) if (mask & (bit)) { for (int it = gw; it < ((Kd) / 64) * ((Nd) / 64); it += NGW) transpose_item((SRC), (Kd), (Nd), (bf16_t*)(wl + (DST)), (GK), (MODE), scr, it, lane); }
; __device__ __forceinline__ void transpose_item(const float* W, int K, int N, bf16_t* WT, const float* gk, int mode, LAS float* scr_, int item, int lane) {
;     LAS unsigned* scr = (LAS unsigned*)scr_;
;     const int nblk = N / 64, kb = item / nblk, nb = item % nblk, k0 = 64 * kb, n0 = 64 * nb;
;     const int sc = (mode == 1) ? (((n0 >> 7) & 1) * DFF + (n0 >> 8) * 128 + (n0 & 127)) : n0;
;     const float* src = W + (size_t)k0 * N + sc + lane;
;     float va[32], vb[32];
; #pragma unroll
;     for (int kp = 0; kp < 32; ++kp) { va[kp] = src[(size_t)(2 * kp) * N]; vb[kp] = src[(size_t)(2 * kp + 1) * N]; }
; #pragma unroll
;     for (int kp = 0; kp < 32; ++kp) {
;         float a = va[kp], b = vb[kp];
;         if (gk) { a *= gk[k0 + 2 * kp]; b *= gk[k0 + 2 * kp + 1]; }
;         scr[kp * 65 + lane] = pk2(a, b);
;     }
; __device__ __forceinline__ void prep(const Params& p, LAS unsigned char* L, int wv, int vb, int nvb, int l, int mask) {
;     ...
;     PREP_CONV(PM_PEG, PIN(I_WPEG) + (size_t)l * DM * DM, DM, DM, WL_PEG, PIN(I_NPE) + l * DM, 0)
.LBB0_2394:
	v_mov_b32_e32 v6, v161
	s_nop 0
	v_add_u32_e32 v6, 0, v6
	v_add_u32_e32 v6, 0x201b0, v6
	s_nop 0
	s_waitcnt lgkmcnt(0)
	v_readlane_b32 s5, v251, 44
	v_mov_b32_e32 v6, v161
	v_readlane_b32 s4, v251, 45
	v_add_u32_e32 v6, 0, v6
	v_add_u32_e32 v6, 0x201a8, v6
	s_nop 0
	s_add_u32 s15, s5, s8
	s_addc_u32 s21, s4, s9
	v_readlane_b32 s4, v251, 42
	v_readlane_b32 s5, v251, 43
	s_add_u32 s30, s4, s10
	s_addc_u32 s31, s5, s11
	s_ashr_i32 s12, s28, 31
	s_lshr_b32 s12, s12, 28
	s_add_i32 s12, s28, s12
	s_ashr_i32 s13, s12, 4
	s_lshl_b32 s12, s13, 6
	s_lshl_b32 s29, s13, 10
	s_ashr_i32 s13, s12, 31
	s_sub_i32 s14, s25, s29
	s_lshl_b64 s[18:19], s[12:13], 12
	s_add_u32 s18, s15, s18
	s_addc_u32 s19, s21, s19
	s_ashr_i32 s15, s14, 31
	s_lshl_b64 s[14:15], s[14:15], 2
	s_add_u32 s14, s18, s14
	s_addc_u32 s15, s19, s15
	v_lshl_add_u64 v[70:71], s[14:15], 0, v[160:161]
	v_add_co_u32_e32 v6, vcc, s79, v70
	global_load_dword v66, v160, s[14:15]
	s_nop 0
	v_addc_co_u32_e32 v7, vcc, 0, v71, vcc
	global_load_dword v67, v[6:7], off offset:-4096
	global_load_dword v68, v[6:7], off
	v_add_co_u32_e32 v6, vcc, s88, v70
	s_mov_b32 s14, 0x3d000
	s_nop 0
	v_addc_co_u32_e32 v7, vcc, 0, v71, vcc
	global_load_dword v69, v[6:7], off offset:-4096
	global_load_dword v62, v[6:7], off
	v_add_co_u32_e32 v6, vcc, s80, v70
	s_cmp_lg_u64 s[4:5], 0
	s_nop 0
	v_addc_co_u32_e32 v7, vcc, 0, v71, vcc
	global_load_dword v63, v[6:7], off offset:-4096
	global_load_dword v64, v[6:7], off
	v_add_co_u32_e32 v6, vcc, s70, v70
	s_mov_b64 s[18:19], -1
	s_nop 0
	v_addc_co_u32_e32 v7, vcc, 0, v71, vcc
	global_load_dword v65, v[6:7], off offset:-4096
	global_load_dword v58, v[6:7], off
	v_add_co_u32_e32 v6, vcc, s71, v70
	s_nop 1
	v_addc_co_u32_e32 v7, vcc, 0, v71, vcc
	global_load_dword v59, v[6:7], off offset:-4096
	global_load_dword v60, v[6:7], off
	v_add_co_u32_e32 v6, vcc, s91, v70
	s_nop 1
	v_addc_co_u32_e32 v7, vcc, 0, v71, vcc
	global_load_dword v61, v[6:7], off offset:-4096
	global_load_dword v54, v[6:7], off
	v_add_co_u32_e32 v6, vcc, s92, v70
	s_nop 1
	v_addc_co_u32_e32 v7, vcc, 0, v71, vcc
	global_load_dword v55, v[6:7], off offset:-4096
	global_load_dword v56, v[6:7], off
	v_add_co_u32_e32 v6, vcc, s37, v70
	s_nop 1
	v_addc_co_u32_e32 v7, vcc, 0, v71, vcc
	global_load_dword v57, v[6:7], off offset:-4096
	global_load_dword v50, v[6:7], off
	v_add_co_u32_e32 v6, vcc, s94, v70
	s_nop 1
	v_addc_co_u32_e32 v7, vcc, 0, v71, vcc
	global_load_dword v51, v[6:7], off offset:-4096
	global_load_dword v52, v[6:7], off
	v_add_co_u32_e32 v6, vcc, s46, v70
	s_nop 1
	v_addc_co_u32_e32 v7, vcc, 0, v71, vcc
	global_load_dword v53, v[6:7], off offset:-4096
	global_load_dword v46, v[6:7], off
	v_add_co_u32_e32 v6, vcc, s47, v70
	s_nop 1
	v_addc_co_u32_e32 v7, vcc, 0, v71, vcc
	global_load_dword v47, v[6:7], off offset:-4096
	global_load_dword v48, v[6:7], off
	v_add_co_u32_e32 v6, vcc, s59, v70
	s_nop 1
	v_addc_co_u32_e32 v7, vcc, 0, v71, vcc
	global_load_dword v49, v[6:7], off offset:-4096
	global_load_dword v42, v[6:7], off
	v_add_co_u32_e32 v6, vcc, s81, v70
	s_nop 1
	v_addc_co_u32_e32 v7, vcc, 0, v71, vcc
	global_load_dword v43, v[6:7], off offset:-4096
	global_load_dword v44, v[6:7], off
	v_add_co_u32_e32 v6, vcc, s83, v70
	s_nop 1
	v_addc_co_u32_e32 v7, vcc, 0, v71, vcc
	global_load_dword v45, v[6:7], off offset:-4096
	global_load_dword v38, v[6:7], off
	v_add_co_u32_e32 v6, vcc, s27, v70
	s_nop 1
	v_addc_co_u32_e32 v7, vcc, 0, v71, vcc
	global_load_dword v39, v[6:7], off offset:-4096
	global_load_dword v40, v[6:7], off
	v_add_co_u32_e32 v6, vcc, s50, v70
	s_nop 1
	v_addc_co_u32_e32 v7, vcc, 0, v71, vcc
	global_load_dword v41, v[6:7], off offset:-4096
	global_load_dword v34, v[6:7], off
	v_add_co_u32_e32 v6, vcc, s53, v70
	s_nop 1
	v_addc_co_u32_e32 v7, vcc, 0, v71, vcc
	global_load_dword v35, v[6:7], off offset:-4096
	global_load_dword v36, v[6:7], off
	v_add_co_u32_e32 v6, vcc, s0, v70
	s_nop 1
	v_addc_co_u32_e32 v7, vcc, 0, v71, vcc
	global_load_dword v37, v[6:7], off offset:-4096
	global_load_dword v30, v[6:7], off
	v_add_co_u32_e32 v6, vcc, s73, v70
	s_nop 1
	v_addc_co_u32_e32 v7, vcc, 0, v71, vcc
	global_load_dword v31, v[6:7], off offset:-4096
	global_load_dword v32, v[6:7], off
	v_add_co_u32_e32 v6, vcc, s1, v70
	s_nop 1
	v_addc_co_u32_e32 v7, vcc, 0, v71, vcc
	global_load_dword v33, v[6:7], off offset:-4096
	global_load_dword v26, v[6:7], off
	v_add_co_u32_e32 v6, vcc, s72, v70
	s_nop 1
	v_addc_co_u32_e32 v7, vcc, 0, v71, vcc
	global_load_dword v27, v[6:7], off offset:-4096
	global_load_dword v28, v[6:7], off
	v_add_co_u32_e32 v6, vcc, s82, v70
	s_nop 1
	v_addc_co_u32_e32 v7, vcc, 0, v71, vcc
	global_load_dword v29, v[6:7], off offset:-4096
	global_load_dword v22, v[6:7], off
	v_add_co_u32_e32 v6, vcc, s33, v70
	s_nop 1
	v_addc_co_u32_e32 v7, vcc, 0, v71, vcc
	global_load_dword v23, v[6:7], off offset:-4096
	global_load_dword v24, v[6:7], off
	v_add_co_u32_e32 v6, vcc, s22, v70
	s_nop 1
	v_addc_co_u32_e32 v7, vcc, 0, v71, vcc
	global_load_dword v25, v[6:7], off offset:-4096
	global_load_dword v18, v[6:7], off
	v_add_co_u32_e32 v6, vcc, s38, v70
	s_nop 1
	v_addc_co_u32_e32 v7, vcc, 0, v71, vcc
	global_load_dword v19, v[6:7], off offset:-4096
	global_load_dword v20, v[6:7], off
	v_add_co_u32_e32 v6, vcc, s39, v70
	s_nop 1
	v_addc_co_u32_e32 v7, vcc, 0, v71, vcc
	global_load_dword v21, v[6:7], off offset:-4096
	global_load_dword v14, v[6:7], off
	v_add_co_u32_e32 v6, vcc, s56, v70
	s_nop 1
	v_addc_co_u32_e32 v7, vcc, 0, v71, vcc
	global_load_dword v15, v[6:7], off offset:-4096
	global_load_dword v16, v[6:7], off
	v_add_co_u32_e32 v6, vcc, s69, v70
	s_nop 1
	v_addc_co_u32_e32 v7, vcc, 0, v71, vcc
	v_add_co_u32_e32 v8, vcc, s87, v70
	global_load_dword v17, v[6:7], off offset:-4096
	s_nop 0
	global_load_dword v6, v[6:7], off
	v_addc_co_u32_e32 v9, vcc, 0, v71, vcc
	global_load_dword v7, v[8:9], off offset:-4096
	global_load_dword v12, v[8:9], off
	v_add_co_u32_e32 v8, vcc, 0x3b000, v70
	s_nop 1
	v_addc_co_u32_e32 v9, vcc, 0, v71, vcc
	v_add_co_u32_e32 v10, vcc, s14, v70
	global_load_dword v13, v[8:9], off
	s_nop 0
	v_addc_co_u32_e32 v11, vcc, 0, v71, vcc
	global_load_dword v8, v[10:11], off offset:-4096
	global_load_dword v9, v[10:11], off
	v_add_co_u32_e32 v10, vcc, 0x3e000, v70
	s_cselect_b64 s[14:15], -1, 0
	s_nop 0
	v_addc_co_u32_e32 v11, vcc, 0, v71, vcc
	v_add_co_u32_e32 v70, vcc, 0x3f000, v70
	global_load_dword v10, v[10:11], off
	s_nop 0
	v_addc_co_u32_e32 v71, vcc, 0, v71, vcc
	global_load_dword v11, v[70:71], off
	s_cmp_eq_u64 s[4:5], 0
	s_cbranch_scc1 .LBB0_2396
	s_lshl_b64 s[4:5], s[12:13], 2
	s_add_u32 s4, s30, s4
	s_addc_u32 s5, s31, s5
	global_load_dwordx4 v[70:73], v161, s[4:5]
	s_mov_b64 s[18:19], 0
	s_waitcnt vmcnt(0)
	v_pk_mul_f32 v[70:71], v[66:67], v[70:71]
	v_pk_mul_f32 v[72:73], v[68:69], v[72:73]

; __device__ __forceinline__ void xcd_barrier(const XcdBarrier& b, bool t0) {
;     asm volatile("s_waitcnt vmcnt(0)" ::: "memory");
;     __syncthreads();
;     if (t0) {
;         unsigned* bar = b.bar;
;         __builtin_amdgcn_s_waitcnt(0);
;         unsigned nloc = b.st[0], nx = b.st[1];
;         if (nloc == 0u) { xcd_barrier_complete(bar, b.x, nloc, nx); b.st[0] = nloc; b.st[1] = nx; }
.LBB0_2462:
	v_mov_b32_e32 v0, v161
	v_mov_b32_e32 v2, v183
	v_add_u32_e32 v0, 0, v0
	v_add_u32_e32 v0, 0x201c0, v0
	s_waitcnt lgkmcnt(0)
	s_nop 0
	s_getreg_b32 s8, hwreg(HW_REG_XCC_ID, 0, 4)
	s_waitcnt vmcnt(0)
	v_readlane_b32 s7, v251, 49
	v_readlane_b32 s6, v251, 48
	v_cmp_eq_u32_e32 vcc, 0, v2
	s_barrier
	s_and_saveexec_b64 s[4:5], vcc
	s_cbranch_execnz .LBB0_2463
	s_getpc_b64 s[98:99]
